# speedup vs baseline: 1.0139x; 1.0001x over previous
; #define LAS __attribute__((address_space(3)))
; #define MFMA32(a_, b_, c_) __builtin_amdgcn_mfma_f32_32x32x16_bf16((a_), (b_), (c_), 0, 0, 0)
; __device__ __forceinline__ int crow(int reg, int h) { return (reg & 3) + 8 * (reg >> 2) + 4 * h; }
; __device__ __forceinline__ void attn_fast(KArgs ap, int l, LAS unsigned char* lds, const Ctx cx) {
;     ...
;             bf16x8 qf[4]; { const bf16_t* qp = z + (tok0 + i0 + r) * DIN + ZQ + head * 64 + 8 * hh;
; #pragma unroll
;                 for (int ks = 0; ks < 4; ++ks) qf[ks] = *(const bf16x8*)(qp + 16 * ks); }
;             f32x16 st[5];
; #pragma unroll
;             for (int kt = 0; kt < 5; ++kt) {
; #pragma unroll
;                 for (int i = 0; i < 16; ++i) st[kt][i] = 0.f;
; #pragma unroll
;                 for (int ks = 0; ks < 4; ++ks) { const bf16x8 kf = *(const LAS bf16x8*)(KL + (i0 + 32 * kt + r) * 144 + (16 * ks + 8 * hh) * 2); st[kt] = MFMA32(kf, qf[ks], st[kt]); }
;             }
;             float m = sink2;
; #pragma unroll
;             for (int kt = 0; kt < 5; ++kt)
; #pragma unroll
;                 for (int i = 0; i < 16; ++i) { const int kl = 32 * kt + crow(i, hh);
;                     const bool valid = (kl > r) && (kl <= 128 + r) && (nb > 0 || i0 + kl >= 128);
;                     const float x = valid ? st[kt][i] * (0.125f * LOG2E) : -__builtin_inff();
;                     st[kt][i] = x; m = fmaxf(m, x); }
.LBB0_135:
	global_load_dwordx4 v[0:3], v[108:109], off offset:-64
	global_load_dwordx4 v[124:127], v[108:109], off offset:-32
	global_load_dwordx4 v[128:131], v[108:109], off
	global_load_dwordx4 v[80:83], v[108:109], off offset:32
	ds_read_b128 v[4:7], v123
	ds_read_b128 v[8:11], v123 offset:32
	s_add_i32 s26, s31, 1
	s_cmp_gt_u32 s31, 2
	s_cselect_b64 vcc, -1, 0
	s_or_b64 vcc, s[28:29], vcc
	s_cmp_gt_u32 s31, 1
	v_add_u32_e32 v122, 0x1200, v123
	s_waitcnt vmcnt(3) lgkmcnt(1)
	v_mfma_f32_32x32x16_bf16 v[64:79], v[4:7], v[0:3], 0
	ds_read_b128 v[4:7], v123 offset:64
	ds_read_b128 v[132:135], v123 offset:18464
	s_waitcnt vmcnt(2) lgkmcnt(2)
	v_mfma_f32_32x32x16_bf16 v[64:79], v[8:11], v[124:127], v[64:79]
	s_waitcnt vmcnt(1) lgkmcnt(1)
	v_mfma_f32_32x32x16_bf16 v[64:79], v[4:7], v[128:131], v[64:79]
	ds_read_b128 v[4:7], v123 offset:96
	s_waitcnt vmcnt(0) lgkmcnt(0)
	v_mfma_f32_32x32x16_bf16 v[64:79], v[4:7], v[80:83], v[64:79]
	ds_read_b128 v[4:7], v123 offset:4608
	s_waitcnt lgkmcnt(0)
	v_mfma_f32_32x32x16_bf16 v[48:63], v[4:7], v[0:3], 0
	ds_read_b128 v[4:7], v123 offset:4640
	s_nop 7
	v_mul_f32_e32 v64, 0x3e38aa3b, v64
	v_mul_f32_e32 v65, 0x3e38aa3b, v65
	v_cndmask_b32_e64 v64, v197, v64, s[80:81]
	v_cndmask_b32_e64 v65, v197, v65, s[82:83]
	v_mul_f32_e32 v66, 0x3e38aa3b, v66
	v_mul_f32_e32 v67, 0x3e38aa3b, v67
	s_waitcnt lgkmcnt(0)
	v_mfma_f32_32x32x16_bf16 v[48:63], v[4:7], v[124:127], v[48:63]
	ds_read_b128 v[4:7], v123 offset:4672
	v_cndmask_b32_e64 v66, v197, v66, s[84:85]
	v_cndmask_b32_e64 v67, v197, v67, s[86:87]
	v_mul_f32_e32 v68, 0x3e38aa3b, v68
	v_mul_f32_e32 v69, 0x3e38aa3b, v69
	v_cndmask_b32_e64 v68, v197, v68, s[88:89]
	v_cndmask_b32_e64 v69, v197, v69, s[90:91]
	s_waitcnt lgkmcnt(0)
	v_mfma_f32_32x32x16_bf16 v[48:63], v[4:7], v[128:131], v[48:63]
	ds_read_b128 v[4:7], v123 offset:4704
	v_mul_f32_e32 v70, 0x3e38aa3b, v70
	v_mul_f32_e32 v71, 0x3e38aa3b, v71
	v_cndmask_b32_e64 v70, v197, v70, s[92:93]
	v_cndmask_b32_e64 v71, v197, v71, s[94:95]
	v_mul_f32_e32 v72, 0x3e38aa3b, v72
	v_mul_f32_e32 v73, 0x3e38aa3b, v73
	s_waitcnt lgkmcnt(0)
	v_mfma_f32_32x32x16_bf16 v[48:63], v[4:7], v[80:83], v[48:63]
	ds_read_b128 v[4:7], v123 offset:9216
	v_cndmask_b32_e64 v72, v197, v72, s[96:97]
	v_cndmask_b32_e64 v73, v197, v73, s[14:15]
	v_mul_f32_e32 v74, 0x3e38aa3b, v74
	v_mul_f32_e32 v75, 0x3e38aa3b, v75
	v_cndmask_b32_e64 v74, v197, v74, s[4:5]
	v_cndmask_b32_e64 v75, v197, v75, s[6:7]
	s_waitcnt lgkmcnt(0)
	v_mfma_f32_32x32x16_bf16 v[32:47], v[4:7], v[0:3], 0
	ds_read_b128 v[4:7], v123 offset:9248
	v_mul_f32_e32 v76, 0x3e38aa3b, v76
	v_mul_f32_e32 v77, 0x3e38aa3b, v77
	v_cndmask_b32_e64 v76, v197, v76, s[0:1]
	v_cndmask_b32_e64 v77, v197, v77, s[8:9]
	v_mul_f32_e32 v78, 0x3e38aa3b, v78
	v_mul_f32_e32 v79, 0x3e38aa3b, v79
	s_waitcnt lgkmcnt(0)
	v_mfma_f32_32x32x16_bf16 v[32:47], v[4:7], v[124:127], v[32:47]
	ds_read_b128 v[4:7], v123 offset:9280
	v_cndmask_b32_e64 v78, v197, v78, s[10:11]
	v_cndmask_b32_e64 v79, v197, v79, s[12:13]
	v_mul_f32_e32 v48, 0x3e38aa3b, v48
	v_mul_f32_e32 v49, 0x3e38aa3b, v49
	v_cndmask_b32_e32 v48, v197, v48, vcc
	v_cndmask_b32_e32 v49, v197, v49, vcc
	s_waitcnt lgkmcnt(0)
	v_mfma_f32_32x32x16_bf16 v[32:47], v[4:7], v[128:131], v[32:47]
	ds_read_b128 v[4:7], v123 offset:9312
	v_mul_f32_e32 v50, 0x3e38aa3b, v50
	v_mul_f32_e32 v51, 0x3e38aa3b, v51
	v_cndmask_b32_e32 v50, v197, v50, vcc
	v_cndmask_b32_e32 v51, v197, v51, vcc
	v_mul_f32_e32 v52, 0x3e38aa3b, v52
	v_mul_f32_e32 v53, 0x3e38aa3b, v53
	s_waitcnt lgkmcnt(0)
	v_mfma_f32_32x32x16_bf16 v[32:47], v[4:7], v[80:83], v[32:47]
	ds_read_b128 v[4:7], v123 offset:13824
	v_cndmask_b32_e32 v52, v197, v52, vcc
	v_cndmask_b32_e32 v53, v197, v53, vcc
	v_mul_f32_e32 v54, 0x3e38aa3b, v54
	v_mul_f32_e32 v55, 0x3e38aa3b, v55
	v_cndmask_b32_e32 v54, v197, v54, vcc
	v_cndmask_b32_e32 v55, v197, v55, vcc
	s_waitcnt lgkmcnt(0)
	v_mfma_f32_32x32x16_bf16 v[16:31], v[4:7], v[0:3], 0
	ds_read_b128 v[4:7], v123 offset:13856
	v_mul_f32_e32 v56, 0x3e38aa3b, v56
	v_mul_f32_e32 v57, 0x3e38aa3b, v57
	v_cndmask_b32_e32 v56, v197, v56, vcc
	v_cndmask_b32_e32 v57, v197, v57, vcc
	v_mul_f32_e32 v58, 0x3e38aa3b, v58
	v_mul_f32_e32 v59, 0x3e38aa3b, v59
	s_waitcnt lgkmcnt(0)
	v_mfma_f32_32x32x16_bf16 v[16:31], v[4:7], v[124:127], v[16:31]
	ds_read_b128 v[4:7], v123 offset:13888
	v_mul_f32_e32 v60, 0x3e38aa3b, v60
	v_mul_f32_e32 v61, 0x3e38aa3b, v61
	v_mul_f32_e32 v62, 0x3e38aa3b, v62
	v_mul_f32_e32 v63, 0x3e38aa3b, v63
	v_cndmask_b32_e32 v58, v197, v58, vcc
	v_cndmask_b32_e32 v59, v197, v59, vcc
	s_waitcnt lgkmcnt(0)
	v_mfma_f32_32x32x16_bf16 v[16:31], v[4:7], v[128:131], v[16:31]
	ds_read_b128 v[4:7], v123 offset:13920
	v_cndmask_b32_e32 v60, v197, v60, vcc
	v_cndmask_b32_e32 v61, v197, v61, vcc
	v_cndmask_b32_e32 v62, v197, v62, vcc
	v_cndmask_b32_e32 v63, v197, v63, vcc
	s_cselect_b64 vcc, -1, 0
	s_or_b64 vcc, s[28:29], vcc
	s_waitcnt lgkmcnt(0)
	v_mfma_f32_32x32x16_bf16 v[16:31], v[4:7], v[80:83], v[16:31]
	ds_read_b128 v[4:7], v123 offset:18432
	v_mul_f32_e32 v32, 0x3e38aa3b, v32
	s_or_b32 s27, s31, s40
	s_cmp_eq_u32 s27, 0
	s_mov_b32 s31, s26
	s_nop 6
	v_mul_f32_e32 v16, 0x3e38aa3b, v16
	s_waitcnt lgkmcnt(0)
	v_mfma_f32_32x32x16_bf16 v[0:15], v[4:7], v[0:3], 0
	v_mul_f32_e32 v17, 0x3e38aa3b, v17
	v_mul_f32_e32 v18, 0x3e38aa3b, v18
	v_mul_f32_e32 v19, 0x3e38aa3b, v19
	v_mul_f32_e32 v20, 0x3e38aa3b, v20
	v_mul_f32_e32 v21, 0x3e38aa3b, v21
	v_mul_f32_e32 v22, 0x3e38aa3b, v22
	v_mul_f32_e32 v23, 0x3e38aa3b, v23
	v_mfma_f32_32x32x16_bf16 v[0:15], v[132:135], v[124:127], v[0:15]
	ds_read_b128 v[124:127], v123 offset:18496
	v_mul_f32_e32 v24, 0x3e38aa3b, v24
	v_mul_f32_e32 v25, 0x3e38aa3b, v25
	v_mul_f32_e32 v26, 0x3e38aa3b, v26
	v_mul_f32_e32 v27, 0x3e38aa3b, v27
	v_mul_f32_e32 v28, 0x3e38aa3b, v28
	v_mul_f32_e32 v29, 0x3e38aa3b, v29
	s_waitcnt lgkmcnt(0)
; __device__ __forceinline__ int crow(int reg, int h) { return (reg & 3) + 8 * (reg >> 2) + 4 * h; }
; __device__ __forceinline__ void attn_fast(KArgs ap, int l, LAS unsigned char* lds, const Ctx cx) {
;     ...
; #pragma unroll
;             for (int kt = 0; kt < 5; ++kt)
; #pragma unroll
;                 for (int i = 0; i < 16; ++i) { const int kl = 32 * kt + crow(i, hh);
;                     const bool valid = (kl > r) && (kl <= 128 + r) && (nb > 0 || i0 + kl >= 128);
;                     const float x = valid ? st[kt][i] * (0.125f * LOG2E) : -__builtin_inff();
;                     st[kt][i] = x; m = fmaxf(m, x); }
;             m = fmaxf(m, __shfl_xor(m, 32));
	v_mfma_f32_32x32x16_bf16 v[0:15], v[124:127], v[128:131], v[0:15]
	ds_read_b128 v[124:127], v123 offset:18528
	v_mul_f32_e32 v30, 0x3e38aa3b, v30
	v_mul_f32_e32 v31, 0x3e38aa3b, v31
	s_waitcnt lgkmcnt(0)
	v_mfma_f32_32x32x16_bf16 v[0:15], v[124:127], v[80:83], v[0:15]
	v_max3_f32 v80, v121, v64, v65
	v_max3_f32 v80, v80, v66, v67
	v_max3_f32 v80, v80, v68, v69
	v_max3_f32 v80, v80, v70, v71
	v_max3_f32 v80, v80, v72, v73
	v_max3_f32 v80, v80, v74, v75
	v_max3_f32 v80, v80, v76, v77
	v_max3_f32 v80, v80, v78, v79
	v_max3_f32 v80, v80, v48, v49
	v_max3_f32 v80, v80, v50, v51
	v_max3_f32 v80, v80, v52, v53
	v_max3_f32 v80, v80, v54, v55
	v_max3_f32 v80, v80, v56, v57
	v_max3_f32 v80, v80, v58, v59
	v_max3_f32 v80, v80, v60, v61
	v_cndmask_b32_e32 v81, v197, v32, vcc
	v_mul_f32_e32 v32, 0x3e38aa3b, v33
	v_max3_f32 v80, v80, v62, v63
	v_cndmask_b32_e32 v82, v197, v32, vcc
	v_mul_f32_e32 v33, 0x3e38aa3b, v34
	v_max3_f32 v32, v80, v81, v82
	v_cndmask_b32_e32 v80, v197, v33, vcc
	v_mul_f32_e32 v33, 0x3e38aa3b, v35
	v_cndmask_b32_e32 v83, v197, v33, vcc
	v_mul_f32_e32 v33, 0x3e38aa3b, v36
	v_cndmask_b32_e32 v123, v197, v33, vcc
	v_mul_f32_e32 v33, 0x3e38aa3b, v37
	v_cndmask_b32_e32 v124, v197, v33, vcc
	v_mul_f32_e32 v33, 0x3e38aa3b, v38
	v_cndmask_b32_e32 v125, v197, v33, vcc
	v_mul_f32_e32 v33, 0x3e38aa3b, v39
	v_cndmask_b32_e32 v126, v197, v33, vcc
	v_mul_f32_e32 v33, 0x3e38aa3b, v40
	v_cndmask_b32_e32 v127, v197, v33, vcc
	v_mul_f32_e32 v33, 0x3e38aa3b, v41
	v_cndmask_b32_e32 v128, v197, v33, vcc
	v_mul_f32_e32 v33, 0x3e38aa3b, v42
	v_max3_f32 v32, v32, v80, v83
	v_cndmask_b32_e32 v129, v197, v33, vcc
	v_mul_f32_e32 v33, 0x3e38aa3b, v43
	v_max3_f32 v32, v32, v123, v124
	v_cndmask_b32_e32 v130, v197, v33, vcc
	v_mul_f32_e32 v33, 0x3e38aa3b, v44
	v_max3_f32 v32, v32, v125, v126
	v_cndmask_b32_e32 v131, v197, v33, vcc
	v_mul_f32_e32 v33, 0x3e38aa3b, v45
	v_max3_f32 v32, v32, v127, v128
	v_cndmask_b32_e32 v132, v197, v33, vcc
	v_mul_f32_e32 v33, 0x3e38aa3b, v46
	v_max3_f32 v32, v32, v129, v130
	v_cndmask_b32_e32 v133, v197, v33, vcc
	v_mul_f32_e32 v33, 0x3e38aa3b, v47
	v_max3_f32 v32, v32, v131, v132
	v_cndmask_b32_e32 v134, v197, v33, vcc
	s_cselect_b64 vcc, -1, 0
	v_max3_f32 v32, v32, v133, v134
	v_cndmask_b32_e32 v16, v16, v197, vcc
	v_cndmask_b32_e32 v17, v17, v197, vcc
	v_max3_f32 v32, v32, v16, v17
	v_cndmask_b32_e32 v18, v18, v197, vcc
	v_cndmask_b32_e32 v19, v19, v197, vcc
	v_max3_f32 v32, v32, v18, v19
	v_cndmask_b32_e32 v20, v20, v197, vcc
	v_cndmask_b32_e32 v21, v21, v197, vcc
	v_max3_f32 v32, v32, v20, v21
	v_cndmask_b32_e32 v22, v22, v197, vcc
	v_cndmask_b32_e32 v23, v23, v197, vcc
	v_max3_f32 v32, v32, v22, v23
	v_cndmask_b32_e32 v24, v24, v197, vcc
	v_cndmask_b32_e32 v25, v25, v197, vcc
	v_max3_f32 v32, v32, v24, v25
	v_cndmask_b32_e32 v26, v26, v197, vcc
	v_cndmask_b32_e32 v27, v27, v197, vcc
	v_max3_f32 v32, v32, v26, v27
	v_cndmask_b32_e32 v28, v28, v197, vcc
	v_cndmask_b32_e32 v29, v29, v197, vcc
	v_max3_f32 v32, v32, v28, v29
	v_cndmask_b32_e32 v30, v30, v197, vcc
	v_cndmask_b32_e32 v31, v31, v197, vcc
	v_mul_f32_e32 v0, 0x3e38aa3b, v0
	v_mul_f32_e32 v1, 0x3e38aa3b, v1
	v_max3_f32 v32, v32, v30, v31
	v_cndmask_b32_e64 v0, v0, v197, s[16:17]
	v_cndmask_b32_e64 v1, v1, v197, s[18:19]
	v_mul_f32_e32 v2, 0x3e38aa3b, v2
	v_mul_f32_e32 v3, 0x3e38aa3b, v3
	v_max3_f32 v32, v32, v0, v1
	v_cndmask_b32_e64 v2, v2, v197, s[20:21]
	v_cndmask_b32_e64 v3, v3, v197, s[38:39]
	v_mul_f32_e32 v4, 0x3e38aa3b, v4
	v_mul_f32_e32 v5, 0x3e38aa3b, v5
	v_max3_f32 v32, v32, v2, v3
	v_cndmask_b32_e64 v4, v4, v197, s[56:57]
	v_cndmask_b32_e64 v5, v5, v197, s[58:59]
	v_mul_f32_e32 v6, 0x3e38aa3b, v6
	v_mul_f32_e32 v7, 0x3e38aa3b, v7
	v_max3_f32 v32, v32, v4, v5
	v_cndmask_b32_e64 v6, v6, v197, s[60:61]
	v_cndmask_b32_e64 v7, v7, v197, s[62:63]
	v_mul_f32_e32 v8, 0x3e38aa3b, v8
	v_mul_f32_e32 v9, 0x3e38aa3b, v9
	v_max3_f32 v32, v32, v6, v7
	v_cndmask_b32_e64 v8, v8, v197, s[64:65]
	v_cndmask_b32_e64 v9, v9, v197, s[66:67]
	v_mul_f32_e32 v10, 0x3e38aa3b, v10
	v_mul_f32_e32 v11, 0x3e38aa3b, v11
	v_max3_f32 v32, v32, v8, v9
	v_cndmask_b32_e64 v10, v10, v197, s[68:69]
	v_cndmask_b32_e64 v11, v11, v197, s[70:71]
	v_mul_f32_e32 v12, 0x3e38aa3b, v12
	v_mul_f32_e32 v13, 0x3e38aa3b, v13
	v_max3_f32 v32, v32, v10, v11
	v_cndmask_b32_e64 v12, v12, v197, s[72:73]
	v_cndmask_b32_e64 v13, v13, v197, s[74:75]
	v_mul_f32_e32 v14, 0x3e38aa3b, v14
	v_mul_f32_e32 v15, 0x3e38aa3b, v15
	v_max3_f32 v32, v32, v12, v13
	v_cndmask_b32_e64 v14, v14, v197, s[76:77]
	v_cndmask_b32_e64 v15, v15, v197, s[78:79]
	v_max3_f32 v32, v32, v14, v15
	ds_bpermute_b32 v33, v89, v32
	s_waitcnt lgkmcnt(0)
; __device__ __forceinline__ void attn_fast(KArgs ap, int l, LAS unsigned char* lds, const Ctx cx) {
;     ...
;             m = fmaxf(m, __shfl_xor(m, 32));
;             float lsum = 0.f;
; #pragma unroll
;             for (int kt = 0; kt < 5; ++kt)
; #pragma unroll
;                 for (int i = 0; i < 16; ++i) { const float pv = __builtin_amdgcn_exp2f(st[kt][i] - m); st[kt][i] = pv; lsum += pv; }
;             lsum += __shfl_xor(lsum, 32); lsum += __builtin_amdgcn_exp2f(sink2 - m);
	v_max_f32_e32 v33, v33, v33
	v_max_f32_e32 v142, v32, v33
	v_sub_f32_e32 v32, v64, v142
	v_exp_f32_e32 v145, v32
	v_sub_f32_e32 v33, v65, v142
	v_exp_f32_e32 v146, v33
	v_sub_f32_e32 v33, v66, v142
	v_exp_f32_e32 v147, v33
	v_sub_f32_e32 v33, v67, v142
	v_exp_f32_e32 v148, v33
	v_sub_f32_e32 v33, v68, v142
	v_add_f32_e32 v32, 0, v145
	v_exp_f32_e32 v149, v33
	v_sub_f32_e32 v33, v69, v142
	v_add_f32_e32 v32, v146, v32
	v_exp_f32_e32 v150, v33
	v_sub_f32_e32 v33, v70, v142
	v_add_f32_e32 v32, v147, v32
	v_exp_f32_e32 v151, v33
	v_sub_f32_e32 v33, v71, v142
	v_add_f32_e32 v32, v148, v32
	v_exp_f32_e32 v152, v33
	v_add_f32_e32 v32, v149, v32
	v_add_f32_e32 v32, v150, v32
	v_add_f32_e32 v32, v151, v32
	v_add_f32_e32 v33, v152, v32
	v_sub_f32_e32 v32, v72, v142
	v_exp_f32_e32 v32, v32
	v_sub_f32_e32 v40, v79, v142
	v_exp_f32_e32 v40, v40
	v_sub_f32_e32 v64, v126, v142
	v_add_f32_e32 v34, v32, v33
	v_sub_f32_e32 v33, v73, v142
	v_exp_f32_e32 v33, v33
	v_exp_f32_e32 v64, v64
	v_sub_f32_e32 v72, v134, v142
	v_exp_f32_e32 v72, v72
	v_add_f32_e32 v35, v33, v34
	v_sub_f32_e32 v34, v74, v142
	v_exp_f32_e32 v34, v34
	v_sub_f32_e32 v16, v16, v142
	v_sub_f32_e32 v17, v17, v142
	v_sub_f32_e32 v0, v0, v142
	v_add_f32_e32 v36, v34, v35
	v_sub_f32_e32 v35, v75, v142
	v_exp_f32_e32 v35, v35
	v_exp_f32_e32 v126, v0
	v_sub_f32_e32 v1, v1, v142
	v_add_f32_e32 v37, v35, v36
	v_sub_f32_e32 v36, v76, v142
	v_exp_f32_e32 v36, v36
	s_nop 0
	v_add_f32_e32 v38, v36, v37
	v_sub_f32_e32 v37, v77, v142
	v_exp_f32_e32 v37, v37
	s_nop 0
	v_add_f32_e32 v39, v37, v38
	v_sub_f32_e32 v38, v78, v142
	v_exp_f32_e32 v38, v38
	s_nop 0
	v_add_f32_e32 v39, v38, v39
	v_add_f32_e32 v41, v40, v39
	v_sub_f32_e32 v39, v48, v142
	v_exp_f32_e32 v39, v39
	v_sub_f32_e32 v48, v55, v142
	v_exp_f32_e32 v48, v48
	v_add_f32_e32 v42, v39, v41
	v_sub_f32_e32 v41, v49, v142
	v_exp_f32_e32 v41, v41
	s_nop 0
	v_add_f32_e32 v43, v41, v42
	v_sub_f32_e32 v42, v50, v142
	v_exp_f32_e32 v42, v42
	s_nop 0
	v_add_f32_e32 v44, v42, v43
	v_sub_f32_e32 v43, v51, v142
	v_exp_f32_e32 v43, v43
	s_nop 0
	v_add_f32_e32 v45, v43, v44
	v_sub_f32_e32 v44, v52, v142
	v_exp_f32_e32 v44, v44
	s_nop 0
	v_add_f32_e32 v46, v44, v45
	v_sub_f32_e32 v45, v53, v142
	v_exp_f32_e32 v45, v45
	s_nop 0
	v_add_f32_e32 v47, v45, v46
	v_sub_f32_e32 v46, v54, v142
	v_exp_f32_e32 v46, v46
	s_nop 0
	v_add_f32_e32 v47, v46, v47
	v_add_f32_e32 v49, v48, v47
	v_sub_f32_e32 v47, v56, v142
	v_exp_f32_e32 v47, v47
	v_sub_f32_e32 v56, v63, v142
	v_exp_f32_e32 v56, v56
	v_add_f32_e32 v50, v47, v49
	v_sub_f32_e32 v49, v57, v142
	v_exp_f32_e32 v49, v49
	s_nop 0
	v_add_f32_e32 v51, v49, v50
	v_sub_f32_e32 v50, v58, v142
	v_exp_f32_e32 v50, v50
	s_nop 0
	v_add_f32_e32 v52, v50, v51
	v_sub_f32_e32 v51, v59, v142
	v_exp_f32_e32 v51, v51
	s_nop 0
	v_add_f32_e32 v53, v51, v52
	v_sub_f32_e32 v52, v60, v142
	v_exp_f32_e32 v52, v52
	s_nop 0
	v_add_f32_e32 v54, v52, v53
	v_sub_f32_e32 v53, v61, v142
	v_exp_f32_e32 v53, v53
	s_nop 0
	v_add_f32_e32 v55, v53, v54
	v_sub_f32_e32 v54, v62, v142
	v_exp_f32_e32 v54, v54
	s_nop 0
	v_add_f32_e32 v55, v54, v55
	v_add_f32_e32 v57, v56, v55
	v_sub_f32_e32 v55, v81, v142
	v_exp_f32_e32 v55, v55
	s_nop 0
	v_add_f32_e32 v58, v55, v57
	v_sub_f32_e32 v57, v82, v142
	v_exp_f32_e32 v57, v57
	s_nop 0
	v_add_f32_e32 v59, v57, v58
	v_sub_f32_e32 v58, v80, v142
	v_exp_f32_e32 v58, v58
	s_nop 0
	v_add_f32_e32 v60, v58, v59
	v_sub_f32_e32 v59, v83, v142
	v_exp_f32_e32 v59, v59
	s_nop 0
	v_add_f32_e32 v61, v59, v60
	v_sub_f32_e32 v60, v123, v142
	v_exp_f32_e32 v60, v60
	s_nop 0
	v_add_f32_e32 v62, v60, v61
	v_sub_f32_e32 v61, v124, v142
	v_exp_f32_e32 v61, v61
	s_nop 0
	v_add_f32_e32 v63, v61, v62
	v_sub_f32_e32 v62, v125, v142
	v_exp_f32_e32 v62, v62
	s_nop 0
	v_add_f32_e32 v63, v62, v63
	v_add_f32_e32 v65, v64, v63
	v_sub_f32_e32 v63, v127, v142
	v_exp_f32_e32 v63, v63
	s_nop 0
	v_add_f32_e32 v66, v63, v65
	v_sub_f32_e32 v65, v128, v142
	v_exp_f32_e32 v65, v65
	v_exp_f32_e32 v128, v1
	v_sub_f32_e32 v1, v2, v142
	v_sub_f32_e32 v2, v121, v142
	v_add_f32_e32 v67, v65, v66
	v_sub_f32_e32 v66, v129, v142
	v_exp_f32_e32 v66, v66
	v_exp_f32_e32 v129, v1
	v_sub_f32_e32 v1, v3, v142
	v_add_f32_e32 v68, v66, v67
	v_sub_f32_e32 v67, v130, v142
	v_exp_f32_e32 v67, v67
	v_exp_f32_e32 v130, v1
	v_sub_f32_e32 v1, v4, v142
	v_add_f32_e32 v69, v67, v68
	v_sub_f32_e32 v68, v131, v142
	v_exp_f32_e32 v68, v68
	v_exp_f32_e32 v131, v1
	v_sub_f32_e32 v1, v5, v142
	v_add_f32_e32 v70, v68, v69
	v_sub_f32_e32 v69, v132, v142
	v_exp_f32_e32 v69, v69
	v_exp_f32_e32 v132, v1
	v_sub_f32_e32 v1, v6, v142
	v_add_f32_e32 v71, v69, v70
	v_sub_f32_e32 v70, v133, v142
	v_exp_f32_e32 v70, v70
	v_exp_f32_e32 v133, v1
	v_sub_f32_e32 v1, v7, v142
	v_exp_f32_e32 v135, v1
	v_add_f32_e32 v71, v70, v71
	v_add_f32_e32 v73, v72, v71
	v_exp_f32_e32 v71, v16
	v_sub_f32_e32 v1, v8, v142
	v_exp_f32_e32 v134, v1
	v_sub_f32_e32 v1, v9, v142
	v_add_f32_e32 v16, v71, v73
	v_exp_f32_e32 v73, v17
	v_sub_f32_e32 v17, v18, v142
	v_exp_f32_e32 v74, v17
	v_sub_f32_e32 v17, v19, v142
	v_exp_f32_e32 v75, v17
	v_sub_f32_e32 v17, v20, v142
	v_exp_f32_e32 v76, v17
	v_sub_f32_e32 v17, v21, v142
	v_add_f32_e32 v16, v73, v16
	v_exp_f32_e32 v77, v17
	v_sub_f32_e32 v17, v22, v142
	v_add_f32_e32 v16, v74, v16
	v_exp_f32_e32 v78, v17
	v_sub_f32_e32 v17, v23, v142
	v_add_f32_e32 v16, v75, v16
	v_exp_f32_e32 v80, v17
	v_sub_f32_e32 v17, v24, v142
	v_add_f32_e32 v16, v76, v16
	v_exp_f32_e32 v79, v17
	v_sub_f32_e32 v17, v25, v142
	v_add_f32_e32 v16, v77, v16
	v_exp_f32_e32 v81, v17
	v_sub_f32_e32 v17, v26, v142
	v_add_f32_e32 v16, v78, v16
	v_exp_f32_e32 v82, v17
	v_sub_f32_e32 v17, v27, v142
	v_add_f32_e32 v16, v80, v16
	v_exp_f32_e32 v83, v17
	v_sub_f32_e32 v17, v28, v142
	v_add_f32_e32 v16, v79, v16
	v_exp_f32_e32 v123, v17
	v_sub_f32_e32 v17, v29, v142
	v_add_f32_e32 v16, v81, v16
	v_exp_f32_e32 v124, v17
	v_sub_f32_e32 v17, v30, v142
	v_add_f32_e32 v16, v82, v16
	v_exp_f32_e32 v125, v17
	v_sub_f32_e32 v17, v31, v142
	v_add_f32_e32 v16, v83, v16
	v_exp_f32_e32 v127, v17
	v_add_f32_e32 v16, v123, v16
	v_add_f32_e32 v16, v124, v16
	v_add_f32_e32 v16, v125, v16
	v_add_f32_e32 v16, v127, v16
	v_add_f32_e32 v0, v126, v16
	v_add_f32_e32 v0, v128, v0
	v_add_f32_e32 v0, v129, v0
	v_add_f32_e32 v0, v130, v0
	v_add_f32_e32 v0, v131, v0
	v_add_f32_e32 v0, v132, v0
	v_exp_f32_e32 v136, v1
	v_sub_f32_e32 v1, v10, v142
	v_add_f32_e32 v0, v133, v0
	v_exp_f32_e32 v137, v1
	v_sub_f32_e32 v1, v11, v142
	v_add_f32_e32 v0, v135, v0
	v_exp_f32_e32 v138, v1
	v_sub_f32_e32 v1, v12, v142
	v_add_f32_e32 v0, v134, v0
	v_exp_f32_e32 v139, v1
	v_sub_f32_e32 v1, v13, v142
	v_add_f32_e32 v0, v136, v0
	v_exp_f32_e32 v140, v1
	v_sub_f32_e32 v1, v14, v142
	v_add_f32_e32 v0, v137, v0
	v_exp_f32_e32 v141, v1
	v_sub_f32_e32 v1, v15, v142
	v_add_f32_e32 v0, v138, v0
	v_exp_f32_e32 v143, v1
	v_add_f32_e32 v0, v139, v0
	v_add_f32_e32 v0, v140, v0
	v_add_f32_e32 v0, v141, v0
	v_add_f32_e32 v0, v143, v0
	ds_bpermute_b32 v1, v89, v0
	v_exp_f32_e32 v142, v2
	s_waitcnt lgkmcnt(0)
; #define LAS __attribute__((address_space(3)))
; __device__ __forceinline__ unsigned pk2(float lo, float hi) { return f2bf(lo) | (f2bf(hi) << 16); }
; #define MFMA32(a_, b_, c_) __builtin_amdgcn_mfma_f32_32x32x16_bf16((a_), (b_), (c_), 0, 0, 0)
; __device__ __forceinline__ void attn_fast(KArgs ap, int l, LAS unsigned char* lds, const Ctx cx) {
;     ...
;             f32x16 o[2];
; #pragma unroll
;             for (int i = 0; i < 16; ++i) { o[0][i] = 0.f; o[1][i] = 0.f; }
; #pragma unroll
;             for (int kt = 0; kt < 5; ++kt)
; #pragma unroll
;                 for (int s2 = 0; s2 < 2; ++s2) {
;                     const bf16x8 pf = pack8(st[kt][8 * s2], st[kt][8 * s2 + 1], st[kt][8 * s2 + 2], st[kt][8 * s2 + 3], st[kt][8 * s2 + 4], st[kt][8 * s2 + 5], st[kt][8 * s2 + 6], st[kt][8 * s2 + 7]);
; #pragma unroll
;                     for (int dt = 0; dt < 2; ++dt) { const LAS unsigned char* va = VTL + (dt * 32 + r) * 520 + (i0 + 32 * kt + 16 * s2 + 4 * hh) * 2;
;                         const u32x2 lo = *(const LAS u32x2*)va, hi = *(const LAS u32x2*)(va + 16);
;                         const u32x4 vv = (u32x4){lo.x, lo.y, hi.x, hi.y};
;                         o[dt] = MFMA32(__builtin_bit_cast(bf16x8, vv), pf, o[dt]); }
;                 }
;             const float inv = 1.0f / lsum;
;             bf16_t* yp = y + (tok0 + i0 + r) * DM + YA + head * 64 + 4 * hh;
; #pragma unroll
;             for (int dt = 0; dt < 2; ++dt)
; #pragma unroll
;                 for (int q4 = 0; q4 < 4; ++q4) { u32x2 w; w.x = pk2(o[dt][4 * q4] * inv, o[dt][4 * q4 + 1] * inv); w.y = pk2(o[dt][4 * q4 + 2] * inv, o[dt][4 * q4 + 3] * inv);
;                     *(u32x2*)(yp + dt * 32 + 8 * q4) = w; }
	v_add_f32_e32 v144, v0, v1
	s_nop 1
	v_cvt_pk_bf16_f32 v0, v145, v146
	v_cvt_pk_bf16_f32 v1, v147, v148
	v_cvt_pk_bf16_f32 v2, v149, v150
	v_cvt_pk_bf16_f32 v3, v151, v152
	s_nop 1
	v_add_u32_e32 v145, s30, v114
	ds_read2_b64 v[4:7], v145 offset0:32 offset1:34
	v_add_u32_e32 v150, s30, v113
	s_waitcnt lgkmcnt(0)
	v_mfma_f32_32x32x16_bf16 v[16:31], v[4:7], v[0:3], 0
	ds_read2_b64 v[4:7], v150 offset0:32 offset1:34
	s_nop 1
	v_cvt_pk_bf16_f32 v146, v32, v33
	v_cvt_pk_bf16_f32 v147, v34, v35
	v_cvt_pk_bf16_f32 v148, v36, v37
	v_cvt_pk_bf16_f32 v149, v38, v40
	s_nop 1
	ds_read2_b64 v[32:35], v145 offset0:36 offset1:38
	s_add_i32 s30, s30, 64
	s_cmp_eq_u32 s30, 0
	s_waitcnt lgkmcnt(0)
	v_mfma_f32_32x32x16_bf16 v[16:31], v[32:35], v[146:149], v[16:31]
	ds_read2_b64 v[32:35], v150 offset0:36 offset1:38
	v_mfma_f32_32x32x16_bf16 v[0:15], v[4:7], v[0:3], 0
	s_waitcnt lgkmcnt(0)
	v_mfma_f32_32x32x16_bf16 v[0:15], v[32:35], v[146:149], v[0:15]
	s_nop 1
	v_cvt_pk_bf16_f32 v32, v39, v41
	v_cvt_pk_bf16_f32 v33, v42, v43
	v_cvt_pk_bf16_f32 v34, v44, v45
	v_cvt_pk_bf16_f32 v35, v46, v48
	s_nop 1
	ds_read2_b64 v[36:39], v145 offset0:40 offset1:42
	s_waitcnt lgkmcnt(0)
	v_mfma_f32_32x32x16_bf16 v[16:31], v[36:39], v[32:35], v[16:31]
	ds_read2_b64 v[36:39], v150 offset0:40 offset1:42
	s_waitcnt lgkmcnt(0)
	v_mfma_f32_32x32x16_bf16 v[0:15], v[36:39], v[32:35], v[0:15]
	s_nop 1
	v_cvt_pk_bf16_f32 v32, v47, v49
	v_cvt_pk_bf16_f32 v33, v50, v51
	v_cvt_pk_bf16_f32 v34, v52, v53
	v_cvt_pk_bf16_f32 v35, v54, v56
	s_nop 1
	ds_read2_b64 v[36:39], v145 offset0:44 offset1:46
	s_waitcnt lgkmcnt(0)
	v_mfma_f32_32x32x16_bf16 v[16:31], v[36:39], v[32:35], v[16:31]
	ds_read2_b64 v[36:39], v150 offset0:44 offset1:46
	s_waitcnt lgkmcnt(0)
	v_mfma_f32_32x32x16_bf16 v[0:15], v[36:39], v[32:35], v[0:15]
	s_nop 1
	v_cvt_pk_bf16_f32 v32, v55, v57
	v_cvt_pk_bf16_f32 v33, v58, v59
	v_cvt_pk_bf16_f32 v34, v60, v61
	v_cvt_pk_bf16_f32 v35, v62, v64
	s_nop 1
	ds_read2_b64 v[36:39], v145 offset0:48 offset1:50
	s_waitcnt lgkmcnt(0)
	v_mfma_f32_32x32x16_bf16 v[16:31], v[36:39], v[32:35], v[16:31]
	ds_read2_b64 v[36:39], v150 offset0:48 offset1:50
	s_waitcnt lgkmcnt(0)
	v_mfma_f32_32x32x16_bf16 v[0:15], v[36:39], v[32:35], v[0:15]
	s_nop 1
	v_cvt_pk_bf16_f32 v32, v63, v65
	v_cvt_pk_bf16_f32 v33, v66, v67
	v_cvt_pk_bf16_f32 v34, v68, v69
	v_cvt_pk_bf16_f32 v35, v70, v72
	s_nop 1
	ds_read2_b64 v[36:39], v145 offset0:52 offset1:54
	s_waitcnt lgkmcnt(0)
	v_mfma_f32_32x32x16_bf16 v[16:31], v[36:39], v[32:35], v[16:31]
	ds_read2_b64 v[36:39], v150 offset0:52 offset1:54
	s_waitcnt lgkmcnt(0)
	v_mfma_f32_32x32x16_bf16 v[0:15], v[36:39], v[32:35], v[0:15]
	s_nop 1
	v_cvt_pk_bf16_f32 v32, v71, v73
	v_cvt_pk_bf16_f32 v33, v74, v75
	v_cvt_pk_bf16_f32 v34, v76, v77
	v_cvt_pk_bf16_f32 v35, v78, v80
	s_nop 1
	ds_read2_b64 v[36:39], v145 offset0:56 offset1:58
	s_waitcnt lgkmcnt(0)
	v_mfma_f32_32x32x16_bf16 v[16:31], v[36:39], v[32:35], v[16:31]
	ds_read2_b64 v[36:39], v150 offset0:56 offset1:58
	s_waitcnt lgkmcnt(0)
	v_mfma_f32_32x32x16_bf16 v[0:15], v[36:39], v[32:35], v[0:15]
	s_nop 1
	v_cvt_pk_bf16_f32 v32, v79, v81
	v_cvt_pk_bf16_f32 v33, v82, v83
	v_cvt_pk_bf16_f32 v34, v123, v124
	v_cvt_pk_bf16_f32 v35, v125, v127
	s_nop 1
	ds_read2_b64 v[36:39], v145 offset0:60 offset1:62
	v_mov_b32_e32 v123, v122
	s_waitcnt lgkmcnt(0)
	v_mfma_f32_32x32x16_bf16 v[16:31], v[36:39], v[32:35], v[16:31]
	ds_read2_b64 v[36:39], v150 offset0:60 offset1:62
	s_waitcnt lgkmcnt(0)
	v_mfma_f32_32x32x16_bf16 v[0:15], v[36:39], v[32:35], v[0:15]
	s_nop 1
	v_cvt_pk_bf16_f32 v32, v126, v128
	v_cvt_pk_bf16_f32 v33, v129, v130
	v_cvt_pk_bf16_f32 v34, v131, v132
	v_cvt_pk_bf16_f32 v35, v133, v135
	s_nop 1
	ds_read2_b64 v[36:39], v145 offset0:64 offset1:66
	s_waitcnt lgkmcnt(0)
	v_mfma_f32_32x32x16_bf16 v[16:31], v[36:39], v[32:35], v[16:31]
	ds_read2_b64 v[36:39], v150 offset0:64 offset1:66
	s_waitcnt lgkmcnt(0)
	v_mfma_f32_32x32x16_bf16 v[0:15], v[36:39], v[32:35], v[0:15]
	s_nop 1
	v_cvt_pk_bf16_f32 v32, v134, v136
	v_cvt_pk_bf16_f32 v33, v137, v138
	v_cvt_pk_bf16_f32 v34, v139, v140
	v_cvt_pk_bf16_f32 v35, v141, v143
	s_nop 1
	ds_read2_b64 v[36:39], v145 offset0:68 offset1:70
	s_waitcnt lgkmcnt(0)
	v_mfma_f32_32x32x16_bf16 v[16:31], v[36:39], v[32:35], v[16:31]
	ds_read2_b64 v[36:39], v150 offset0:68 offset1:70
	s_waitcnt lgkmcnt(0)
	v_mfma_f32_32x32x16_bf16 v[0:15], v[36:39], v[32:35], v[0:15]
	v_add_f32_e32 v32, v142, v144
	v_div_scale_f32 v33, vcc, v32, v32, 1.0
	v_rcp_f32_e32 v34, v33
	s_nop 0
	v_fma_f32 v35, -v33, v34, 1.0
	v_fmac_f32_e32 v34, v35, v34
	v_div_scale_f32 v35, vcc, 1.0, v32, 1.0
	v_mul_f32_e32 v36, v35, v34
	v_fma_f32 v37, -v33, v36, v35
	v_fmac_f32_e32 v36, v37, v34
	v_fma_f32 v33, -v33, v36, v35
	v_div_fmas_f32 v33, v33, v34, v36
	v_div_fixup_f32 v32, v33, v32, 1.0
	v_mul_f32_e32 v16, v16, v32
	v_mul_f32_e32 v17, v17, v32
	v_mul_f32_e32 v18, v18, v32
	v_mul_f32_e32 v19, v19, v32
	v_mul_f32_e32 v20, v20, v32
	v_mul_f32_e32 v21, v21, v32
	v_mul_f32_e32 v22, v22, v32
	v_mul_f32_e32 v23, v23, v32
	v_mul_f32_e32 v24, v24, v32
	v_mul_f32_e32 v25, v25, v32
	v_mul_f32_e32 v26, v26, v32
	v_mul_f32_e32 v27, v27, v32
	v_mul_f32_e32 v28, v28, v32
	v_mul_f32_e32 v29, v29, v32
	v_mul_f32_e32 v30, v30, v32
	v_mul_f32_e32 v31, v31, v32
	v_mul_f32_e32 v0, v0, v32
	v_mul_f32_e32 v1, v1, v32
	v_mul_f32_e32 v2, v2, v32
	v_mul_f32_e32 v3, v3, v32
	v_mul_f32_e32 v4, v4, v32
	v_mul_f32_e32 v5, v5, v32
	v_mul_f32_e32 v6, v6, v32
	v_mul_f32_e32 v7, v7, v32
	v_mul_f32_e32 v8, v8, v32
	v_mul_f32_e32 v9, v9, v32
	v_mul_f32_e32 v10, v10, v32
	v_mul_f32_e32 v11, v11, v32
	v_mul_f32_e32 v12, v12, v32
	v_mul_f32_e32 v13, v13, v32
	v_mul_f32_e32 v14, v14, v32
	v_mul_f32_e32 v15, v15, v32
	v_cvt_pk_bf16_f32 v170, v16, v17
	v_cvt_pk_bf16_f32 v171, v18, v19
	v_cvt_pk_bf16_f32 v172, v20, v21
	v_cvt_pk_bf16_f32 v173, v22, v23
	v_cvt_pk_bf16_f32 v174, v24, v25
	v_cvt_pk_bf16_f32 v175, v26, v27
	v_cvt_pk_bf16_f32 v176, v28, v29
	v_cvt_pk_bf16_f32 v177, v30, v31
	v_cvt_pk_bf16_f32 v178, v0, v1
	v_cvt_pk_bf16_f32 v179, v2, v3
	v_cvt_pk_bf16_f32 v180, v4, v5
	v_cvt_pk_bf16_f32 v181, v6, v7
	v_cvt_pk_bf16_f32 v182, v8, v9
	v_cvt_pk_bf16_f32 v183, v10, v11
	v_cvt_pk_bf16_f32 v184, v12, v13
	v_cvt_pk_bf16_f32 v185, v14, v15
	global_store_dwordx2 v[110:111], v[170:171], off offset:-64
	global_store_dwordx2 v[110:111], v[172:173], off offset:-48
	global_store_dwordx2 v[110:111], v[174:175], off offset:-32
	global_store_dwordx2 v[110:111], v[176:177], off offset:-16
	global_store_dwordx2 v[110:111], v[178:179], off
	global_store_dwordx2 v[110:111], v[180:181], off offset:16
	global_store_dwordx2 v[110:111], v[182:183], off offset:32
	global_store_dwordx2 v[110:111], v[184:185], off offset:48
	s_mov_b64 vcc, 0x2c000
	v_lshl_add_u64 v[108:109], v[108:109], 0, vcc
	s_mov_b64 vcc, 0x20000
	v_lshl_add_u64 v[110:111], v[110:111], 0, vcc
	s_cbranch_scc0 .LBB0_135
; __device__ __forceinline__ void attn_fast(KArgs ap, int l, LAS unsigned char* lds, const Ctx cx) {
;     ...
;     for (int u = cx.bid; u < BATCH * (SEQ / 128) * 2; u += cx.nb) {
;         const int kvh = u & 1, nbk = u >> 1, nb = nbk & 127;
	v_readlane_b32 s0, v242, 9
	v_readlane_b32 s1, v242, 10
	s_add_i32 s41, s41, s55
	s_xor_b64 s[24:25], s[24:25], s[0:1]
	s_cmpk_gt_i32 s41, 0x1ff
	s_mov_b32 s80, s22
	s_cbranch_scc0 .LBB0_124
	v_readlane_b32 s78, v243, 14
	v_readlane_b32 s79, v243, 15
	s_mov_b32 s77, s23
	v_readlane_b32 s62, v243, 25
	v_readlane_b32 s57, v242, 8
	v_readlane_b32 s63, v243, 26

; __device__ __forceinline__ unsigned pk2(float lo, float hi) { return f2bf(lo) | (f2bf(hi) << 16); }
; __device__ __forceinline__ void gmlp_fast(KArgs ap, int l, LAS unsigned char* lds, const Ctx cx) {
;     ...
;             const size_t t = t0 + tl; const float bsv = bsp[g * 128 + tl];
;             const bf16_t* zu = z + t * DIN + ZGU + g * 128 + 4 * hh; bf16_t* yo = y + t * DM + YG + g * 128 + 4 * hh;
; #pragma unroll
;             for (int ht = 0; ht < 4; ++ht)
; #pragma unroll
;                 for (int q4 = 0; q4 < 4; ++q4) { const u32x2 uu = *(const u32x2*)(zu + ht * 32 + 8 * q4);
;                     const float o0 = gelu_tanh(bflo(uu.x)) * (acc[ht][4 * q4] + bsv), o1 = gelu_tanh(bfhi(uu.x)) * (acc[ht][4 * q4 + 1] + bsv);
;                     const float o2 = gelu_tanh(bflo(uu.y)) * (acc[ht][4 * q4 + 2] + bsv), o3 = gelu_tanh(bfhi(uu.y)) * (acc[ht][4 * q4 + 3] + bsv);
;                     u32x2 w; w.x = pk2(o0, o1); w.y = pk2(o2, o3); *(u32x2*)(yo + ht * 32 + 8 * q4) = w; }
.LBB0_160:
	s_lshl_b32 s20, s20, 7
	s_ashr_i32 s21, s20, 31
	v_or_b32_e32 v64, s20, v80
	s_lshl_b64 s[20:21], s[20:21], 1
	v_lshl_add_u64 v[68:69], v[94:95], 0, s[20:21]
	global_load_dwordx2 v[70:71], v[68:69], off offset:3584
	v_ashrrev_i32_e32 v65, 31, v64
	v_lshl_add_u64 v[64:65], v[64:65], 2, s[14:15]
	global_load_dword v64, v[64:65], off
	global_load_dwordx2 v[200:201], v[68:69], off offset:3600
	global_load_dwordx2 v[202:203], v[68:69], off offset:3616
	global_load_dwordx2 v[204:205], v[68:69], off offset:3632
	global_load_dwordx2 v[206:207], v[68:69], off offset:3648
	global_load_dwordx2 v[208:209], v[68:69], off offset:3664
	global_load_dwordx2 v[210:211], v[68:69], off offset:3680
	global_load_dwordx2 v[212:213], v[68:69], off offset:3696
	global_load_dwordx2 v[214:215], v[68:69], off offset:3712
	global_load_dwordx2 v[216:217], v[68:69], off offset:3728
	global_load_dwordx2 v[218:219], v[68:69], off offset:3744
	global_load_dwordx2 v[220:221], v[68:69], off offset:3760
	global_load_dwordx2 v[222:223], v[68:69], off offset:3776
	global_load_dwordx2 v[224:225], v[68:69], off offset:3792
	global_load_dwordx2 v[226:227], v[68:69], off offset:3808
	global_load_dwordx2 v[228:229], v[68:69], off offset:3824
	v_lshl_add_u64 v[66:67], v[96:97], 0, s[20:21]
	s_mov_b32 s13, 1
	s_mov_b64 s[20:21], 0
	s_and_b64 vcc, exec, s[0:1]
	s_waitcnt vmcnt(16)
	v_lshlrev_b32_e32 v72, 16, v70
	v_mul_f32_e32 v65, 0x3d372713, v72
	v_mul_f32_e32 v65, v65, v72
	v_mov_b32_e32 v74, v72
	v_fmac_f32_e32 v74, v65, v74
	v_mul_f32_e32 v65, 0x3f4c422a, v74
	v_add_f32_e32 v65, v65, v65
	v_mul_f32_e32 v65, 0x3fb8aa3b, v65
	v_exp_f32_e32 v65, v65
	v_and_b32_e32 v70, 0xffff0000, v70
	v_mov_b32_e32 v75, v70
	v_lshlrev_b32_e32 v73, 16, v71
	v_add_f32_e32 v65, 1.0, v65
	v_rcp_f32_e32 v74, v65
	v_mul_f32_e32 v65, 0x3d372713, v70
	v_mul_f32_e32 v65, v65, v70
	v_fmac_f32_e32 v75, v65, v75
	v_mul_f32_e32 v65, 0x3f4c422a, v75
	v_add_f32_e32 v65, v65, v65
	v_mul_f32_e32 v65, 0x3fb8aa3b, v65
	v_exp_f32_e32 v65, v65
	v_mov_b32_e32 v75, v73
	v_and_b32_e32 v71, 0xffff0000, v71
	v_add_f32_e32 v65, 1.0, v65
	v_rcp_f32_e32 v76, v65
	v_mul_f32_e32 v65, 0x3d372713, v73
	v_mul_f32_e32 v65, v65, v73
	v_fmac_f32_e32 v75, v65, v75
	v_mul_f32_e32 v65, 0x3f4c422a, v75
	v_add_f32_e32 v65, v65, v65
	v_mul_f32_e32 v65, 0x3fb8aa3b, v65
	v_exp_f32_e32 v65, v65
	v_pk_mul_f32 v[72:73], v[72:73], 0.5 op_sel_hi:[1,0]
	v_add_f32_e32 v65, 1.0, v65
	v_rcp_f32_e32 v75, v65
	s_nop 0
	v_pk_fma_f32 v[74:75], v[74:75], 2.0, 1.0 op_sel_hi:[1,0,0] neg_lo:[1,0,0] neg_hi:[1,0,0]
	s_nop 0
	v_pk_add_f32 v[74:75], v[74:75], 1.0 op_sel_hi:[1,0]
	s_nop 0
	v_pk_mul_f32 v[72:73], v[72:73], v[74:75]
	v_mov_b32_e32 v74, v48
	v_mul_f32_e32 v48, 0x3d372713, v71
	v_mov_b32_e32 v75, v50
	v_mul_f32_e32 v48, v48, v71
	v_mov_b32_e32 v50, v71
	v_fmac_f32_e32 v50, v48, v50
	v_mul_f32_e32 v48, 0x3f4c422a, v50
	v_add_f32_e32 v48, v48, v48
	v_mul_f32_e32 v48, 0x3fb8aa3b, v48
	v_exp_f32_e32 v48, v48
	s_waitcnt vmcnt(15)
	v_pk_add_f32 v[74:75], v[74:75], v[64:65] op_sel_hi:[1,0]
	v_pk_mul_f32 v[70:71], v[70:71], 0.5 op_sel_hi:[1,0]
	v_pk_mul_f32 v[72:73], v[74:75], v[72:73]
	v_add_f32_e32 v48, 1.0, v48
	v_rcp_f32_e32 v77, v48
	v_mov_b32_e32 v50, v49
	v_pk_add_f32 v[48:49], v[50:51], v[64:65] op_sel_hi:[1,0]
	v_and_b32_sdwa v50, v73, v196 dst_sel:DWORD dst_unused:UNUSED_PAD src0_sel:WORD_1 src1_sel:DWORD
	v_pk_fma_f32 v[74:75], v[76:77], 2.0, 1.0 op_sel_hi:[1,0,0] neg_lo:[1,0,0] neg_hi:[1,0,0]
	v_and_b32_sdwa v51, v72, v196 dst_sel:DWORD dst_unused:UNUSED_PAD src0_sel:WORD_1 src1_sel:DWORD
	v_pk_add_f32 v[74:75], v[74:75], 1.0 op_sel_hi:[1,0]
	v_add3_u32 v51, v72, v51, s45
	v_pk_mul_f32 v[70:71], v[70:71], v[74:75]
	v_add3_u32 v50, v73, v50, s45
	v_pk_mul_f32 v[48:49], v[48:49], v[70:71]
	s_nop 0
	v_and_b32_sdwa v65, v49, v196 dst_sel:DWORD dst_unused:UNUSED_PAD src0_sel:WORD_1 src1_sel:DWORD
	v_and_b32_sdwa v70, v48, v196 dst_sel:DWORD dst_unused:UNUSED_PAD src0_sel:WORD_1 src1_sel:DWORD
	v_add3_u32 v49, v49, v65, s45
	v_add3_u32 v48, v48, v70, s45
	v_and_b32_e32 v49, 0xffff0000, v49
	v_and_b32_e32 v48, 0xffff0000, v48
	v_or_b32_sdwa v49, v49, v50 dst_sel:DWORD dst_unused:UNUSED_PAD src0_sel:DWORD src1_sel:WORD_1
	v_or_b32_sdwa v48, v48, v51 dst_sel:DWORD dst_unused:UNUSED_PAD src0_sel:DWORD src1_sel:WORD_1
	global_store_dwordx2 v[66:67], v[48:49], off
	s_waitcnt vmcnt(15)
; __device__ __forceinline__ unsigned pk2(float lo, float hi) { return f2bf(lo) | (f2bf(hi) << 16); }
; __device__ __forceinline__ void gmlp_fast(KArgs ap, int l, LAS unsigned char* lds, const Ctx cx) {
;     ...
;                 for (int q4 = 0; q4 < 4; ++q4) { const u32x2 uu = *(const u32x2*)(zu + ht * 32 + 8 * q4);
;                     const float o0 = gelu_tanh(bflo(uu.x)) * (acc[ht][4 * q4] + bsv), o1 = gelu_tanh(bfhi(uu.x)) * (acc[ht][4 * q4 + 1] + bsv);
;                     const float o2 = gelu_tanh(bflo(uu.y)) * (acc[ht][4 * q4 + 2] + bsv), o3 = gelu_tanh(bfhi(uu.y)) * (acc[ht][4 * q4 + 3] + bsv);
;                     u32x2 w; w.x = pk2(o0, o1); w.y = pk2(o2, o3); *(u32x2*)(yo + ht * 32 + 8 * q4) = w; }
	v_mov_b32_e32 v48, v200
	v_mov_b32_e32 v49, v201
	v_lshlrev_b32_e32 v50, 16, v48
	v_mul_f32_e32 v65, 0x3d372713, v50
	v_mul_f32_e32 v65, v65, v50
	v_mov_b32_e32 v70, v50
	v_fmac_f32_e32 v70, v65, v70
	v_mul_f32_e32 v65, 0x3f4c422a, v70
	v_add_f32_e32 v65, v65, v65
	v_mul_f32_e32 v65, 0x3fb8aa3b, v65
	v_exp_f32_e32 v65, v65
	v_and_b32_e32 v48, 0xffff0000, v48
	v_mov_b32_e32 v71, v48
	v_lshlrev_b32_e32 v51, 16, v49
	v_add_f32_e32 v65, 1.0, v65
	v_rcp_f32_e32 v70, v65
	v_mul_f32_e32 v65, 0x3d372713, v48
	v_mul_f32_e32 v65, v65, v48
	v_fmac_f32_e32 v71, v65, v71
	v_mul_f32_e32 v65, 0x3f4c422a, v71
	v_add_f32_e32 v65, v65, v65
	v_mul_f32_e32 v65, 0x3fb8aa3b, v65
	v_exp_f32_e32 v65, v65
	v_mov_b32_e32 v71, v51
	v_and_b32_e32 v49, 0xffff0000, v49
	v_add_f32_e32 v65, 1.0, v65
	v_rcp_f32_e32 v72, v65
	v_mul_f32_e32 v65, 0x3d372713, v51
	v_mul_f32_e32 v65, v65, v51
	v_fmac_f32_e32 v71, v65, v71
	v_mul_f32_e32 v65, 0x3f4c422a, v71
	v_add_f32_e32 v65, v65, v65
	v_mul_f32_e32 v65, 0x3fb8aa3b, v65
	v_exp_f32_e32 v65, v65
	v_pk_mul_f32 v[50:51], v[50:51], 0.5 op_sel_hi:[1,0]
	v_add_f32_e32 v65, 1.0, v65
	v_rcp_f32_e32 v71, v65
	s_nop 0
	v_pk_fma_f32 v[70:71], v[70:71], 2.0, 1.0 op_sel_hi:[1,0,0] neg_lo:[1,0,0] neg_hi:[1,0,0]
	s_nop 0
	v_pk_add_f32 v[70:71], v[70:71], 1.0 op_sel_hi:[1,0]
	s_nop 0
	v_pk_mul_f32 v[50:51], v[50:51], v[70:71]
	v_mov_b32_e32 v70, v52
	v_mul_f32_e32 v52, 0x3d372713, v49
	v_mov_b32_e32 v71, v54
	v_mul_f32_e32 v52, v52, v49
	v_mov_b32_e32 v54, v49
	v_fmac_f32_e32 v54, v52, v54
	v_mul_f32_e32 v52, 0x3f4c422a, v54
	v_add_f32_e32 v52, v52, v52
	v_mul_f32_e32 v52, 0x3fb8aa3b, v52
	v_exp_f32_e32 v52, v52
	v_pk_add_f32 v[70:71], v[70:71], v[64:65] op_sel_hi:[1,0]
	v_pk_mul_f32 v[48:49], v[48:49], 0.5 op_sel_hi:[1,0]
	v_pk_mul_f32 v[50:51], v[70:71], v[50:51]
	v_add_f32_e32 v52, 1.0, v52
	v_rcp_f32_e32 v73, v52
	v_mov_b32_e32 v54, v53
	v_pk_add_f32 v[52:53], v[54:55], v[64:65] op_sel_hi:[1,0]
	v_pk_fma_f32 v[70:71], v[72:73], 2.0, 1.0 op_sel_hi:[1,0,0] neg_lo:[1,0,0] neg_hi:[1,0,0]
	s_nop 0
	v_pk_add_f32 v[70:71], v[70:71], 1.0 op_sel_hi:[1,0]
	s_nop 0
	v_pk_mul_f32 v[48:49], v[48:49], v[70:71]
	s_nop 0
	v_pk_mul_f32 v[48:49], v[52:53], v[48:49]
	v_and_b32_sdwa v52, v51, v196 dst_sel:DWORD dst_unused:UNUSED_PAD src0_sel:WORD_1 src1_sel:DWORD
	v_and_b32_sdwa v53, v50, v196 dst_sel:DWORD dst_unused:UNUSED_PAD src0_sel:WORD_1 src1_sel:DWORD
	v_add3_u32 v50, v50, v53, s45
	v_add3_u32 v51, v51, v52, s45
	v_and_b32_sdwa v52, v49, v196 dst_sel:DWORD dst_unused:UNUSED_PAD src0_sel:WORD_1 src1_sel:DWORD
	v_and_b32_sdwa v53, v48, v196 dst_sel:DWORD dst_unused:UNUSED_PAD src0_sel:WORD_1 src1_sel:DWORD
	v_add3_u32 v49, v49, v52, s45
	v_add3_u32 v48, v48, v53, s45
	v_and_b32_e32 v49, 0xffff0000, v49
	v_and_b32_e32 v48, 0xffff0000, v48
	v_or_b32_sdwa v49, v49, v51 dst_sel:DWORD dst_unused:UNUSED_PAD src0_sel:DWORD src1_sel:WORD_1
	v_or_b32_sdwa v48, v48, v50 dst_sel:DWORD dst_unused:UNUSED_PAD src0_sel:DWORD src1_sel:WORD_1
	global_store_dwordx2 v[66:67], v[48:49], off offset:16
	s_waitcnt vmcnt(15)
	v_mov_b32_e32 v48, v202
	v_mov_b32_e32 v49, v203
	v_lshlrev_b32_e32 v50, 16, v48
	v_mul_f32_e32 v52, 0x3d372713, v50
	v_mul_f32_e32 v52, v52, v50
	v_mov_b32_e32 v53, v50
	v_fmac_f32_e32 v53, v52, v53
	v_and_b32_e32 v48, 0xffff0000, v48
	v_mul_f32_e32 v52, 0x3f4c422a, v53
	v_mul_f32_e32 v53, 0x3d372713, v48
	v_mul_f32_e32 v53, v53, v48
	v_mov_b32_e32 v54, v48
	v_fmac_f32_e32 v54, v53, v54
	v_mul_f32_e32 v53, 0x3f4c422a, v54
	v_add_f32_e32 v53, v53, v53
	v_mul_f32_e32 v53, 0x3fb8aa3b, v53
	v_exp_f32_e32 v53, v53
	v_lshlrev_b32_e32 v51, 16, v49
	v_mov_b32_e32 v55, v51
	v_add_f32_e32 v52, v52, v52
	v_add_f32_e32 v53, 1.0, v53
	v_rcp_f32_e32 v54, v53
	v_mul_f32_e32 v53, 0x3d372713, v51
	v_mul_f32_e32 v53, v53, v51
	v_fmac_f32_e32 v55, v53, v55
	v_mul_f32_e32 v53, 0x3f4c422a, v55
	v_add_f32_e32 v53, v53, v53
	v_mul_f32_e32 v52, 0x3fb8aa3b, v52
	v_mul_f32_e32 v53, 0x3fb8aa3b, v53
	v_exp_f32_e32 v52, v52
	v_exp_f32_e32 v53, v53
	v_pk_mul_f32 v[50:51], v[50:51], 0.5 op_sel_hi:[1,0]
	v_and_b32_e32 v49, 0xffff0000, v49
	v_add_f32_e32 v52, 1.0, v52
	v_add_f32_e32 v53, 1.0, v53
	v_rcp_f32_e32 v52, v52
	v_rcp_f32_e32 v53, v53
	s_nop 0
	v_pk_fma_f32 v[52:53], v[52:53], 2.0, 1.0 op_sel_hi:[1,0,0] neg_lo:[1,0,0] neg_hi:[1,0,0]
	s_nop 0
	v_pk_add_f32 v[52:53], v[52:53], 1.0 op_sel_hi:[1,0]
	s_nop 0
	v_pk_mul_f32 v[50:51], v[50:51], v[52:53]
	v_mov_b32_e32 v52, v56
	v_mov_b32_e32 v53, v58
	v_pk_add_f32 v[52:53], v[52:53], v[64:65] op_sel_hi:[1,0]
	v_mov_b32_e32 v58, v57
	v_pk_mul_f32 v[50:51], v[52:53], v[50:51]
	v_mul_f32_e32 v52, 0x3d372713, v49
	v_mul_f32_e32 v52, v52, v49
	v_mov_b32_e32 v53, v49
	v_fmac_f32_e32 v53, v52, v53
	v_mul_f32_e32 v52, 0x3f4c422a, v53
	v_add_f32_e32 v52, v52, v52
	v_mul_f32_e32 v52, 0x3fb8aa3b, v52
	v_exp_f32_e32 v52, v52
	v_pk_mul_f32 v[48:49], v[48:49], 0.5 op_sel_hi:[1,0]
	v_add_f32_e32 v52, 1.0, v52
	v_rcp_f32_e32 v55, v52
	s_nop 0
	v_pk_fma_f32 v[52:53], v[54:55], 2.0, 1.0 op_sel_hi:[1,0,0] neg_lo:[1,0,0] neg_hi:[1,0,0]
	s_nop 0
	v_pk_add_f32 v[52:53], v[52:53], 1.0 op_sel_hi:[1,0]
	s_nop 0
	v_pk_mul_f32 v[48:49], v[48:49], v[52:53]
	v_pk_add_f32 v[52:53], v[58:59], v[64:65] op_sel_hi:[1,0]
	s_nop 0
	v_pk_mul_f32 v[48:49], v[52:53], v[48:49]
	v_and_b32_sdwa v52, v51, v196 dst_sel:DWORD dst_unused:UNUSED_PAD src0_sel:WORD_1 src1_sel:DWORD
	v_and_b32_sdwa v53, v50, v196 dst_sel:DWORD dst_unused:UNUSED_PAD src0_sel:WORD_1 src1_sel:DWORD
	v_add3_u32 v50, v50, v53, s45
	v_add3_u32 v51, v51, v52, s45
	v_and_b32_sdwa v52, v49, v196 dst_sel:DWORD dst_unused:UNUSED_PAD src0_sel:WORD_1 src1_sel:DWORD
	v_and_b32_sdwa v53, v48, v196 dst_sel:DWORD dst_unused:UNUSED_PAD src0_sel:WORD_1 src1_sel:DWORD
	v_add3_u32 v49, v49, v52, s45
	v_add3_u32 v48, v48, v53, s45
	v_and_b32_e32 v49, 0xffff0000, v49
	v_and_b32_e32 v48, 0xffff0000, v48
	v_or_b32_sdwa v49, v49, v51 dst_sel:DWORD dst_unused:UNUSED_PAD src0_sel:DWORD src1_sel:WORD_1
	v_or_b32_sdwa v48, v48, v50 dst_sel:DWORD dst_unused:UNUSED_PAD src0_sel:DWORD src1_sel:WORD_1
	global_store_dwordx2 v[66:67], v[48:49], off offset:32
	s_waitcnt vmcnt(15)
; __device__ __forceinline__ unsigned pk2(float lo, float hi) { return f2bf(lo) | (f2bf(hi) << 16); }
; __device__ __forceinline__ void gmlp_fast(KArgs ap, int l, LAS unsigned char* lds, const Ctx cx) {
;     ...
;                 for (int q4 = 0; q4 < 4; ++q4) { const u32x2 uu = *(const u32x2*)(zu + ht * 32 + 8 * q4);
;                     const float o0 = gelu_tanh(bflo(uu.x)) * (acc[ht][4 * q4] + bsv), o1 = gelu_tanh(bfhi(uu.x)) * (acc[ht][4 * q4 + 1] + bsv);
;                     const float o2 = gelu_tanh(bflo(uu.y)) * (acc[ht][4 * q4 + 2] + bsv), o3 = gelu_tanh(bfhi(uu.y)) * (acc[ht][4 * q4 + 3] + bsv);
;                     u32x2 w; w.x = pk2(o0, o1); w.y = pk2(o2, o3); *(u32x2*)(yo + ht * 32 + 8 * q4) = w; }
	v_mov_b32_e32 v48, v204
	v_mov_b32_e32 v49, v205
	v_lshlrev_b32_e32 v50, 16, v48
	v_mul_f32_e32 v52, 0x3d372713, v50
	v_mul_f32_e32 v52, v52, v50
	v_mov_b32_e32 v53, v50
	v_fmac_f32_e32 v53, v52, v53
	v_and_b32_e32 v48, 0xffff0000, v48
	v_mul_f32_e32 v52, 0x3f4c422a, v53
	v_mul_f32_e32 v53, 0x3d372713, v48
	v_mul_f32_e32 v53, v53, v48
	v_mov_b32_e32 v54, v48
	v_fmac_f32_e32 v54, v53, v54
	v_mul_f32_e32 v53, 0x3f4c422a, v54
	v_add_f32_e32 v53, v53, v53
	v_mul_f32_e32 v53, 0x3fb8aa3b, v53
	v_exp_f32_e32 v53, v53
	v_lshlrev_b32_e32 v51, 16, v49
	v_mov_b32_e32 v55, v51
	v_add_f32_e32 v52, v52, v52
	v_add_f32_e32 v53, 1.0, v53
	v_rcp_f32_e32 v54, v53
	v_mul_f32_e32 v53, 0x3d372713, v51
	v_mul_f32_e32 v53, v53, v51
	v_fmac_f32_e32 v55, v53, v55
	v_mul_f32_e32 v53, 0x3f4c422a, v55
	v_add_f32_e32 v53, v53, v53
	v_mul_f32_e32 v52, 0x3fb8aa3b, v52
	v_mul_f32_e32 v53, 0x3fb8aa3b, v53
	v_exp_f32_e32 v52, v52
	v_exp_f32_e32 v53, v53
	v_pk_mul_f32 v[50:51], v[50:51], 0.5 op_sel_hi:[1,0]
	v_and_b32_e32 v49, 0xffff0000, v49
	v_add_f32_e32 v52, 1.0, v52
	v_add_f32_e32 v53, 1.0, v53
	v_rcp_f32_e32 v52, v52
	v_rcp_f32_e32 v53, v53
	s_nop 0
	v_pk_fma_f32 v[52:53], v[52:53], 2.0, 1.0 op_sel_hi:[1,0,0] neg_lo:[1,0,0] neg_hi:[1,0,0]
	s_nop 0
	v_pk_add_f32 v[52:53], v[52:53], 1.0 op_sel_hi:[1,0]
	s_nop 0
	v_pk_mul_f32 v[50:51], v[50:51], v[52:53]
	v_mov_b32_e32 v52, v60
	v_mov_b32_e32 v53, v62
	v_pk_add_f32 v[52:53], v[52:53], v[64:65] op_sel_hi:[1,0]
	v_mov_b32_e32 v62, v61
	v_pk_mul_f32 v[50:51], v[52:53], v[50:51]
	v_mul_f32_e32 v52, 0x3d372713, v49
	v_mul_f32_e32 v52, v52, v49
	v_mov_b32_e32 v53, v49
	v_fmac_f32_e32 v53, v52, v53
	v_mul_f32_e32 v52, 0x3f4c422a, v53
	v_add_f32_e32 v52, v52, v52
	v_mul_f32_e32 v52, 0x3fb8aa3b, v52
	v_exp_f32_e32 v52, v52
	v_pk_mul_f32 v[48:49], v[48:49], 0.5 op_sel_hi:[1,0]
	v_add_f32_e32 v52, 1.0, v52
	v_rcp_f32_e32 v55, v52
	s_nop 0
	v_pk_fma_f32 v[52:53], v[54:55], 2.0, 1.0 op_sel_hi:[1,0,0] neg_lo:[1,0,0] neg_hi:[1,0,0]
	s_nop 0
	v_pk_add_f32 v[52:53], v[52:53], 1.0 op_sel_hi:[1,0]
	s_nop 0
	v_pk_mul_f32 v[48:49], v[48:49], v[52:53]
	v_pk_add_f32 v[52:53], v[62:63], v[64:65] op_sel_hi:[1,0]
	s_nop 0
	v_pk_mul_f32 v[48:49], v[52:53], v[48:49]
	v_and_b32_sdwa v52, v51, v196 dst_sel:DWORD dst_unused:UNUSED_PAD src0_sel:WORD_1 src1_sel:DWORD
	v_and_b32_sdwa v53, v50, v196 dst_sel:DWORD dst_unused:UNUSED_PAD src0_sel:WORD_1 src1_sel:DWORD
	v_add3_u32 v50, v50, v53, s45
	v_add3_u32 v51, v51, v52, s45
	v_and_b32_sdwa v52, v49, v196 dst_sel:DWORD dst_unused:UNUSED_PAD src0_sel:WORD_1 src1_sel:DWORD
	v_and_b32_sdwa v53, v48, v196 dst_sel:DWORD dst_unused:UNUSED_PAD src0_sel:WORD_1 src1_sel:DWORD
	v_add3_u32 v49, v49, v52, s45
	v_add3_u32 v48, v48, v53, s45
	v_and_b32_e32 v49, 0xffff0000, v49
	v_and_b32_e32 v48, 0xffff0000, v48
	v_or_b32_sdwa v49, v49, v51 dst_sel:DWORD dst_unused:UNUSED_PAD src0_sel:DWORD src1_sel:WORD_1
	v_or_b32_sdwa v48, v48, v50 dst_sel:DWORD dst_unused:UNUSED_PAD src0_sel:DWORD src1_sel:WORD_1
	global_store_dwordx2 v[66:67], v[48:49], off offset:48
	s_waitcnt vmcnt(15)
	v_mov_b32_e32 v48, v206
	v_mov_b32_e32 v49, v207
	v_lshlrev_b32_e32 v50, 16, v48
	v_mul_f32_e32 v52, 0x3d372713, v50
	v_mul_f32_e32 v52, v52, v50
	v_mov_b32_e32 v53, v50
	v_fmac_f32_e32 v53, v52, v53
	v_and_b32_e32 v48, 0xffff0000, v48
	v_mul_f32_e32 v52, 0x3f4c422a, v53
	v_mul_f32_e32 v53, 0x3d372713, v48
	v_mul_f32_e32 v53, v53, v48
	v_mov_b32_e32 v54, v48
	v_fmac_f32_e32 v54, v53, v54
	v_mul_f32_e32 v53, 0x3f4c422a, v54
	v_add_f32_e32 v53, v53, v53
	v_mul_f32_e32 v53, 0x3fb8aa3b, v53
	v_exp_f32_e32 v53, v53
	v_lshlrev_b32_e32 v51, 16, v49
	v_mov_b32_e32 v55, v51
	v_add_f32_e32 v52, v52, v52
	v_add_f32_e32 v53, 1.0, v53
	v_rcp_f32_e32 v54, v53
	v_mul_f32_e32 v53, 0x3d372713, v51
	v_mul_f32_e32 v53, v53, v51
	v_fmac_f32_e32 v55, v53, v55
	v_mul_f32_e32 v53, 0x3f4c422a, v55
	v_add_f32_e32 v53, v53, v53
	v_mul_f32_e32 v52, 0x3fb8aa3b, v52
	v_mul_f32_e32 v53, 0x3fb8aa3b, v53
	v_exp_f32_e32 v52, v52
	v_exp_f32_e32 v53, v53
	v_and_b32_e32 v49, 0xffff0000, v49
	v_pk_mul_f32 v[50:51], v[50:51], 0.5 op_sel_hi:[1,0]
	v_add_f32_e32 v52, 1.0, v52
	v_add_f32_e32 v53, 1.0, v53
	v_rcp_f32_e32 v52, v52
	v_rcp_f32_e32 v53, v53
	s_nop 0
	v_pk_fma_f32 v[52:53], v[52:53], 2.0, 1.0 op_sel_hi:[1,0,0] neg_lo:[1,0,0] neg_hi:[1,0,0]
	s_nop 0
	v_pk_add_f32 v[52:53], v[52:53], 1.0 op_sel_hi:[1,0]
	s_nop 0
	v_pk_mul_f32 v[50:51], v[50:51], v[52:53]
	v_mov_b32_e32 v52, v32
	v_mul_f32_e32 v32, 0x3d372713, v49
	v_mov_b32_e32 v53, v34
	v_mul_f32_e32 v32, v32, v49
	v_mov_b32_e32 v34, v49
	v_fmac_f32_e32 v34, v32, v34
	v_mul_f32_e32 v32, 0x3f4c422a, v34
	v_add_f32_e32 v32, v32, v32
	v_mul_f32_e32 v32, 0x3fb8aa3b, v32
	v_exp_f32_e32 v32, v32
	v_pk_add_f32 v[52:53], v[52:53], v[64:65] op_sel_hi:[1,0]
	v_pk_mul_f32 v[48:49], v[48:49], 0.5 op_sel_hi:[1,0]
	v_pk_mul_f32 v[50:51], v[52:53], v[50:51]
	v_add_f32_e32 v32, 1.0, v32
	v_rcp_f32_e32 v55, v32
	v_mov_b32_e32 v34, v33
	v_pk_add_f32 v[32:33], v[34:35], v[64:65] op_sel_hi:[1,0]
	v_and_b32_sdwa v34, v51, v196 dst_sel:DWORD dst_unused:UNUSED_PAD src0_sel:WORD_1 src1_sel:DWORD
	v_pk_fma_f32 v[52:53], v[54:55], 2.0, 1.0 op_sel_hi:[1,0,0] neg_lo:[1,0,0] neg_hi:[1,0,0]
	v_and_b32_sdwa v35, v50, v196 dst_sel:DWORD dst_unused:UNUSED_PAD src0_sel:WORD_1 src1_sel:DWORD
	v_pk_add_f32 v[52:53], v[52:53], 1.0 op_sel_hi:[1,0]
	v_add3_u32 v35, v50, v35, s45
	v_pk_mul_f32 v[48:49], v[48:49], v[52:53]
	v_add3_u32 v34, v51, v34, s45
	v_pk_mul_f32 v[32:33], v[32:33], v[48:49]
	s_nop 0
	v_and_b32_sdwa v48, v33, v196 dst_sel:DWORD dst_unused:UNUSED_PAD src0_sel:WORD_1 src1_sel:DWORD
	v_and_b32_sdwa v49, v32, v196 dst_sel:DWORD dst_unused:UNUSED_PAD src0_sel:WORD_1 src1_sel:DWORD
	v_add3_u32 v33, v33, v48, s45
	v_add3_u32 v32, v32, v49, s45
	v_and_b32_e32 v33, 0xffff0000, v33
	v_and_b32_e32 v32, 0xffff0000, v32
	v_or_b32_sdwa v33, v33, v34 dst_sel:DWORD dst_unused:UNUSED_PAD src0_sel:DWORD src1_sel:WORD_1
	v_or_b32_sdwa v32, v32, v35 dst_sel:DWORD dst_unused:UNUSED_PAD src0_sel:DWORD src1_sel:WORD_1
	global_store_dwordx2 v[66:67], v[32:33], off offset:64
	s_waitcnt vmcnt(15)
; __device__ __forceinline__ unsigned pk2(float lo, float hi) { return f2bf(lo) | (f2bf(hi) << 16); }
; __device__ __forceinline__ void gmlp_fast(KArgs ap, int l, LAS unsigned char* lds, const Ctx cx) {
;     ...
;                 for (int q4 = 0; q4 < 4; ++q4) { const u32x2 uu = *(const u32x2*)(zu + ht * 32 + 8 * q4);
;                     const float o0 = gelu_tanh(bflo(uu.x)) * (acc[ht][4 * q4] + bsv), o1 = gelu_tanh(bfhi(uu.x)) * (acc[ht][4 * q4 + 1] + bsv);
;                     const float o2 = gelu_tanh(bflo(uu.y)) * (acc[ht][4 * q4 + 2] + bsv), o3 = gelu_tanh(bfhi(uu.y)) * (acc[ht][4 * q4 + 3] + bsv);
;                     u32x2 w; w.x = pk2(o0, o1); w.y = pk2(o2, o3); *(u32x2*)(yo + ht * 32 + 8 * q4) = w; }
	v_mov_b32_e32 v32, v208
	v_mov_b32_e32 v33, v209
	v_lshlrev_b32_e32 v34, 16, v32
	v_mul_f32_e32 v48, 0x3d372713, v34
	v_mul_f32_e32 v48, v48, v34
	v_mov_b32_e32 v49, v34
	v_fmac_f32_e32 v49, v48, v49
	v_and_b32_e32 v32, 0xffff0000, v32
	v_mul_f32_e32 v48, 0x3f4c422a, v49
	v_mul_f32_e32 v49, 0x3d372713, v32
	v_mul_f32_e32 v49, v49, v32
	v_mov_b32_e32 v50, v32
	v_fmac_f32_e32 v50, v49, v50
	v_mul_f32_e32 v49, 0x3f4c422a, v50
	v_add_f32_e32 v49, v49, v49
	v_mul_f32_e32 v49, 0x3fb8aa3b, v49
	v_exp_f32_e32 v49, v49
	v_lshlrev_b32_e32 v35, 16, v33
	v_mov_b32_e32 v51, v35
	v_add_f32_e32 v48, v48, v48
	v_add_f32_e32 v49, 1.0, v49
	v_rcp_f32_e32 v50, v49
	v_mul_f32_e32 v49, 0x3d372713, v35
	v_mul_f32_e32 v49, v49, v35
	v_fmac_f32_e32 v51, v49, v51
	v_mul_f32_e32 v49, 0x3f4c422a, v51
	v_add_f32_e32 v49, v49, v49
	v_mul_f32_e32 v48, 0x3fb8aa3b, v48
	v_mul_f32_e32 v49, 0x3fb8aa3b, v49
	v_exp_f32_e32 v48, v48
	v_exp_f32_e32 v49, v49
	v_and_b32_e32 v33, 0xffff0000, v33
	v_pk_mul_f32 v[34:35], v[34:35], 0.5 op_sel_hi:[1,0]
	v_add_f32_e32 v48, 1.0, v48
	v_add_f32_e32 v49, 1.0, v49
	v_rcp_f32_e32 v48, v48
	v_rcp_f32_e32 v49, v49
	s_nop 0
	v_pk_fma_f32 v[48:49], v[48:49], 2.0, 1.0 op_sel_hi:[1,0,0] neg_lo:[1,0,0] neg_hi:[1,0,0]
	s_nop 0
	v_pk_add_f32 v[48:49], v[48:49], 1.0 op_sel_hi:[1,0]
	s_nop 0
	v_pk_mul_f32 v[34:35], v[34:35], v[48:49]
	v_mov_b32_e32 v48, v36
	v_mul_f32_e32 v36, 0x3d372713, v33
	v_mov_b32_e32 v49, v38
	v_mul_f32_e32 v36, v36, v33
	v_mov_b32_e32 v38, v33
	v_fmac_f32_e32 v38, v36, v38
	v_mul_f32_e32 v36, 0x3f4c422a, v38
	v_add_f32_e32 v36, v36, v36
	v_mul_f32_e32 v36, 0x3fb8aa3b, v36
	v_exp_f32_e32 v36, v36
	v_pk_add_f32 v[48:49], v[48:49], v[64:65] op_sel_hi:[1,0]
	v_pk_mul_f32 v[32:33], v[32:33], 0.5 op_sel_hi:[1,0]
	v_pk_mul_f32 v[34:35], v[48:49], v[34:35]
	v_add_f32_e32 v36, 1.0, v36
	v_rcp_f32_e32 v51, v36
	v_mov_b32_e32 v38, v37
	v_pk_add_f32 v[36:37], v[38:39], v[64:65] op_sel_hi:[1,0]
	v_pk_fma_f32 v[48:49], v[50:51], 2.0, 1.0 op_sel_hi:[1,0,0] neg_lo:[1,0,0] neg_hi:[1,0,0]
	s_nop 0
	v_pk_add_f32 v[48:49], v[48:49], 1.0 op_sel_hi:[1,0]
	s_nop 0
	v_pk_mul_f32 v[32:33], v[32:33], v[48:49]
	s_nop 0
	v_pk_mul_f32 v[32:33], v[36:37], v[32:33]
	v_and_b32_sdwa v36, v35, v196 dst_sel:DWORD dst_unused:UNUSED_PAD src0_sel:WORD_1 src1_sel:DWORD
	v_and_b32_sdwa v37, v34, v196 dst_sel:DWORD dst_unused:UNUSED_PAD src0_sel:WORD_1 src1_sel:DWORD
	v_add3_u32 v34, v34, v37, s45
	v_add3_u32 v35, v35, v36, s45
	v_and_b32_sdwa v36, v33, v196 dst_sel:DWORD dst_unused:UNUSED_PAD src0_sel:WORD_1 src1_sel:DWORD
	v_and_b32_sdwa v37, v32, v196 dst_sel:DWORD dst_unused:UNUSED_PAD src0_sel:WORD_1 src1_sel:DWORD
	v_add3_u32 v33, v33, v36, s45
	v_add3_u32 v32, v32, v37, s45
	v_and_b32_e32 v33, 0xffff0000, v33
	v_and_b32_e32 v32, 0xffff0000, v32
	v_or_b32_sdwa v33, v33, v35 dst_sel:DWORD dst_unused:UNUSED_PAD src0_sel:DWORD src1_sel:WORD_1
	v_or_b32_sdwa v32, v32, v34 dst_sel:DWORD dst_unused:UNUSED_PAD src0_sel:DWORD src1_sel:WORD_1
	global_store_dwordx2 v[66:67], v[32:33], off offset:80
	s_waitcnt vmcnt(15)
	v_mov_b32_e32 v32, v210
	v_mov_b32_e32 v33, v211
	v_lshlrev_b32_e32 v34, 16, v32
	v_mul_f32_e32 v36, 0x3d372713, v34
	v_mul_f32_e32 v36, v36, v34
	v_mov_b32_e32 v37, v34
	v_fmac_f32_e32 v37, v36, v37
	v_and_b32_e32 v32, 0xffff0000, v32
	v_mul_f32_e32 v36, 0x3f4c422a, v37
	v_mul_f32_e32 v37, 0x3d372713, v32
	v_mul_f32_e32 v37, v37, v32
	v_mov_b32_e32 v38, v32
	v_fmac_f32_e32 v38, v37, v38
	v_mul_f32_e32 v37, 0x3f4c422a, v38
	v_add_f32_e32 v37, v37, v37
	v_mul_f32_e32 v37, 0x3fb8aa3b, v37
	v_exp_f32_e32 v37, v37
	v_lshlrev_b32_e32 v35, 16, v33
	v_mov_b32_e32 v39, v35
	v_add_f32_e32 v36, v36, v36
	v_add_f32_e32 v37, 1.0, v37
	v_rcp_f32_e32 v38, v37
	v_mul_f32_e32 v37, 0x3d372713, v35
	v_mul_f32_e32 v37, v37, v35
	v_fmac_f32_e32 v39, v37, v39
	v_mul_f32_e32 v37, 0x3f4c422a, v39
	v_add_f32_e32 v37, v37, v37
	v_mul_f32_e32 v36, 0x3fb8aa3b, v36
	v_mul_f32_e32 v37, 0x3fb8aa3b, v37
	v_exp_f32_e32 v36, v36
	v_exp_f32_e32 v37, v37
	v_pk_mul_f32 v[34:35], v[34:35], 0.5 op_sel_hi:[1,0]
	v_and_b32_e32 v33, 0xffff0000, v33
	v_add_f32_e32 v36, 1.0, v36
	v_add_f32_e32 v37, 1.0, v37
	v_rcp_f32_e32 v36, v36
	v_rcp_f32_e32 v37, v37
	s_nop 0
	v_pk_fma_f32 v[36:37], v[36:37], 2.0, 1.0 op_sel_hi:[1,0,0] neg_lo:[1,0,0] neg_hi:[1,0,0]
	s_nop 0
	v_pk_add_f32 v[36:37], v[36:37], 1.0 op_sel_hi:[1,0]
	s_nop 0
	v_pk_mul_f32 v[34:35], v[34:35], v[36:37]
	v_mov_b32_e32 v36, v40
	v_mov_b32_e32 v37, v42
	v_pk_add_f32 v[36:37], v[36:37], v[64:65] op_sel_hi:[1,0]
	v_mov_b32_e32 v42, v41
	v_pk_mul_f32 v[34:35], v[36:37], v[34:35]
	v_mul_f32_e32 v36, 0x3d372713, v33
	v_mul_f32_e32 v36, v36, v33
	v_mov_b32_e32 v37, v33
	v_fmac_f32_e32 v37, v36, v37
	v_mul_f32_e32 v36, 0x3f4c422a, v37
	v_add_f32_e32 v36, v36, v36
	v_mul_f32_e32 v36, 0x3fb8aa3b, v36
	v_exp_f32_e32 v36, v36
	v_pk_mul_f32 v[32:33], v[32:33], 0.5 op_sel_hi:[1,0]
	v_add_f32_e32 v36, 1.0, v36
	v_rcp_f32_e32 v39, v36
	s_nop 0
	v_pk_fma_f32 v[36:37], v[38:39], 2.0, 1.0 op_sel_hi:[1,0,0] neg_lo:[1,0,0] neg_hi:[1,0,0]
	s_nop 0
	v_pk_add_f32 v[36:37], v[36:37], 1.0 op_sel_hi:[1,0]
	s_nop 0
	v_pk_mul_f32 v[32:33], v[32:33], v[36:37]
	v_pk_add_f32 v[36:37], v[42:43], v[64:65] op_sel_hi:[1,0]
	s_nop 0
	v_pk_mul_f32 v[32:33], v[36:37], v[32:33]
	v_and_b32_sdwa v36, v35, v196 dst_sel:DWORD dst_unused:UNUSED_PAD src0_sel:WORD_1 src1_sel:DWORD
	v_and_b32_sdwa v37, v34, v196 dst_sel:DWORD dst_unused:UNUSED_PAD src0_sel:WORD_1 src1_sel:DWORD
	v_add3_u32 v34, v34, v37, s45
	v_add3_u32 v35, v35, v36, s45
	v_and_b32_sdwa v36, v33, v196 dst_sel:DWORD dst_unused:UNUSED_PAD src0_sel:WORD_1 src1_sel:DWORD
	v_and_b32_sdwa v37, v32, v196 dst_sel:DWORD dst_unused:UNUSED_PAD src0_sel:WORD_1 src1_sel:DWORD
	v_add3_u32 v33, v33, v36, s45
	v_add3_u32 v32, v32, v37, s45
	v_and_b32_e32 v33, 0xffff0000, v33
	v_and_b32_e32 v32, 0xffff0000, v32
	v_or_b32_sdwa v33, v33, v35 dst_sel:DWORD dst_unused:UNUSED_PAD src0_sel:DWORD src1_sel:WORD_1
	v_or_b32_sdwa v32, v32, v34 dst_sel:DWORD dst_unused:UNUSED_PAD src0_sel:DWORD src1_sel:WORD_1
	global_store_dwordx2 v[66:67], v[32:33], off offset:96
	s_waitcnt vmcnt(15)
; __device__ __forceinline__ unsigned pk2(float lo, float hi) { return f2bf(lo) | (f2bf(hi) << 16); }
; __device__ __forceinline__ void gmlp_fast(KArgs ap, int l, LAS unsigned char* lds, const Ctx cx) {
;     ...
;             const size_t t = t0 + tl; const float bsv = bsp[g * 128 + tl];
;             const bf16_t* zu = z + t * DIN + ZGU + g * 128 + 4 * hh; bf16_t* yo = y + t * DM + YG + g * 128 + 4 * hh;
; #pragma unroll
;             for (int ht = 0; ht < 4; ++ht)
; #pragma unroll
;                 for (int q4 = 0; q4 < 4; ++q4) { const u32x2 uu = *(const u32x2*)(zu + ht * 32 + 8 * q4);
;                     const float o0 = gelu_tanh(bflo(uu.x)) * (acc[ht][4 * q4] + bsv), o1 = gelu_tanh(bfhi(uu.x)) * (acc[ht][4 * q4 + 1] + bsv);
;                     const float o2 = gelu_tanh(bflo(uu.y)) * (acc[ht][4 * q4 + 2] + bsv), o3 = gelu_tanh(bfhi(uu.y)) * (acc[ht][4 * q4 + 3] + bsv);
;                     u32x2 w; w.x = pk2(o0, o1); w.y = pk2(o2, o3); *(u32x2*)(yo + ht * 32 + 8 * q4) = w; }
	v_mov_b32_e32 v32, v212
	v_mov_b32_e32 v33, v213
	v_lshlrev_b32_e32 v34, 16, v32
	v_mul_f32_e32 v36, 0x3d372713, v34
	v_mul_f32_e32 v36, v36, v34
	v_mov_b32_e32 v37, v34
	v_fmac_f32_e32 v37, v36, v37
	v_and_b32_e32 v32, 0xffff0000, v32
	v_mul_f32_e32 v36, 0x3f4c422a, v37
	v_mul_f32_e32 v37, 0x3d372713, v32
	v_mul_f32_e32 v37, v37, v32
	v_mov_b32_e32 v38, v32
	v_fmac_f32_e32 v38, v37, v38
	v_mul_f32_e32 v37, 0x3f4c422a, v38
	v_add_f32_e32 v37, v37, v37
	v_mul_f32_e32 v37, 0x3fb8aa3b, v37
	v_exp_f32_e32 v37, v37
	v_lshlrev_b32_e32 v35, 16, v33
	v_mov_b32_e32 v39, v35
	v_add_f32_e32 v36, v36, v36
	v_add_f32_e32 v37, 1.0, v37
	v_rcp_f32_e32 v38, v37
	v_mul_f32_e32 v37, 0x3d372713, v35
	v_mul_f32_e32 v37, v37, v35
	v_fmac_f32_e32 v39, v37, v39
	v_mul_f32_e32 v37, 0x3f4c422a, v39
	v_add_f32_e32 v37, v37, v37
	v_mul_f32_e32 v36, 0x3fb8aa3b, v36
	v_mul_f32_e32 v37, 0x3fb8aa3b, v37
	v_exp_f32_e32 v36, v36
	v_exp_f32_e32 v37, v37
	v_pk_mul_f32 v[34:35], v[34:35], 0.5 op_sel_hi:[1,0]
	v_and_b32_e32 v33, 0xffff0000, v33
	v_add_f32_e32 v36, 1.0, v36
	v_add_f32_e32 v37, 1.0, v37
	v_rcp_f32_e32 v36, v36
	v_rcp_f32_e32 v37, v37
	s_nop 0
	v_pk_fma_f32 v[36:37], v[36:37], 2.0, 1.0 op_sel_hi:[1,0,0] neg_lo:[1,0,0] neg_hi:[1,0,0]
	s_nop 0
	v_pk_add_f32 v[36:37], v[36:37], 1.0 op_sel_hi:[1,0]
	s_nop 0
	v_pk_mul_f32 v[34:35], v[34:35], v[36:37]
	v_mov_b32_e32 v36, v44
	v_mov_b32_e32 v37, v46
	v_pk_add_f32 v[36:37], v[36:37], v[64:65] op_sel_hi:[1,0]
	v_mov_b32_e32 v46, v45
	v_pk_mul_f32 v[34:35], v[36:37], v[34:35]
	v_mul_f32_e32 v36, 0x3d372713, v33
	v_mul_f32_e32 v36, v36, v33
	v_mov_b32_e32 v37, v33
	v_fmac_f32_e32 v37, v36, v37
	v_mul_f32_e32 v36, 0x3f4c422a, v37
	v_add_f32_e32 v36, v36, v36
	v_mul_f32_e32 v36, 0x3fb8aa3b, v36
	v_exp_f32_e32 v36, v36
	v_pk_mul_f32 v[32:33], v[32:33], 0.5 op_sel_hi:[1,0]
	v_add_f32_e32 v36, 1.0, v36
	v_rcp_f32_e32 v39, v36
	s_nop 0
	v_pk_fma_f32 v[36:37], v[38:39], 2.0, 1.0 op_sel_hi:[1,0,0] neg_lo:[1,0,0] neg_hi:[1,0,0]
	s_nop 0
	v_pk_add_f32 v[36:37], v[36:37], 1.0 op_sel_hi:[1,0]
	s_nop 0
	v_pk_mul_f32 v[32:33], v[32:33], v[36:37]
	v_pk_add_f32 v[36:37], v[46:47], v[64:65] op_sel_hi:[1,0]
	s_nop 0
	v_pk_mul_f32 v[32:33], v[36:37], v[32:33]
	v_and_b32_sdwa v36, v35, v196 dst_sel:DWORD dst_unused:UNUSED_PAD src0_sel:WORD_1 src1_sel:DWORD
	v_and_b32_sdwa v37, v34, v196 dst_sel:DWORD dst_unused:UNUSED_PAD src0_sel:WORD_1 src1_sel:DWORD
	v_add3_u32 v34, v34, v37, s45
	v_add3_u32 v35, v35, v36, s45
	v_and_b32_sdwa v36, v33, v196 dst_sel:DWORD dst_unused:UNUSED_PAD src0_sel:WORD_1 src1_sel:DWORD
	v_and_b32_sdwa v37, v32, v196 dst_sel:DWORD dst_unused:UNUSED_PAD src0_sel:WORD_1 src1_sel:DWORD
	v_add3_u32 v33, v33, v36, s45
	v_add3_u32 v32, v32, v37, s45
	v_and_b32_e32 v33, 0xffff0000, v33
	v_and_b32_e32 v32, 0xffff0000, v32
	v_or_b32_sdwa v33, v33, v35 dst_sel:DWORD dst_unused:UNUSED_PAD src0_sel:DWORD src1_sel:WORD_1
	v_or_b32_sdwa v32, v32, v34 dst_sel:DWORD dst_unused:UNUSED_PAD src0_sel:DWORD src1_sel:WORD_1
	global_store_dwordx2 v[66:67], v[32:33], off offset:112
	s_waitcnt vmcnt(15)
	v_mov_b32_e32 v32, v214
	v_mov_b32_e32 v33, v215
	v_lshlrev_b32_e32 v34, 16, v32
	v_mul_f32_e32 v36, 0x3d372713, v34
	v_mul_f32_e32 v36, v36, v34
	v_mov_b32_e32 v37, v34
	v_fmac_f32_e32 v37, v36, v37
	v_and_b32_e32 v32, 0xffff0000, v32
	v_mul_f32_e32 v36, 0x3f4c422a, v37
	v_mul_f32_e32 v37, 0x3d372713, v32
	v_mul_f32_e32 v37, v37, v32
	v_mov_b32_e32 v38, v32
	v_fmac_f32_e32 v38, v37, v38
	v_mul_f32_e32 v37, 0x3f4c422a, v38
	v_add_f32_e32 v37, v37, v37
	v_mul_f32_e32 v37, 0x3fb8aa3b, v37
	v_exp_f32_e32 v37, v37
	v_lshlrev_b32_e32 v35, 16, v33
	v_mov_b32_e32 v39, v35
	v_add_f32_e32 v36, v36, v36
	v_add_f32_e32 v37, 1.0, v37
	v_rcp_f32_e32 v38, v37
	v_mul_f32_e32 v37, 0x3d372713, v35
	v_mul_f32_e32 v37, v37, v35
	v_fmac_f32_e32 v39, v37, v39
	v_mul_f32_e32 v37, 0x3f4c422a, v39
	v_add_f32_e32 v37, v37, v37
	v_mul_f32_e32 v36, 0x3fb8aa3b, v36
	v_mul_f32_e32 v37, 0x3fb8aa3b, v37
	v_exp_f32_e32 v36, v36
	v_exp_f32_e32 v37, v37
	v_and_b32_e32 v33, 0xffff0000, v33
	v_pk_mul_f32 v[34:35], v[34:35], 0.5 op_sel_hi:[1,0]
	v_add_f32_e32 v36, 1.0, v36
	v_add_f32_e32 v37, 1.0, v37
	v_rcp_f32_e32 v36, v36
	v_rcp_f32_e32 v37, v37
	s_nop 0
	v_pk_fma_f32 v[36:37], v[36:37], 2.0, 1.0 op_sel_hi:[1,0,0] neg_lo:[1,0,0] neg_hi:[1,0,0]
	s_nop 0
	v_pk_add_f32 v[36:37], v[36:37], 1.0 op_sel_hi:[1,0]
	s_nop 0
	v_pk_mul_f32 v[34:35], v[34:35], v[36:37]
	v_mov_b32_e32 v36, v16
	v_mul_f32_e32 v16, 0x3d372713, v33
	v_mov_b32_e32 v37, v18
	v_mul_f32_e32 v16, v16, v33
	v_mov_b32_e32 v18, v33
	v_fmac_f32_e32 v18, v16, v18
	v_mul_f32_e32 v16, 0x3f4c422a, v18
	v_add_f32_e32 v16, v16, v16
	v_mul_f32_e32 v16, 0x3fb8aa3b, v16
	v_exp_f32_e32 v16, v16
	v_pk_add_f32 v[36:37], v[36:37], v[64:65] op_sel_hi:[1,0]
	v_pk_mul_f32 v[32:33], v[32:33], 0.5 op_sel_hi:[1,0]
	v_pk_mul_f32 v[34:35], v[36:37], v[34:35]
	v_add_f32_e32 v16, 1.0, v16
	v_rcp_f32_e32 v39, v16
	v_mov_b32_e32 v18, v17
	v_pk_add_f32 v[16:17], v[18:19], v[64:65] op_sel_hi:[1,0]
	v_and_b32_sdwa v18, v35, v196 dst_sel:DWORD dst_unused:UNUSED_PAD src0_sel:WORD_1 src1_sel:DWORD
	v_pk_fma_f32 v[36:37], v[38:39], 2.0, 1.0 op_sel_hi:[1,0,0] neg_lo:[1,0,0] neg_hi:[1,0,0]
	v_and_b32_sdwa v19, v34, v196 dst_sel:DWORD dst_unused:UNUSED_PAD src0_sel:WORD_1 src1_sel:DWORD
	v_pk_add_f32 v[36:37], v[36:37], 1.0 op_sel_hi:[1,0]
	v_add3_u32 v19, v34, v19, s45
	v_pk_mul_f32 v[32:33], v[32:33], v[36:37]
	v_add3_u32 v18, v35, v18, s45
	v_pk_mul_f32 v[16:17], v[16:17], v[32:33]
	s_nop 0
	v_and_b32_sdwa v32, v17, v196 dst_sel:DWORD dst_unused:UNUSED_PAD src0_sel:WORD_1 src1_sel:DWORD
	v_and_b32_sdwa v33, v16, v196 dst_sel:DWORD dst_unused:UNUSED_PAD src0_sel:WORD_1 src1_sel:DWORD
	v_add3_u32 v17, v17, v32, s45
	v_add3_u32 v16, v16, v33, s45
	v_and_b32_e32 v17, 0xffff0000, v17
	v_and_b32_e32 v16, 0xffff0000, v16
	v_or_b32_sdwa v17, v17, v18 dst_sel:DWORD dst_unused:UNUSED_PAD src0_sel:DWORD src1_sel:WORD_1
	v_or_b32_sdwa v16, v16, v19 dst_sel:DWORD dst_unused:UNUSED_PAD src0_sel:DWORD src1_sel:WORD_1
	global_store_dwordx2 v[66:67], v[16:17], off offset:128
	s_waitcnt vmcnt(15)
; __device__ __forceinline__ unsigned pk2(float lo, float hi) { return f2bf(lo) | (f2bf(hi) << 16); }
; __device__ __forceinline__ void gmlp_fast(KArgs ap, int l, LAS unsigned char* lds, const Ctx cx) {
;     ...
;             for (int ht = 0; ht < 4; ++ht)
; #pragma unroll
;                 for (int q4 = 0; q4 < 4; ++q4) { const u32x2 uu = *(const u32x2*)(zu + ht * 32 + 8 * q4);
;                     const float o0 = gelu_tanh(bflo(uu.x)) * (acc[ht][4 * q4] + bsv), o1 = gelu_tanh(bfhi(uu.x)) * (acc[ht][4 * q4 + 1] + bsv);
;                     const float o2 = gelu_tanh(bflo(uu.y)) * (acc[ht][4 * q4 + 2] + bsv), o3 = gelu_tanh(bfhi(uu.y)) * (acc[ht][4 * q4 + 3] + bsv);
;                     u32x2 w; w.x = pk2(o0, o1); w.y = pk2(o2, o3); *(u32x2*)(yo + ht * 32 + 8 * q4) = w; }
	v_mov_b32_e32 v16, v216
	v_mov_b32_e32 v17, v217
	v_lshlrev_b32_e32 v18, 16, v16
	v_mul_f32_e32 v32, 0x3d372713, v18
	v_mul_f32_e32 v32, v32, v18
	v_mov_b32_e32 v33, v18
	v_fmac_f32_e32 v33, v32, v33
	v_and_b32_e32 v16, 0xffff0000, v16
	v_mul_f32_e32 v32, 0x3f4c422a, v33
	v_mul_f32_e32 v33, 0x3d372713, v16
	v_mul_f32_e32 v33, v33, v16
	v_mov_b32_e32 v34, v16
	v_fmac_f32_e32 v34, v33, v34
	v_mul_f32_e32 v33, 0x3f4c422a, v34
	v_add_f32_e32 v33, v33, v33
	v_mul_f32_e32 v33, 0x3fb8aa3b, v33
	v_exp_f32_e32 v33, v33
	v_lshlrev_b32_e32 v19, 16, v17
	v_mov_b32_e32 v35, v19
	v_add_f32_e32 v32, v32, v32
	v_add_f32_e32 v33, 1.0, v33
	v_rcp_f32_e32 v34, v33
	v_mul_f32_e32 v33, 0x3d372713, v19
	v_mul_f32_e32 v33, v33, v19
	v_fmac_f32_e32 v35, v33, v35
	v_mul_f32_e32 v33, 0x3f4c422a, v35
	v_add_f32_e32 v33, v33, v33
	v_mul_f32_e32 v32, 0x3fb8aa3b, v32
	v_mul_f32_e32 v33, 0x3fb8aa3b, v33
	v_exp_f32_e32 v32, v32
	v_exp_f32_e32 v33, v33
	v_and_b32_e32 v17, 0xffff0000, v17
	v_pk_mul_f32 v[18:19], v[18:19], 0.5 op_sel_hi:[1,0]
	v_add_f32_e32 v32, 1.0, v32
	v_add_f32_e32 v33, 1.0, v33
	v_rcp_f32_e32 v32, v32
	v_rcp_f32_e32 v33, v33
	s_nop 0
	v_pk_fma_f32 v[32:33], v[32:33], 2.0, 1.0 op_sel_hi:[1,0,0] neg_lo:[1,0,0] neg_hi:[1,0,0]
	s_nop 0
	v_pk_add_f32 v[32:33], v[32:33], 1.0 op_sel_hi:[1,0]
	s_nop 0
	v_pk_mul_f32 v[18:19], v[18:19], v[32:33]
	v_mov_b32_e32 v32, v20
	v_mul_f32_e32 v20, 0x3d372713, v17
	v_mov_b32_e32 v33, v22
	v_mul_f32_e32 v20, v20, v17
	v_mov_b32_e32 v22, v17
	v_fmac_f32_e32 v22, v20, v22
	v_mul_f32_e32 v20, 0x3f4c422a, v22
	v_add_f32_e32 v20, v20, v20
	v_mul_f32_e32 v20, 0x3fb8aa3b, v20
	v_exp_f32_e32 v20, v20
	v_pk_add_f32 v[32:33], v[32:33], v[64:65] op_sel_hi:[1,0]
	v_pk_mul_f32 v[16:17], v[16:17], 0.5 op_sel_hi:[1,0]
	v_pk_mul_f32 v[18:19], v[32:33], v[18:19]
	v_add_f32_e32 v20, 1.0, v20
	v_rcp_f32_e32 v35, v20
	v_mov_b32_e32 v22, v21
	v_pk_add_f32 v[20:21], v[22:23], v[64:65] op_sel_hi:[1,0]
	v_pk_fma_f32 v[32:33], v[34:35], 2.0, 1.0 op_sel_hi:[1,0,0] neg_lo:[1,0,0] neg_hi:[1,0,0]
	s_nop 0
	v_pk_add_f32 v[32:33], v[32:33], 1.0 op_sel_hi:[1,0]
	s_nop 0
	v_pk_mul_f32 v[16:17], v[16:17], v[32:33]
	s_nop 0
	v_pk_mul_f32 v[16:17], v[20:21], v[16:17]
	v_and_b32_sdwa v20, v19, v196 dst_sel:DWORD dst_unused:UNUSED_PAD src0_sel:WORD_1 src1_sel:DWORD
	v_and_b32_sdwa v21, v18, v196 dst_sel:DWORD dst_unused:UNUSED_PAD src0_sel:WORD_1 src1_sel:DWORD
	v_add3_u32 v18, v18, v21, s45
	v_add3_u32 v19, v19, v20, s45
	v_and_b32_sdwa v20, v17, v196 dst_sel:DWORD dst_unused:UNUSED_PAD src0_sel:WORD_1 src1_sel:DWORD
	v_and_b32_sdwa v21, v16, v196 dst_sel:DWORD dst_unused:UNUSED_PAD src0_sel:WORD_1 src1_sel:DWORD
	v_add3_u32 v17, v17, v20, s45
	v_add3_u32 v16, v16, v21, s45
	v_and_b32_e32 v17, 0xffff0000, v17
	v_and_b32_e32 v16, 0xffff0000, v16
	v_or_b32_sdwa v17, v17, v19 dst_sel:DWORD dst_unused:UNUSED_PAD src0_sel:DWORD src1_sel:WORD_1
	v_or_b32_sdwa v16, v16, v18 dst_sel:DWORD dst_unused:UNUSED_PAD src0_sel:DWORD src1_sel:WORD_1
	global_store_dwordx2 v[66:67], v[16:17], off offset:144
	s_waitcnt vmcnt(15)
	v_mov_b32_e32 v16, v218
	v_mov_b32_e32 v17, v219
	v_lshlrev_b32_e32 v18, 16, v16
	v_mul_f32_e32 v20, 0x3d372713, v18
	v_mul_f32_e32 v20, v20, v18
	v_mov_b32_e32 v21, v18
	v_fmac_f32_e32 v21, v20, v21
	v_and_b32_e32 v16, 0xffff0000, v16
	v_mul_f32_e32 v20, 0x3f4c422a, v21
	v_mul_f32_e32 v21, 0x3d372713, v16
	v_mul_f32_e32 v21, v21, v16
	v_mov_b32_e32 v22, v16
	v_fmac_f32_e32 v22, v21, v22
	v_mul_f32_e32 v21, 0x3f4c422a, v22
	v_add_f32_e32 v21, v21, v21
	v_mul_f32_e32 v21, 0x3fb8aa3b, v21
	v_exp_f32_e32 v21, v21
	v_lshlrev_b32_e32 v19, 16, v17
	v_mov_b32_e32 v23, v19
	v_add_f32_e32 v20, v20, v20
	v_add_f32_e32 v21, 1.0, v21
	v_rcp_f32_e32 v22, v21
	v_mul_f32_e32 v21, 0x3d372713, v19
	v_mul_f32_e32 v21, v21, v19
	v_fmac_f32_e32 v23, v21, v23
	v_mul_f32_e32 v21, 0x3f4c422a, v23
	v_add_f32_e32 v21, v21, v21
	v_mul_f32_e32 v20, 0x3fb8aa3b, v20
	v_mul_f32_e32 v21, 0x3fb8aa3b, v21
	v_exp_f32_e32 v20, v20
	v_exp_f32_e32 v21, v21
	v_pk_mul_f32 v[18:19], v[18:19], 0.5 op_sel_hi:[1,0]
	v_and_b32_e32 v17, 0xffff0000, v17
	v_add_f32_e32 v20, 1.0, v20
	v_add_f32_e32 v21, 1.0, v21
	v_rcp_f32_e32 v20, v20
	v_rcp_f32_e32 v21, v21
	s_nop 0
	v_pk_fma_f32 v[20:21], v[20:21], 2.0, 1.0 op_sel_hi:[1,0,0] neg_lo:[1,0,0] neg_hi:[1,0,0]
	s_nop 0
	v_pk_add_f32 v[20:21], v[20:21], 1.0 op_sel_hi:[1,0]
	s_nop 0
	v_pk_mul_f32 v[18:19], v[18:19], v[20:21]
	v_mov_b32_e32 v20, v24
	v_mov_b32_e32 v21, v26
	v_pk_add_f32 v[20:21], v[20:21], v[64:65] op_sel_hi:[1,0]
	v_mov_b32_e32 v26, v25
	v_pk_mul_f32 v[18:19], v[20:21], v[18:19]
	v_mul_f32_e32 v20, 0x3d372713, v17
	v_mul_f32_e32 v20, v20, v17
	v_mov_b32_e32 v21, v17
	v_fmac_f32_e32 v21, v20, v21
	v_mul_f32_e32 v20, 0x3f4c422a, v21
	v_add_f32_e32 v20, v20, v20
	v_mul_f32_e32 v20, 0x3fb8aa3b, v20
	v_exp_f32_e32 v20, v20
	v_pk_mul_f32 v[16:17], v[16:17], 0.5 op_sel_hi:[1,0]
	v_add_f32_e32 v20, 1.0, v20
	v_rcp_f32_e32 v23, v20
	s_nop 0
	v_pk_fma_f32 v[20:21], v[22:23], 2.0, 1.0 op_sel_hi:[1,0,0] neg_lo:[1,0,0] neg_hi:[1,0,0]
	s_nop 0
	v_pk_add_f32 v[20:21], v[20:21], 1.0 op_sel_hi:[1,0]
	s_nop 0
	v_pk_mul_f32 v[16:17], v[16:17], v[20:21]
	v_pk_add_f32 v[20:21], v[26:27], v[64:65] op_sel_hi:[1,0]
	s_nop 0
	v_pk_mul_f32 v[16:17], v[20:21], v[16:17]
	v_and_b32_sdwa v20, v19, v196 dst_sel:DWORD dst_unused:UNUSED_PAD src0_sel:WORD_1 src1_sel:DWORD
	v_and_b32_sdwa v21, v18, v196 dst_sel:DWORD dst_unused:UNUSED_PAD src0_sel:WORD_1 src1_sel:DWORD
	v_add3_u32 v18, v18, v21, s45
	v_add3_u32 v19, v19, v20, s45
	v_and_b32_sdwa v20, v17, v196 dst_sel:DWORD dst_unused:UNUSED_PAD src0_sel:WORD_1 src1_sel:DWORD
	v_and_b32_sdwa v21, v16, v196 dst_sel:DWORD dst_unused:UNUSED_PAD src0_sel:WORD_1 src1_sel:DWORD
	v_add3_u32 v17, v17, v20, s45
	v_add3_u32 v16, v16, v21, s45
	v_and_b32_e32 v17, 0xffff0000, v17
	v_and_b32_e32 v16, 0xffff0000, v16
	v_or_b32_sdwa v17, v17, v19 dst_sel:DWORD dst_unused:UNUSED_PAD src0_sel:DWORD src1_sel:WORD_1
	v_or_b32_sdwa v16, v16, v18 dst_sel:DWORD dst_unused:UNUSED_PAD src0_sel:DWORD src1_sel:WORD_1
	global_store_dwordx2 v[66:67], v[16:17], off offset:160
	s_waitcnt vmcnt(15)
; __device__ __forceinline__ unsigned pk2(float lo, float hi) { return f2bf(lo) | (f2bf(hi) << 16); }
; __device__ __forceinline__ void gmlp_fast(KArgs ap, int l, LAS unsigned char* lds, const Ctx cx) {
;     ...
;             for (int ht = 0; ht < 4; ++ht)
; #pragma unroll
;                 for (int q4 = 0; q4 < 4; ++q4) { const u32x2 uu = *(const u32x2*)(zu + ht * 32 + 8 * q4);
;                     const float o0 = gelu_tanh(bflo(uu.x)) * (acc[ht][4 * q4] + bsv), o1 = gelu_tanh(bfhi(uu.x)) * (acc[ht][4 * q4 + 1] + bsv);
;                     const float o2 = gelu_tanh(bflo(uu.y)) * (acc[ht][4 * q4 + 2] + bsv), o3 = gelu_tanh(bfhi(uu.y)) * (acc[ht][4 * q4 + 3] + bsv);
;                     u32x2 w; w.x = pk2(o0, o1); w.y = pk2(o2, o3); *(u32x2*)(yo + ht * 32 + 8 * q4) = w; }
	v_mov_b32_e32 v16, v220
	v_mov_b32_e32 v17, v221
	v_lshlrev_b32_e32 v18, 16, v16
	v_mul_f32_e32 v20, 0x3d372713, v18
	v_mul_f32_e32 v20, v20, v18
	v_mov_b32_e32 v21, v18
	v_fmac_f32_e32 v21, v20, v21
	v_and_b32_e32 v16, 0xffff0000, v16
	v_mul_f32_e32 v20, 0x3f4c422a, v21
	v_mul_f32_e32 v21, 0x3d372713, v16
	v_mul_f32_e32 v21, v21, v16
	v_mov_b32_e32 v22, v16
	v_fmac_f32_e32 v22, v21, v22
	v_mul_f32_e32 v21, 0x3f4c422a, v22
	v_add_f32_e32 v21, v21, v21
	v_mul_f32_e32 v21, 0x3fb8aa3b, v21
	v_exp_f32_e32 v21, v21
	v_lshlrev_b32_e32 v19, 16, v17
	v_mov_b32_e32 v23, v19
	v_add_f32_e32 v20, v20, v20
	v_add_f32_e32 v21, 1.0, v21
	v_rcp_f32_e32 v22, v21
	v_mul_f32_e32 v21, 0x3d372713, v19
	v_mul_f32_e32 v21, v21, v19
	v_fmac_f32_e32 v23, v21, v23
	v_mul_f32_e32 v21, 0x3f4c422a, v23
	v_add_f32_e32 v21, v21, v21
	v_mul_f32_e32 v20, 0x3fb8aa3b, v20
	v_mul_f32_e32 v21, 0x3fb8aa3b, v21
	v_exp_f32_e32 v20, v20
	v_exp_f32_e32 v21, v21
	v_pk_mul_f32 v[18:19], v[18:19], 0.5 op_sel_hi:[1,0]
	v_and_b32_e32 v17, 0xffff0000, v17
	v_add_f32_e32 v20, 1.0, v20
	v_add_f32_e32 v21, 1.0, v21
	v_rcp_f32_e32 v20, v20
	v_rcp_f32_e32 v21, v21
	s_nop 0
	v_pk_fma_f32 v[20:21], v[20:21], 2.0, 1.0 op_sel_hi:[1,0,0] neg_lo:[1,0,0] neg_hi:[1,0,0]
	s_nop 0
	v_pk_add_f32 v[20:21], v[20:21], 1.0 op_sel_hi:[1,0]
	s_nop 0
	v_pk_mul_f32 v[18:19], v[18:19], v[20:21]
	v_mov_b32_e32 v20, v28
	v_mov_b32_e32 v21, v30
	v_pk_add_f32 v[20:21], v[20:21], v[64:65] op_sel_hi:[1,0]
	v_mov_b32_e32 v30, v29
	v_pk_mul_f32 v[18:19], v[20:21], v[18:19]
	v_mul_f32_e32 v20, 0x3d372713, v17
	v_mul_f32_e32 v20, v20, v17
	v_mov_b32_e32 v21, v17
	v_fmac_f32_e32 v21, v20, v21
	v_mul_f32_e32 v20, 0x3f4c422a, v21
	v_add_f32_e32 v20, v20, v20
	v_mul_f32_e32 v20, 0x3fb8aa3b, v20
	v_exp_f32_e32 v20, v20
	v_pk_mul_f32 v[16:17], v[16:17], 0.5 op_sel_hi:[1,0]
	v_add_f32_e32 v20, 1.0, v20
	v_rcp_f32_e32 v23, v20
	s_nop 0
	v_pk_fma_f32 v[20:21], v[22:23], 2.0, 1.0 op_sel_hi:[1,0,0] neg_lo:[1,0,0] neg_hi:[1,0,0]
	s_nop 0
	v_pk_add_f32 v[20:21], v[20:21], 1.0 op_sel_hi:[1,0]
	s_nop 0
	v_pk_mul_f32 v[16:17], v[16:17], v[20:21]
	v_pk_add_f32 v[20:21], v[30:31], v[64:65] op_sel_hi:[1,0]
	s_nop 0
	v_pk_mul_f32 v[16:17], v[20:21], v[16:17]
	v_and_b32_sdwa v20, v19, v196 dst_sel:DWORD dst_unused:UNUSED_PAD src0_sel:WORD_1 src1_sel:DWORD
	v_and_b32_sdwa v21, v18, v196 dst_sel:DWORD dst_unused:UNUSED_PAD src0_sel:WORD_1 src1_sel:DWORD
	v_add3_u32 v18, v18, v21, s45
	v_add3_u32 v19, v19, v20, s45
	v_and_b32_sdwa v20, v17, v196 dst_sel:DWORD dst_unused:UNUSED_PAD src0_sel:WORD_1 src1_sel:DWORD
	v_and_b32_sdwa v21, v16, v196 dst_sel:DWORD dst_unused:UNUSED_PAD src0_sel:WORD_1 src1_sel:DWORD
	v_add3_u32 v17, v17, v20, s45
	v_add3_u32 v16, v16, v21, s45
	v_and_b32_e32 v17, 0xffff0000, v17
	v_and_b32_e32 v16, 0xffff0000, v16
	v_or_b32_sdwa v17, v17, v19 dst_sel:DWORD dst_unused:UNUSED_PAD src0_sel:DWORD src1_sel:WORD_1
	v_or_b32_sdwa v16, v16, v18 dst_sel:DWORD dst_unused:UNUSED_PAD src0_sel:DWORD src1_sel:WORD_1
	global_store_dwordx2 v[66:67], v[16:17], off offset:176
	s_waitcnt vmcnt(15)
	v_mov_b32_e32 v16, v222
	v_mov_b32_e32 v17, v223
	v_lshlrev_b32_e32 v18, 16, v16
	v_mul_f32_e32 v20, 0x3d372713, v18
	v_mul_f32_e32 v20, v20, v18
	v_mov_b32_e32 v21, v18
	v_fmac_f32_e32 v21, v20, v21
	v_and_b32_e32 v16, 0xffff0000, v16
	v_mul_f32_e32 v20, 0x3f4c422a, v21
	v_mul_f32_e32 v21, 0x3d372713, v16
	v_mul_f32_e32 v21, v21, v16
	v_mov_b32_e32 v22, v16
	v_fmac_f32_e32 v22, v21, v22
	v_mul_f32_e32 v21, 0x3f4c422a, v22
	v_add_f32_e32 v21, v21, v21
	v_mul_f32_e32 v21, 0x3fb8aa3b, v21
	v_exp_f32_e32 v21, v21
	v_lshlrev_b32_e32 v19, 16, v17
	v_mov_b32_e32 v23, v19
	v_add_f32_e32 v20, v20, v20
	v_add_f32_e32 v21, 1.0, v21
	v_rcp_f32_e32 v22, v21
	v_mul_f32_e32 v21, 0x3d372713, v19
	v_mul_f32_e32 v21, v21, v19
	v_fmac_f32_e32 v23, v21, v23
	v_mul_f32_e32 v21, 0x3f4c422a, v23
	v_add_f32_e32 v21, v21, v21
	v_mul_f32_e32 v20, 0x3fb8aa3b, v20
	v_mul_f32_e32 v21, 0x3fb8aa3b, v21
	v_exp_f32_e32 v20, v20
	v_exp_f32_e32 v21, v21
	v_and_b32_e32 v17, 0xffff0000, v17
	v_pk_mul_f32 v[18:19], v[18:19], 0.5 op_sel_hi:[1,0]
	v_add_f32_e32 v20, 1.0, v20
	v_add_f32_e32 v21, 1.0, v21
	v_rcp_f32_e32 v20, v20
	v_rcp_f32_e32 v21, v21
	s_nop 0
	v_pk_fma_f32 v[20:21], v[20:21], 2.0, 1.0 op_sel_hi:[1,0,0] neg_lo:[1,0,0] neg_hi:[1,0,0]
	s_nop 0
	v_pk_add_f32 v[20:21], v[20:21], 1.0 op_sel_hi:[1,0]
	s_nop 0
	v_pk_mul_f32 v[18:19], v[18:19], v[20:21]
	v_mov_b32_e32 v20, v0
	v_mul_f32_e32 v0, 0x3d372713, v17
	v_mov_b32_e32 v21, v2
	v_mul_f32_e32 v0, v0, v17
	v_mov_b32_e32 v2, v17
	v_fmac_f32_e32 v2, v0, v2
	v_mul_f32_e32 v0, 0x3f4c422a, v2
	v_add_f32_e32 v0, v0, v0
	v_mul_f32_e32 v0, 0x3fb8aa3b, v0
	v_exp_f32_e32 v0, v0
	v_pk_add_f32 v[20:21], v[20:21], v[64:65] op_sel_hi:[1,0]
	v_pk_mul_f32 v[16:17], v[16:17], 0.5 op_sel_hi:[1,0]
	v_pk_mul_f32 v[18:19], v[20:21], v[18:19]
	v_add_f32_e32 v0, 1.0, v0
	v_rcp_f32_e32 v23, v0
	v_mov_b32_e32 v2, v1
	v_pk_add_f32 v[0:1], v[2:3], v[64:65] op_sel_hi:[1,0]
	v_and_b32_sdwa v2, v19, v196 dst_sel:DWORD dst_unused:UNUSED_PAD src0_sel:WORD_1 src1_sel:DWORD
	v_pk_fma_f32 v[20:21], v[22:23], 2.0, 1.0 op_sel_hi:[1,0,0] neg_lo:[1,0,0] neg_hi:[1,0,0]
	v_and_b32_sdwa v3, v18, v196 dst_sel:DWORD dst_unused:UNUSED_PAD src0_sel:WORD_1 src1_sel:DWORD
	v_pk_add_f32 v[20:21], v[20:21], 1.0 op_sel_hi:[1,0]
	v_add3_u32 v3, v18, v3, s45
	v_pk_mul_f32 v[16:17], v[16:17], v[20:21]
	v_add3_u32 v2, v19, v2, s45
	v_pk_mul_f32 v[0:1], v[0:1], v[16:17]
	s_nop 0
	v_and_b32_sdwa v16, v1, v196 dst_sel:DWORD dst_unused:UNUSED_PAD src0_sel:WORD_1 src1_sel:DWORD
	v_and_b32_sdwa v17, v0, v196 dst_sel:DWORD dst_unused:UNUSED_PAD src0_sel:WORD_1 src1_sel:DWORD
	v_add3_u32 v1, v1, v16, s45
	v_add3_u32 v0, v0, v17, s45
	v_and_b32_e32 v1, 0xffff0000, v1
	v_and_b32_e32 v0, 0xffff0000, v0
	v_or_b32_sdwa v1, v1, v2 dst_sel:DWORD dst_unused:UNUSED_PAD src0_sel:DWORD src1_sel:WORD_1
	v_or_b32_sdwa v0, v0, v3 dst_sel:DWORD dst_unused:UNUSED_PAD src0_sel:DWORD src1_sel:WORD_1
	global_store_dwordx2 v[66:67], v[0:1], off offset:192
	s_waitcnt vmcnt(15)
; __device__ __forceinline__ unsigned pk2(float lo, float hi) { return f2bf(lo) | (f2bf(hi) << 16); }
; __device__ __forceinline__ void gmlp_fast(KArgs ap, int l, LAS unsigned char* lds, const Ctx cx) {
;     ...
;             for (int ht = 0; ht < 4; ++ht)
; #pragma unroll
;                 for (int q4 = 0; q4 < 4; ++q4) { const u32x2 uu = *(const u32x2*)(zu + ht * 32 + 8 * q4);
;                     const float o0 = gelu_tanh(bflo(uu.x)) * (acc[ht][4 * q4] + bsv), o1 = gelu_tanh(bfhi(uu.x)) * (acc[ht][4 * q4 + 1] + bsv);
;                     const float o2 = gelu_tanh(bflo(uu.y)) * (acc[ht][4 * q4 + 2] + bsv), o3 = gelu_tanh(bfhi(uu.y)) * (acc[ht][4 * q4 + 3] + bsv);
;                     u32x2 w; w.x = pk2(o0, o1); w.y = pk2(o2, o3); *(u32x2*)(yo + ht * 32 + 8 * q4) = w; }
	v_mov_b32_e32 v0, v224
	v_mov_b32_e32 v1, v225
	v_lshlrev_b32_e32 v2, 16, v0
	v_mul_f32_e32 v16, 0x3d372713, v2
	v_mul_f32_e32 v16, v16, v2
	v_mov_b32_e32 v17, v2
	v_fmac_f32_e32 v17, v16, v17
	v_and_b32_e32 v0, 0xffff0000, v0
	v_mul_f32_e32 v16, 0x3f4c422a, v17
	v_mul_f32_e32 v17, 0x3d372713, v0
	v_mul_f32_e32 v17, v17, v0
	v_mov_b32_e32 v18, v0
	v_fmac_f32_e32 v18, v17, v18
	v_mul_f32_e32 v17, 0x3f4c422a, v18
	v_add_f32_e32 v17, v17, v17
	v_mul_f32_e32 v17, 0x3fb8aa3b, v17
	v_exp_f32_e32 v17, v17
	v_lshlrev_b32_e32 v3, 16, v1
	v_mov_b32_e32 v19, v3
	v_add_f32_e32 v16, v16, v16
	v_add_f32_e32 v17, 1.0, v17
	v_rcp_f32_e32 v18, v17
	v_mul_f32_e32 v17, 0x3d372713, v3
	v_mul_f32_e32 v17, v17, v3
	v_fmac_f32_e32 v19, v17, v19
	v_mul_f32_e32 v17, 0x3f4c422a, v19
	v_add_f32_e32 v17, v17, v17
	v_mul_f32_e32 v16, 0x3fb8aa3b, v16
	v_mul_f32_e32 v17, 0x3fb8aa3b, v17
	v_exp_f32_e32 v16, v16
	v_exp_f32_e32 v17, v17
	v_and_b32_e32 v1, 0xffff0000, v1
	v_pk_mul_f32 v[2:3], v[2:3], 0.5 op_sel_hi:[1,0]
	v_add_f32_e32 v16, 1.0, v16
	v_add_f32_e32 v17, 1.0, v17
	v_rcp_f32_e32 v16, v16
	v_rcp_f32_e32 v17, v17
	s_nop 0
	v_pk_fma_f32 v[16:17], v[16:17], 2.0, 1.0 op_sel_hi:[1,0,0] neg_lo:[1,0,0] neg_hi:[1,0,0]
	s_nop 0
	v_pk_add_f32 v[16:17], v[16:17], 1.0 op_sel_hi:[1,0]
	s_nop 0
	v_pk_mul_f32 v[2:3], v[2:3], v[16:17]
	v_mov_b32_e32 v16, v4
	v_mul_f32_e32 v4, 0x3d372713, v1
	v_mov_b32_e32 v17, v6
	v_mul_f32_e32 v4, v4, v1
	v_mov_b32_e32 v6, v1
	v_fmac_f32_e32 v6, v4, v6
	v_mul_f32_e32 v4, 0x3f4c422a, v6
	v_add_f32_e32 v4, v4, v4
	v_mul_f32_e32 v4, 0x3fb8aa3b, v4
	v_exp_f32_e32 v4, v4
	v_pk_add_f32 v[16:17], v[16:17], v[64:65] op_sel_hi:[1,0]
	v_pk_mul_f32 v[0:1], v[0:1], 0.5 op_sel_hi:[1,0]
	v_pk_mul_f32 v[2:3], v[16:17], v[2:3]
	v_add_f32_e32 v4, 1.0, v4
	v_rcp_f32_e32 v19, v4
	v_mov_b32_e32 v6, v5
	v_pk_add_f32 v[4:5], v[6:7], v[64:65] op_sel_hi:[1,0]
	v_pk_fma_f32 v[16:17], v[18:19], 2.0, 1.0 op_sel_hi:[1,0,0] neg_lo:[1,0,0] neg_hi:[1,0,0]
	s_nop 0
	v_pk_add_f32 v[16:17], v[16:17], 1.0 op_sel_hi:[1,0]
	s_nop 0
	v_pk_mul_f32 v[0:1], v[0:1], v[16:17]
	s_nop 0
	v_pk_mul_f32 v[0:1], v[4:5], v[0:1]
	v_and_b32_sdwa v4, v3, v196 dst_sel:DWORD dst_unused:UNUSED_PAD src0_sel:WORD_1 src1_sel:DWORD
	v_and_b32_sdwa v5, v2, v196 dst_sel:DWORD dst_unused:UNUSED_PAD src0_sel:WORD_1 src1_sel:DWORD
	v_add3_u32 v2, v2, v5, s45
	v_add3_u32 v3, v3, v4, s45
	v_and_b32_sdwa v4, v1, v196 dst_sel:DWORD dst_unused:UNUSED_PAD src0_sel:WORD_1 src1_sel:DWORD
	v_and_b32_sdwa v5, v0, v196 dst_sel:DWORD dst_unused:UNUSED_PAD src0_sel:WORD_1 src1_sel:DWORD
	v_add3_u32 v1, v1, v4, s45
	v_add3_u32 v0, v0, v5, s45
	v_and_b32_e32 v1, 0xffff0000, v1
	v_and_b32_e32 v0, 0xffff0000, v0
	v_or_b32_sdwa v1, v1, v3 dst_sel:DWORD dst_unused:UNUSED_PAD src0_sel:DWORD src1_sel:WORD_1
	v_or_b32_sdwa v0, v0, v2 dst_sel:DWORD dst_unused:UNUSED_PAD src0_sel:DWORD src1_sel:WORD_1
	global_store_dwordx2 v[66:67], v[0:1], off offset:208
	s_waitcnt vmcnt(15)
	v_mov_b32_e32 v0, v226
	v_mov_b32_e32 v1, v227
	v_lshlrev_b32_e32 v2, 16, v0
	v_mul_f32_e32 v4, 0x3d372713, v2
	v_mul_f32_e32 v4, v4, v2
	v_mov_b32_e32 v5, v2
	v_fmac_f32_e32 v5, v4, v5
	v_and_b32_e32 v0, 0xffff0000, v0
	v_mul_f32_e32 v4, 0x3f4c422a, v5
	v_mul_f32_e32 v5, 0x3d372713, v0
	v_mul_f32_e32 v5, v5, v0
	v_mov_b32_e32 v6, v0
	v_fmac_f32_e32 v6, v5, v6
	v_mul_f32_e32 v5, 0x3f4c422a, v6
	v_add_f32_e32 v5, v5, v5
	v_mul_f32_e32 v5, 0x3fb8aa3b, v5
	v_exp_f32_e32 v5, v5
	v_lshlrev_b32_e32 v3, 16, v1
	v_mov_b32_e32 v7, v3
	v_add_f32_e32 v4, v4, v4
	v_add_f32_e32 v5, 1.0, v5
	v_rcp_f32_e32 v6, v5
	v_mul_f32_e32 v5, 0x3d372713, v3
	v_mul_f32_e32 v5, v5, v3
	v_fmac_f32_e32 v7, v5, v7
	v_mul_f32_e32 v5, 0x3f4c422a, v7
	v_add_f32_e32 v5, v5, v5
	v_mul_f32_e32 v4, 0x3fb8aa3b, v4
	v_mul_f32_e32 v5, 0x3fb8aa3b, v5
	v_exp_f32_e32 v4, v4
	v_exp_f32_e32 v5, v5
	v_pk_mul_f32 v[2:3], v[2:3], 0.5 op_sel_hi:[1,0]
	v_and_b32_e32 v1, 0xffff0000, v1
	v_add_f32_e32 v4, 1.0, v4
	v_add_f32_e32 v5, 1.0, v5
	v_rcp_f32_e32 v4, v4
	v_rcp_f32_e32 v5, v5
	s_nop 0
	v_pk_fma_f32 v[4:5], v[4:5], 2.0, 1.0 op_sel_hi:[1,0,0] neg_lo:[1,0,0] neg_hi:[1,0,0]
	s_nop 0
	v_pk_add_f32 v[4:5], v[4:5], 1.0 op_sel_hi:[1,0]
	s_nop 0
	v_pk_mul_f32 v[2:3], v[2:3], v[4:5]
	v_mov_b32_e32 v4, v8
	v_mov_b32_e32 v5, v10
	v_pk_add_f32 v[4:5], v[4:5], v[64:65] op_sel_hi:[1,0]
	v_mov_b32_e32 v10, v9
	v_pk_mul_f32 v[2:3], v[4:5], v[2:3]
	v_mul_f32_e32 v4, 0x3d372713, v1
	v_mul_f32_e32 v4, v4, v1
	v_mov_b32_e32 v5, v1
	v_fmac_f32_e32 v5, v4, v5
	v_mul_f32_e32 v4, 0x3f4c422a, v5
	v_add_f32_e32 v4, v4, v4
	v_mul_f32_e32 v4, 0x3fb8aa3b, v4
	v_exp_f32_e32 v4, v4
	v_pk_mul_f32 v[0:1], v[0:1], 0.5 op_sel_hi:[1,0]
	v_add_f32_e32 v4, 1.0, v4
	v_rcp_f32_e32 v7, v4
	s_nop 0
	v_pk_fma_f32 v[4:5], v[6:7], 2.0, 1.0 op_sel_hi:[1,0,0] neg_lo:[1,0,0] neg_hi:[1,0,0]
	s_nop 0
	v_pk_add_f32 v[4:5], v[4:5], 1.0 op_sel_hi:[1,0]
	s_nop 0
	v_pk_mul_f32 v[0:1], v[0:1], v[4:5]
	v_pk_add_f32 v[4:5], v[10:11], v[64:65] op_sel_hi:[1,0]
	s_nop 0
	v_pk_mul_f32 v[0:1], v[4:5], v[0:1]
	v_and_b32_sdwa v4, v3, v196 dst_sel:DWORD dst_unused:UNUSED_PAD src0_sel:WORD_1 src1_sel:DWORD
	v_and_b32_sdwa v5, v2, v196 dst_sel:DWORD dst_unused:UNUSED_PAD src0_sel:WORD_1 src1_sel:DWORD
	v_add3_u32 v2, v2, v5, s45
	v_add3_u32 v3, v3, v4, s45
	v_and_b32_sdwa v4, v1, v196 dst_sel:DWORD dst_unused:UNUSED_PAD src0_sel:WORD_1 src1_sel:DWORD
	v_and_b32_sdwa v5, v0, v196 dst_sel:DWORD dst_unused:UNUSED_PAD src0_sel:WORD_1 src1_sel:DWORD
	v_add3_u32 v1, v1, v4, s45
	v_add3_u32 v0, v0, v5, s45
	v_and_b32_e32 v1, 0xffff0000, v1
	v_and_b32_e32 v0, 0xffff0000, v0
	v_or_b32_sdwa v1, v1, v3 dst_sel:DWORD dst_unused:UNUSED_PAD src0_sel:DWORD src1_sel:WORD_1
	v_or_b32_sdwa v0, v0, v2 dst_sel:DWORD dst_unused:UNUSED_PAD src0_sel:DWORD src1_sel:WORD_1
	s_nop 0
	global_store_dwordx2 v[66:67], v[0:1], off offset:224
	s_waitcnt vmcnt(15)
; __device__ __forceinline__ unsigned pk2(float lo, float hi) { return f2bf(lo) | (f2bf(hi) << 16); }
; __device__ __forceinline__ void gmlp_fast(KArgs ap, int l, LAS unsigned char* lds, const Ctx cx) {
;     ...
;         for (int k = 0; k < 2; ++k) {
;             __syncthreads();
; #pragma unroll 2
;             for (int e = 0; e < 4; ++e) { const int chl = lane + 64 * e, ch = 256 * k + chl;
;                 const float gg = lng[ch], bb = lnb[ch];
;                 float vv[16];
; #pragma unroll
;                 for (int i = 0; i < 16; ++i) { const int s = wave * 16 + i; const float x = gelu_tanh(bf2f(z[(t0 + s) * DIN + ZGV + ch])); vv[i] = (x - ST[2 * s]) * ST[2 * s + 1] * gg + bb; }
;     ...
;             for (int ht = 0; ht < 4; ++ht)
; #pragma unroll
;                 for (int q4 = 0; q4 < 4; ++q4) { const u32x2 uu = *(const u32x2*)(zu + ht * 32 + 8 * q4);
;                     const float o0 = gelu_tanh(bflo(uu.x)) * (acc[ht][4 * q4] + bsv), o1 = gelu_tanh(bfhi(uu.x)) * (acc[ht][4 * q4 + 1] + bsv);
;                     const float o2 = gelu_tanh(bflo(uu.y)) * (acc[ht][4 * q4 + 2] + bsv), o3 = gelu_tanh(bfhi(uu.y)) * (acc[ht][4 * q4 + 3] + bsv);
;                     u32x2 w; w.x = pk2(o0, o1); w.y = pk2(o2, o3); *(u32x2*)(yo + ht * 32 + 8 * q4) = w; }
	v_mov_b32_e32 v2, v228
	v_mov_b32_e32 v3, v229
	v_lshlrev_b32_e32 v0, 16, v2
	v_mul_f32_e32 v4, 0x3d372713, v0
	v_mul_f32_e32 v4, v4, v0
	v_mov_b32_e32 v5, v0
	v_fmac_f32_e32 v5, v4, v5
	v_and_b32_e32 v2, 0xffff0000, v2
	v_mul_f32_e32 v4, 0x3f4c422a, v5
	v_mul_f32_e32 v5, 0x3d372713, v2
	v_mul_f32_e32 v5, v5, v2
	v_mov_b32_e32 v6, v2
	v_fmac_f32_e32 v6, v5, v6
	v_mul_f32_e32 v5, 0x3f4c422a, v6
	v_add_f32_e32 v5, v5, v5
	v_mul_f32_e32 v5, 0x3fb8aa3b, v5
	v_exp_f32_e32 v5, v5
	v_lshlrev_b32_e32 v1, 16, v3
	v_mov_b32_e32 v7, v1
	v_add_f32_e32 v4, v4, v4
	v_add_f32_e32 v5, 1.0, v5
	v_rcp_f32_e32 v6, v5
	v_mul_f32_e32 v5, 0x3d372713, v1
	v_mul_f32_e32 v5, v5, v1
	v_fmac_f32_e32 v7, v5, v7
	v_mul_f32_e32 v5, 0x3f4c422a, v7
	v_add_f32_e32 v5, v5, v5
	v_mul_f32_e32 v4, 0x3fb8aa3b, v4
	v_mul_f32_e32 v5, 0x3fb8aa3b, v5
	v_exp_f32_e32 v4, v4
	v_exp_f32_e32 v5, v5
	v_pk_mul_f32 v[0:1], v[0:1], 0.5 op_sel_hi:[1,0]
	v_and_b32_e32 v3, 0xffff0000, v3
	v_add_f32_e32 v4, 1.0, v4
	v_add_f32_e32 v5, 1.0, v5
	v_rcp_f32_e32 v4, v4
	v_rcp_f32_e32 v5, v5
	s_nop 0
	v_pk_fma_f32 v[4:5], v[4:5], 2.0, 1.0 op_sel_hi:[1,0,0] neg_lo:[1,0,0] neg_hi:[1,0,0]
	s_nop 0
	v_pk_add_f32 v[4:5], v[4:5], 1.0 op_sel_hi:[1,0]
	s_nop 0
	v_pk_mul_f32 v[0:1], v[0:1], v[4:5]
	v_mov_b32_e32 v4, v12
	v_mov_b32_e32 v5, v14
	v_pk_add_f32 v[4:5], v[4:5], v[64:65] op_sel_hi:[1,0]
	v_mov_b32_e32 v14, v13
	v_pk_mul_f32 v[0:1], v[4:5], v[0:1]
	v_mul_f32_e32 v4, 0x3d372713, v3
	v_mul_f32_e32 v4, v4, v3
	v_mov_b32_e32 v5, v3
	v_fmac_f32_e32 v5, v4, v5
	v_mul_f32_e32 v4, 0x3f4c422a, v5
	v_add_f32_e32 v4, v4, v4
	v_mul_f32_e32 v4, 0x3fb8aa3b, v4
	v_exp_f32_e32 v4, v4
	v_pk_mul_f32 v[2:3], v[2:3], 0.5 op_sel_hi:[1,0]
	v_add_f32_e32 v4, 1.0, v4
	v_rcp_f32_e32 v7, v4
	s_nop 0
	v_pk_fma_f32 v[4:5], v[6:7], 2.0, 1.0 op_sel_hi:[1,0,0] neg_lo:[1,0,0] neg_hi:[1,0,0]
	s_nop 0
	v_pk_add_f32 v[4:5], v[4:5], 1.0 op_sel_hi:[1,0]
	s_nop 0
	v_pk_mul_f32 v[2:3], v[2:3], v[4:5]
	v_pk_add_f32 v[4:5], v[14:15], v[64:65] op_sel_hi:[1,0]
	s_nop 0
	v_pk_mul_f32 v[2:3], v[4:5], v[2:3]
	v_and_b32_sdwa v4, v1, v196 dst_sel:DWORD dst_unused:UNUSED_PAD src0_sel:WORD_1 src1_sel:DWORD
	v_and_b32_sdwa v5, v0, v196 dst_sel:DWORD dst_unused:UNUSED_PAD src0_sel:WORD_1 src1_sel:DWORD
	v_add3_u32 v0, v0, v5, s45
	v_add3_u32 v1, v1, v4, s45
	v_and_b32_sdwa v4, v3, v196 dst_sel:DWORD dst_unused:UNUSED_PAD src0_sel:WORD_1 src1_sel:DWORD
	v_and_b32_sdwa v5, v2, v196 dst_sel:DWORD dst_unused:UNUSED_PAD src0_sel:WORD_1 src1_sel:DWORD
	v_add3_u32 v3, v3, v4, s45
	v_add3_u32 v2, v2, v5, s45
	v_and_b32_e32 v3, 0xffff0000, v3
	v_and_b32_e32 v2, 0xffff0000, v2
	v_or_b32_sdwa v1, v3, v1 dst_sel:DWORD dst_unused:UNUSED_PAD src0_sel:DWORD src1_sel:WORD_1
	v_or_b32_sdwa v0, v2, v0 dst_sel:DWORD dst_unused:UNUSED_PAD src0_sel:DWORD src1_sel:WORD_1
	global_store_dwordx2 v[66:67], v[0:1], off offset:240
	s_cbranch_vccnz .LBB0_140
.LBB0_161:
	s_xor_b64 s[0:1], s[20:21], -1
	s_lshl_b32 s20, s13, 8
	v_or_b32_e32 v0, s20, v106
	v_or_b32_e32 v6, s20, v112
	v_mov_b32_e32 v7, v153
	v_lshlrev_b32_e32 v0, 1, v0
	v_mov_b32_e32 v235, v0
	v_mov_b32_e32 v1, v153
	v_lshlrev_b64 v[4:5], 2, v[6:7]
	v_lshlrev_b32_e32 v6, 1, v6
	v_mov_b32_e32 v234, v6
	v_lshl_add_u64 v[0:1], s[18:19], 0, v[0:1]
	s_waitcnt lgkmcnt(0)
	v_lshl_add_u64 v[2:3], s[8:9], 0, v[4:5]
	v_lshl_add_u64 v[4:5], s[10:11], 0, v[4:5]
	v_lshl_add_u64 v[6:7], s[18:19], 0, v[6:7]
	s_mov_b64 s[20:21], 0
	v_mov_b32_e32 v9, v105
	s_barrier
.LBB0_162:
	v_lshl_add_u64 v[34:35], v[6:7], 0, s[20:21]
	global_load_dword v8, v[2:3], off offset:-256
	global_load_dword v10, v[4:5], off offset:-256
	global_load_dword v232, v[2:3], off
	global_load_dword v233, v[4:5], off
	s_add_u32 s88, s18, s20
	s_addc_u32 s89, s19, s21
	s_add_u32 s82, s88, 0x13001000
	s_addc_u32 s83, s89, 0
	global_load_ushort v200, v234, s[82:83] offset:512
	s_add_u32 s84, s88, 0x13003000
	s_addc_u32 s85, s89, 0
	global_load_ushort v201, v234, s[84:85] offset:3584
	s_add_u32 s86, s88, 0x13002000
	s_addc_u32 s87, s89, 0
	global_load_ushort v202, v234, s[86:87] offset:2048
	s_add_u32 s82, s88, 0x13005000
	s_addc_u32 s83, s89, 0
	global_load_ushort v203, v234, s[82:83] offset:1024
	s_add_u32 s84, s88, 0x13006000
	s_addc_u32 s85, s89, 0
	global_load_ushort v204, v234, s[84:85] offset:2560
	s_add_u32 s86, s88, 0x13009000
	s_addc_u32 s87, s89, 0
	global_load_ushort v205, v234, s[86:87] offset:1536
	s_add_u32 s82, s88, 0x13008000
	s_addc_u32 s83, s89, 0
	global_load_ushort v206, v234, s[82:83]
	s_add_u32 s84, s88, 0x1300a000
	s_addc_u32 s85, s89, 0
	global_load_ushort v207, v234, s[84:85] offset:3072
	s_add_u32 s86, s88, 0x1300c000
	s_addc_u32 s87, s89, 0
	global_load_ushort v208, v234, s[86:87] offset:512
	s_add_u32 s82, s88, 0x1300e000
	s_addc_u32 s83, s89, 0
	global_load_ushort v209, v234, s[82:83] offset:3584
	s_add_u32 s84, s88, 0x1300d000
	s_addc_u32 s85, s89, 0
	global_load_ushort v210, v234, s[84:85] offset:2048
	s_add_u32 s86, s88, 0x13010000
	s_addc_u32 s87, s89, 0
	global_load_ushort v211, v234, s[86:87] offset:1024
	s_add_u32 s82, s88, 0x13011000
	s_addc_u32 s83, s89, 0
	global_load_ushort v212, v234, s[82:83] offset:2560
	s_add_u32 s84, s88, 0x13014000
	s_addc_u32 s85, s89, 0
	global_load_ushort v213, v234, s[84:85] offset:1536
	s_add_u32 s86, s88, 0x13015000
	s_addc_u32 s87, s89, 0
	global_load_ushort v214, v234, s[86:87] offset:3072
	s_add_u32 s82, s88, 0x13013000
	s_addc_u32 s83, s89, 0
	global_load_ushort v215, v234, s[82:83]
	s_add_u32 s84, s88, 0x13001000
	s_addc_u32 s85, s89, 0
	global_load_ushort v216, v235, s[84:85] offset:512
	s_add_u32 s86, s88, 0x13003000
	s_addc_u32 s87, s89, 0
	global_load_ushort v217, v235, s[86:87] offset:3584
; __device__ __forceinline__ void gmlp_fast(KArgs ap, int l, LAS unsigned char* lds, const Ctx cx) {
;     ...
;             for (int e = 0; e < 4; ++e) { const int chl = lane + 64 * e, ch = 256 * k + chl;
;                 const float gg = lng[ch], bb = lnb[ch];
;                 float vv[16];
; #pragma unroll
;                 for (int i = 0; i < 16; ++i) { const int s = wave * 16 + i; const float x = gelu_tanh(bf2f(z[(t0 + s) * DIN + ZGV + ch])); vv[i] = (x - ST[2 * s]) * ST[2 * s + 1] * gg + bb; }
	s_add_u32 s82, s88, 0x13002000
	s_addc_u32 s83, s89, 0
	global_load_ushort v218, v235, s[82:83] offset:2048
	s_add_u32 s84, s88, 0x13005000
	s_addc_u32 s85, s89, 0
	global_load_ushort v219, v235, s[84:85] offset:1024
	s_add_u32 s86, s88, 0x13006000
	s_addc_u32 s87, s89, 0
	global_load_ushort v220, v235, s[86:87] offset:2560
	s_add_u32 s82, s88, 0x13009000
	s_addc_u32 s83, s89, 0
	global_load_ushort v221, v235, s[82:83] offset:1536
	s_add_u32 s84, s88, 0x13008000
	s_addc_u32 s85, s89, 0
	global_load_ushort v222, v235, s[84:85]
	s_add_u32 s86, s88, 0x1300a000
	s_addc_u32 s87, s89, 0
	global_load_ushort v223, v235, s[86:87] offset:3072
	s_add_u32 s82, s88, 0x1300c000
	s_addc_u32 s83, s89, 0
	global_load_ushort v224, v235, s[82:83] offset:512
	s_add_u32 s84, s88, 0x1300e000
	s_addc_u32 s85, s89, 0
	global_load_ushort v225, v235, s[84:85] offset:3584
	s_add_u32 s86, s88, 0x1300d000
	s_addc_u32 s87, s89, 0
	global_load_ushort v226, v235, s[86:87] offset:2048
	s_add_u32 s82, s88, 0x13010000
	s_addc_u32 s83, s89, 0
	global_load_ushort v227, v235, s[82:83] offset:1024
	s_add_u32 s84, s88, 0x13011000
	s_addc_u32 s85, s89, 0
	global_load_ushort v228, v235, s[84:85] offset:2560
	s_add_u32 s86, s88, 0x13014000
	s_addc_u32 s87, s89, 0
	global_load_ushort v229, v235, s[86:87] offset:1536
	s_add_u32 s82, s88, 0x13013000
	s_addc_u32 s83, s89, 0
	global_load_ushort v230, v235, s[82:83]
	s_add_u32 s84, s88, 0x13015000
	s_addc_u32 s85, s89, 0
	global_load_ushort v231, v235, s[84:85] offset:3072
	s_add_i32 s22, 0, 0x11000
	s_nop 0
	s_add_i32 s23, s22, s30
	s_waitcnt vmcnt(31)
	v_lshlrev_b32_e32 v40, 16, v200
	v_mul_f32_e32 v11, 0x3d372713, v40
	v_mul_f32_e32 v11, v11, v40
	s_waitcnt vmcnt(30)
	v_lshlrev_b32_e32 v41, 16, v201
	v_mov_b32_e32 v12, v40
	v_fmac_f32_e32 v12, v11, v12
	v_mul_f32_e32 v11, 0x3f4c422a, v12
	v_add_f32_e32 v11, v11, v11
	v_mul_f32_e32 v11, 0x3fb8aa3b, v11
	v_exp_f32_e32 v11, v11
	v_mov_b32_e32 v13, v41
	v_add_f32_e32 v11, 1.0, v11
	v_rcp_f32_e32 v12, v11
	v_mul_f32_e32 v11, 0x3d372713, v41
	v_mul_f32_e32 v11, v11, v41
	v_fmac_f32_e32 v13, v11, v13
	v_mul_f32_e32 v11, 0x3f4c422a, v13
	v_add_f32_e32 v11, v11, v11
	v_mul_f32_e32 v11, 0x3fb8aa3b, v11
	v_exp_f32_e32 v11, v11
	v_pk_mul_f32 v[40:41], v[40:41], 0.5 op_sel_hi:[1,0]
	v_add_f32_e32 v11, 1.0, v11
	v_rcp_f32_e32 v13, v11
	s_nop 0
	v_pk_fma_f32 v[42:43], v[12:13], 2.0, 1.0 op_sel_hi:[1,0,0] neg_lo:[1,0,0] neg_hi:[1,0,0]
	s_nop 0
	v_pk_add_f32 v[42:43], v[42:43], 1.0 op_sel_hi:[1,0]
	s_nop 0
	s_nop 1
	s_waitcnt vmcnt(28)
	v_lshlrev_b32_e32 v13, 16, v203
	s_waitcnt vmcnt(29)
	v_lshlrev_b32_e32 v12, 16, v202
	v_mul_f32_e32 v11, 0x3d372713, v12
	v_mul_f32_e32 v11, v11, v12
	v_mov_b32_e32 v14, v12
	v_fmac_f32_e32 v14, v11, v14
	v_mul_f32_e32 v11, 0x3f4c422a, v14
	v_add_f32_e32 v11, v11, v11
	v_mul_f32_e32 v11, 0x3fb8aa3b, v11
	v_exp_f32_e32 v11, v11
	v_mov_b32_e32 v15, v13
	v_add_f32_e32 v11, 1.0, v11
	v_rcp_f32_e32 v14, v11
	v_mul_f32_e32 v11, 0x3d372713, v13
	v_mul_f32_e32 v11, v11, v13
	v_fmac_f32_e32 v15, v11, v15
	v_mul_f32_e32 v11, 0x3f4c422a, v15
	v_add_f32_e32 v11, v11, v11
	v_mul_f32_e32 v11, 0x3fb8aa3b, v11
	v_exp_f32_e32 v11, v11
	v_pk_mul_f32 v[12:13], v[12:13], 0.5 op_sel_hi:[1,0]
	v_add_f32_e32 v11, 1.0, v11
	v_rcp_f32_e32 v15, v11
	s_nop 0
	v_pk_fma_f32 v[14:15], v[14:15], 2.0, 1.0 op_sel_hi:[1,0,0] neg_lo:[1,0,0] neg_hi:[1,0,0]
	s_nop 0
	v_pk_add_f32 v[14:15], v[14:15], 1.0 op_sel_hi:[1,0]
	s_waitcnt vmcnt(26)
	v_lshlrev_b32_e32 v17, 16, v205
	s_waitcnt vmcnt(27)
	v_lshlrev_b32_e32 v16, 16, v204
	v_mul_f32_e32 v11, 0x3d372713, v16
	v_mul_f32_e32 v11, v11, v16
	v_mov_b32_e32 v18, v16
	v_fmac_f32_e32 v18, v11, v18
	v_mul_f32_e32 v11, 0x3f4c422a, v18
	v_add_f32_e32 v11, v11, v11
	v_mul_f32_e32 v11, 0x3fb8aa3b, v11
	v_exp_f32_e32 v11, v11
	v_mov_b32_e32 v19, v17
	v_add_f32_e32 v11, 1.0, v11
	v_rcp_f32_e32 v18, v11
	v_mul_f32_e32 v11, 0x3d372713, v17
	v_mul_f32_e32 v11, v11, v17
	v_fmac_f32_e32 v19, v11, v19
	v_mul_f32_e32 v11, 0x3f4c422a, v19
	v_add_f32_e32 v11, v11, v11
	v_mul_f32_e32 v11, 0x3fb8aa3b, v11
	v_exp_f32_e32 v11, v11
	s_nop 0
	v_add_f32_e32 v11, 1.0, v11
	v_rcp_f32_e32 v19, v11
	s_nop 0
	v_pk_fma_f32 v[22:23], v[18:19], 2.0, 1.0 op_sel_hi:[1,0,0] neg_lo:[1,0,0] neg_hi:[1,0,0]
	s_nop 0
	v_pk_add_f32 v[22:23], v[22:23], 1.0 op_sel_hi:[1,0]
	s_nop 0
	s_waitcnt vmcnt(25)
	v_lshlrev_b32_e32 v20, 16, v206
	v_mul_f32_e32 v11, 0x3d372713, v20
	v_mul_f32_e32 v11, v11, v20
	s_waitcnt vmcnt(24)
	v_lshlrev_b32_e32 v21, 16, v207
	v_mov_b32_e32 v18, v20
	v_fmac_f32_e32 v18, v11, v18
	v_mul_f32_e32 v11, 0x3f4c422a, v18
	v_add_f32_e32 v11, v11, v11
	v_mul_f32_e32 v11, 0x3fb8aa3b, v11
	v_exp_f32_e32 v11, v11
	v_mov_b32_e32 v19, v21
	v_add_f32_e32 v11, 1.0, v11
	v_rcp_f32_e32 v18, v11
	v_mul_f32_e32 v11, 0x3d372713, v21
	v_mul_f32_e32 v11, v11, v21
	v_fmac_f32_e32 v19, v11, v19
	v_mul_f32_e32 v11, 0x3f4c422a, v19
	v_add_f32_e32 v11, v11, v11
	v_mul_f32_e32 v11, 0x3fb8aa3b, v11
	v_exp_f32_e32 v11, v11
	v_pk_mul_f32 v[20:21], v[20:21], 0.5 op_sel_hi:[1,0]
	v_add_f32_e32 v11, 1.0, v11
	v_rcp_f32_e32 v19, v11
	s_nop 0
	v_pk_fma_f32 v[28:29], v[18:19], 2.0, 1.0 op_sel_hi:[1,0,0] neg_lo:[1,0,0] neg_hi:[1,0,0]
	s_nop 1
	s_nop 1
	s_waitcnt vmcnt(22)
	v_lshlrev_b32_e32 v19, 16, v209
	s_waitcnt vmcnt(23)
; #define LAS __attribute__((address_space(3)))
; __device__ __forceinline__ unsigned pk2(float lo, float hi) { return f2bf(lo) | (f2bf(hi) << 16); }
; __device__ __forceinline__ void gmlp_fast(KArgs ap, int l, LAS unsigned char* lds, const Ctx cx) {
;     ...
;             for (int e = 0; e < 4; ++e) { const int chl = lane + 64 * e, ch = 256 * k + chl;
;                 const float gg = lng[ch], bb = lnb[ch];
;                 float vv[16];
; #pragma unroll
;                 for (int i = 0; i < 16; ++i) { const int s = wave * 16 + i; const float x = gelu_tanh(bf2f(z[(t0 + s) * DIN + ZGV + ch])); vv[i] = (x - ST[2 * s]) * ST[2 * s + 1] * gg + bb; }
;                 u32x4 w0, w1;
;                 w0.x = pk2(vv[0], vv[1]); w0.y = pk2(vv[2], vv[3]); w0.z = pk2(vv[4], vv[5]); w0.w = pk2(vv[6], vv[7]);
;                 w1.x = pk2(vv[8], vv[9]); w1.y = pk2(vv[10], vv[11]); w1.z = pk2(vv[12], vv[13]); w1.w = pk2(vv[14], vv[15]);
;                 *(LAS u32x4*)(VT + chl * 272 + wave * 32) = w0; *(LAS u32x4*)(VT + chl * 272 + wave * 32 + 16) = w1; }
	v_lshlrev_b32_e32 v18, 16, v208
	v_mul_f32_e32 v11, 0x3d372713, v18
	v_mul_f32_e32 v11, v11, v18
	v_mov_b32_e32 v24, v18
	v_fmac_f32_e32 v24, v11, v24
	v_mul_f32_e32 v11, 0x3f4c422a, v24
	v_add_f32_e32 v11, v11, v11
	v_mul_f32_e32 v11, 0x3fb8aa3b, v11
	v_exp_f32_e32 v11, v11
	v_mov_b32_e32 v25, v19
	v_add_f32_e32 v11, 1.0, v11
	v_rcp_f32_e32 v24, v11
	v_mul_f32_e32 v11, 0x3d372713, v19
	v_mul_f32_e32 v11, v11, v19
	v_fmac_f32_e32 v25, v11, v25
	v_mul_f32_e32 v11, 0x3f4c422a, v25
	v_add_f32_e32 v11, v11, v11
	v_mul_f32_e32 v11, 0x3fb8aa3b, v11
	v_exp_f32_e32 v11, v11
	v_pk_mul_f32 v[18:19], v[18:19], 0.5 op_sel_hi:[1,0]
	v_add_f32_e32 v11, 1.0, v11
	v_rcp_f32_e32 v25, v11
	s_nop 0
	v_pk_fma_f32 v[26:27], v[24:25], 2.0, 1.0 op_sel_hi:[1,0,0] neg_lo:[1,0,0] neg_hi:[1,0,0]
	s_nop 1
	s_nop 1
	s_waitcnt vmcnt(20)
	v_lshlrev_b32_e32 v25, 16, v211
	s_waitcnt vmcnt(21)
	v_lshlrev_b32_e32 v24, 16, v210
	v_mul_f32_e32 v11, 0x3d372713, v24
	v_mul_f32_e32 v11, v11, v24
	v_mov_b32_e32 v30, v24
	v_fmac_f32_e32 v30, v11, v30
	v_mul_f32_e32 v11, 0x3f4c422a, v30
	v_add_f32_e32 v11, v11, v11
	v_mul_f32_e32 v11, 0x3fb8aa3b, v11
	v_exp_f32_e32 v11, v11
	v_mov_b32_e32 v31, v25
	v_add_f32_e32 v11, 1.0, v11
	v_rcp_f32_e32 v30, v11
	v_mul_f32_e32 v11, 0x3d372713, v25
	v_mul_f32_e32 v11, v11, v25
	v_fmac_f32_e32 v31, v11, v31
	v_mul_f32_e32 v11, 0x3f4c422a, v31
	v_add_f32_e32 v11, v11, v11
	v_mul_f32_e32 v11, 0x3fb8aa3b, v11
	v_exp_f32_e32 v11, v11
	s_nop 0
	v_add_f32_e32 v11, 1.0, v11
	v_rcp_f32_e32 v31, v11
	s_nop 0
	v_pk_fma_f32 v[30:31], v[30:31], 2.0, 1.0 op_sel_hi:[1,0,0] neg_lo:[1,0,0] neg_hi:[1,0,0]
	s_nop 0
	s_nop 1
	s_nop 1
	s_waitcnt vmcnt(18)
	v_lshlrev_b32_e32 v33, 16, v213
	s_waitcnt vmcnt(19)
	v_lshlrev_b32_e32 v32, 16, v212
	v_mul_f32_e32 v11, 0x3d372713, v32
	v_mul_f32_e32 v11, v11, v32
	v_mov_b32_e32 v36, v32
	v_fmac_f32_e32 v36, v11, v36
	v_mul_f32_e32 v11, 0x3f4c422a, v36
	v_add_f32_e32 v11, v11, v11
	v_mul_f32_e32 v11, 0x3fb8aa3b, v11
	v_exp_f32_e32 v11, v11
	v_mov_b32_e32 v37, v33
	s_waitcnt vmcnt(17)
	v_lshlrev_b32_e32 v35, 16, v214
	v_add_f32_e32 v11, 1.0, v11
	v_rcp_f32_e32 v36, v11
	v_mul_f32_e32 v11, 0x3d372713, v33
	v_mul_f32_e32 v11, v11, v33
	v_fmac_f32_e32 v37, v11, v37
	v_mul_f32_e32 v11, 0x3f4c422a, v37
	v_add_f32_e32 v11, v11, v11
	v_mul_f32_e32 v11, 0x3fb8aa3b, v11
	v_exp_f32_e32 v11, v11
	s_nop 0
	v_add_f32_e32 v11, 1.0, v11
	v_rcp_f32_e32 v37, v11
	v_mov_b32_e32 v39, v35
	v_pk_fma_f32 v[36:37], v[36:37], 2.0, 1.0 op_sel_hi:[1,0,0] neg_lo:[1,0,0] neg_hi:[1,0,0]
	s_waitcnt vmcnt(16)
	v_lshlrev_b32_e32 v34, 16, v215
	v_mul_f32_e32 v11, 0x3d372713, v34
	v_mul_f32_e32 v11, v11, v34
	v_mov_b32_e32 v38, v34
	v_fmac_f32_e32 v38, v11, v38
	v_mul_f32_e32 v11, 0x3f4c422a, v38
	v_add_f32_e32 v11, v11, v11
	v_mul_f32_e32 v11, 0x3fb8aa3b, v11
	v_exp_f32_e32 v11, v11
	s_nop 0
	v_add_f32_e32 v11, 1.0, v11
	v_rcp_f32_e32 v38, v11
	v_mul_f32_e32 v11, 0x3d372713, v35
	v_mul_f32_e32 v11, v11, v35
	v_fmac_f32_e32 v39, v11, v39
	v_mul_f32_e32 v11, 0x3f4c422a, v39
	v_add_f32_e32 v11, v11, v11
	v_mul_f32_e32 v11, 0x3fb8aa3b, v11
	v_exp_f32_e32 v11, v11
	s_nop 0
	v_add_f32_e32 v11, 1.0, v11
	v_rcp_f32_e32 v39, v11
	v_mov_b32_e32 v11, s23
	ds_read_b128 v[44:47], v11
	ds_read_b128 v[48:51], v11 offset:16
	s_add_i32 s23, s22, s31
	v_pk_fma_f32 v[38:39], v[38:39], 2.0, 1.0 op_sel_hi:[1,0,0] neg_lo:[1,0,0] neg_hi:[1,0,0]
	s_waitcnt lgkmcnt(1)
	v_mov_b32_e32 v52, v44
	s_waitcnt lgkmcnt(0)
	v_mov_b32_e32 v53, v48
	v_pk_fma_f32 v[40:41], v[40:41], v[42:43], v[52:53] neg_lo:[0,0,1] neg_hi:[0,0,1]
	v_mov_b32_e32 v48, v45
	v_pk_mul_f32 v[40:41], v[48:49], v[40:41]
	v_pk_mul_f32 v[48:49], v[16:17], 0.5 op_sel_hi:[1,0]
	v_pk_fma_f32 v[44:45], v[8:9], v[40:41], v[10:11] op_sel_hi:[0,1,0]
	v_mov_b32_e32 v40, v46
	v_mov_b32_e32 v41, v50
	v_pk_fma_f32 v[12:13], v[12:13], v[14:15], v[40:41] neg_lo:[0,0,1] neg_hi:[0,0,1]
	v_mov_b32_e32 v50, v47
	v_pk_mul_f32 v[12:13], v[50:51], v[12:13]
	s_nop 0
	v_pk_fma_f32 v[46:47], v[8:9], v[12:13], v[10:11] op_sel_hi:[0,1,0]
	v_mov_b32_e32 v12, s23
	ds_read_b128 v[14:17], v12
	ds_read_b128 v[40:43], v12 offset:16
	s_add_i32 s23, s22, s38
	s_add_i32 s22, s22, s39
	s_waitcnt lgkmcnt(1)
	v_mov_b32_e32 v50, v14
	s_waitcnt lgkmcnt(0)
	v_mov_b32_e32 v51, v40
	v_pk_fma_f32 v[22:23], v[48:49], v[22:23], v[50:51] neg_lo:[0,0,1] neg_hi:[0,0,1]
	v_mov_b32_e32 v40, v15
	v_pk_mul_f32 v[14:15], v[40:41], v[22:23]
	v_pk_add_f32 v[22:23], v[28:29], 1.0 op_sel_hi:[1,0]
	v_mov_b32_e32 v28, v16
	v_mov_b32_e32 v29, v42
	v_pk_fma_f32 v[20:21], v[20:21], v[22:23], v[28:29] neg_lo:[0,0,1] neg_hi:[0,0,1]
	v_mov_b32_e32 v42, v17
	v_pk_mul_f32 v[16:17], v[42:43], v[20:21]
	v_pk_fma_f32 v[14:15], v[8:9], v[14:15], v[10:11] op_sel_hi:[0,1,0]
	v_pk_fma_f32 v[16:17], v[8:9], v[16:17], v[10:11] op_sel_hi:[0,1,0]
	s_nop 0
	v_bfe_u32 v13, v17, 16, 1
	v_bfe_u32 v20, v16, 16, 1
	v_bfe_u32 v22, v46, 16, 1
	v_bfe_u32 v23, v15, 16, 1
	v_add3_u32 v28, v46, v22, s45
	v_add3_u32 v16, v16, v20, s45
	v_add3_u32 v13, v17, v13, s45
	v_bfe_u32 v17, v44, 16, 1
	v_bfe_u32 v20, v45, 16, 1
	v_bfe_u32 v22, v14, 16, 1
	v_add3_u32 v15, v15, v23, s45
	v_bfe_u32 v21, v47, 16, 1
	v_add3_u32 v14, v14, v22, s45
	v_add3_u32 v20, v45, v20, s45
	v_add3_u32 v17, v44, v17, s45
	v_lshrrev_b32_e32 v15, 16, v15
	v_add3_u32 v21, v47, v21, s45
	v_lshrrev_b32_e32 v17, 16, v17
	v_lshrrev_b32_e32 v20, 16, v20
	v_lshrrev_b32_e32 v14, 16, v14
	v_and_or_b32 v23, v13, s43, v15
	v_mov_b32_e32 v13, s23
	v_and_or_b32 v22, v16, s43, v14
	v_and_or_b32 v21, v21, s43, v20
	v_and_or_b32 v20, v28, s43, v17
	v_pk_add_f32 v[40:41], v[26:27], 1.0 op_sel_hi:[1,0]
	ds_read_b128 v[14:17], v13
	ds_read_b128 v[26:29], v13 offset:16
	s_waitcnt lgkmcnt(1)
; #define LAS __attribute__((address_space(3)))
; __device__ __forceinline__ unsigned pk2(float lo, float hi) { return f2bf(lo) | (f2bf(hi) << 16); }
; __device__ __forceinline__ void gmlp_fast(KArgs ap, int l, LAS unsigned char* lds, const Ctx cx) {
;     ...
;             for (int e = 0; e < 4; ++e) { const int chl = lane + 64 * e, ch = 256 * k + chl;
;                 const float gg = lng[ch], bb = lnb[ch];
;                 float vv[16];
; #pragma unroll
;                 for (int i = 0; i < 16; ++i) { const int s = wave * 16 + i; const float x = gelu_tanh(bf2f(z[(t0 + s) * DIN + ZGV + ch])); vv[i] = (x - ST[2 * s]) * ST[2 * s + 1] * gg + bb; }
;                 u32x4 w0, w1;
;                 w0.x = pk2(vv[0], vv[1]); w0.y = pk2(vv[2], vv[3]); w0.z = pk2(vv[4], vv[5]); w0.w = pk2(vv[6], vv[7]);
;                 w1.x = pk2(vv[8], vv[9]); w1.y = pk2(vv[10], vv[11]); w1.z = pk2(vv[12], vv[13]); w1.w = pk2(vv[14], vv[15]);
;                 *(LAS u32x4*)(VT + chl * 272 + wave * 32) = w0; *(LAS u32x4*)(VT + chl * 272 + wave * 32 + 16) = w1; }
	v_mov_b32_e32 v42, v14
	s_waitcnt lgkmcnt(0)
	v_mov_b32_e32 v43, v26
	v_pk_fma_f32 v[18:19], v[18:19], v[40:41], v[42:43] neg_lo:[0,0,1] neg_hi:[0,0,1]
	v_mov_b32_e32 v26, v15
	v_pk_mul_f32 v[14:15], v[26:27], v[18:19]
	v_pk_add_f32 v[18:19], v[30:31], 1.0 op_sel_hi:[1,0]
	v_pk_fma_f32 v[40:41], v[8:9], v[14:15], v[10:11] op_sel_hi:[0,1,0]
	v_pk_mul_f32 v[14:15], v[24:25], 0.5 op_sel_hi:[1,0]
	v_mov_b32_e32 v24, v16
	v_mov_b32_e32 v25, v28
	v_pk_fma_f32 v[14:15], v[14:15], v[18:19], v[24:25] neg_lo:[0,0,1] neg_hi:[0,0,1]
	v_mov_b32_e32 v28, v17
	v_pk_mul_f32 v[14:15], v[28:29], v[14:15]
	v_pk_mul_f32 v[30:31], v[32:33], 0.5 op_sel_hi:[1,0]
	v_pk_fma_f32 v[28:29], v[8:9], v[14:15], v[10:11] op_sel_hi:[0,1,0]
	v_mov_b32_e32 v14, s22
	ds_read_b128 v[16:19], v14
	ds_read_b128 v[24:27], v14 offset:16
	v_pk_add_f32 v[32:33], v[36:37], 1.0 op_sel_hi:[1,0]
	v_bfe_u32 v15, v29, 16, 1
	v_add3_u32 v15, v29, v15, s45
	s_waitcnt lgkmcnt(1)
	v_mov_b32_e32 v36, v16
	s_waitcnt lgkmcnt(0)
	v_mov_b32_e32 v37, v24
	v_pk_fma_f32 v[30:31], v[30:31], v[32:33], v[36:37] neg_lo:[0,0,1] neg_hi:[0,0,1]
	v_mov_b32_e32 v24, v17
	v_pk_mul_f32 v[16:17], v[24:25], v[30:31]
	v_pk_mul_f32 v[24:25], v[34:35], 0.5 op_sel_hi:[1,0]
	v_pk_add_f32 v[30:31], v[38:39], 1.0 op_sel_hi:[1,0]
	v_mov_b32_e32 v32, v18
	v_mov_b32_e32 v33, v26
	v_pk_fma_f32 v[24:25], v[24:25], v[30:31], v[32:33] neg_lo:[0,0,1] neg_hi:[0,0,1]
	v_mov_b32_e32 v26, v19
	v_pk_mul_f32 v[18:19], v[26:27], v[24:25]
	v_pk_fma_f32 v[16:17], v[8:9], v[16:17], v[10:11] op_sel_hi:[0,1,0]
	v_pk_fma_f32 v[18:19], v[8:9], v[18:19], v[10:11] op_sel_hi:[0,1,0]
	s_nop 0
	v_bfe_u32 v8, v19, 16, 1
	v_bfe_u32 v10, v18, 16, 1
	v_add3_u32 v10, v18, v10, s45
	v_add3_u32 v8, v19, v8, s45
	v_bfe_u32 v18, v40, 16, 1
	v_bfe_u32 v19, v41, 16, 1
	v_bfe_u32 v25, v16, 16, 1
	v_bfe_u32 v26, v17, 16, 1
	v_bfe_u32 v24, v28, 16, 1
	v_add3_u32 v17, v17, v26, s45
	v_add3_u32 v16, v16, v25, s45
	v_add3_u32 v19, v41, v19, s45
	v_add3_u32 v18, v40, v18, s45
	v_add3_u32 v24, v28, v24, s45
	v_lshrrev_b32_e32 v25, 16, v18
	v_lshrrev_b32_e32 v26, 16, v19
	v_lshrrev_b32_e32 v16, 16, v16
	v_lshrrev_b32_e32 v17, 16, v17
	v_and_or_b32 v19, v8, s43, v17
	v_and_or_b32 v18, v10, s43, v16
	v_and_or_b32 v17, v15, s43, v26
	v_and_or_b32 v16, v24, s43, v25
	ds_write_b128 v9, v[20:23]
	ds_write_b128 v9, v[16:19] offset:16
	s_mov_b32 s22, 0x13001000
	s_mov_b32 s22, 0x13003000
	s_nop 0
	v_mov_b32_e32 v8, v232
	v_mov_b32_e32 v10, v233
	s_add_u32 s20, s20, 0x100
	s_nop 0
	s_addc_u32 s21, s21, 0
	s_nop 0
	v_lshl_add_u64 v[2:3], v[2:3], 0, s[36:37]
	v_lshl_add_u64 v[4:5], v[4:5], 0, s[36:37]
	s_cmpk_eq_i32 s20, 0x200
	s_waitcnt vmcnt(0)
	v_lshlrev_b32_e32 v19, 16, v217
	v_lshlrev_b32_e32 v18, 16, v216
	v_mul_f32_e32 v15, 0x3d372713, v18
	v_mul_f32_e32 v15, v15, v18
	v_mov_b32_e32 v20, v18
	v_fmac_f32_e32 v20, v15, v20
	v_mul_f32_e32 v15, 0x3f4c422a, v20
	v_add_f32_e32 v15, v15, v15
	v_mul_f32_e32 v15, 0x3fb8aa3b, v15
	v_exp_f32_e32 v15, v15
	v_mov_b32_e32 v21, v19
	v_pk_mul_f32 v[52:53], v[18:19], 0.5 op_sel_hi:[1,0]
	v_add_f32_e32 v15, 1.0, v15
	v_rcp_f32_e32 v20, v15
	v_mul_f32_e32 v15, 0x3d372713, v19
	v_mul_f32_e32 v15, v15, v19
	v_fmac_f32_e32 v21, v15, v21
	v_mul_f32_e32 v15, 0x3f4c422a, v21
	v_add_f32_e32 v15, v15, v15
	v_mul_f32_e32 v15, 0x3fb8aa3b, v15
	v_exp_f32_e32 v15, v15
	s_nop 0
	v_add_f32_e32 v15, 1.0, v15
	v_rcp_f32_e32 v21, v15
	s_nop 0
	v_pk_fma_f32 v[20:21], v[20:21], 2.0, 1.0 op_sel_hi:[1,0,0] neg_lo:[1,0,0] neg_hi:[1,0,0]
	s_nop 0
	v_pk_add_f32 v[54:55], v[20:21], 1.0 op_sel_hi:[1,0]
	v_lshlrev_b32_e32 v24, 16, v218
	v_mul_f32_e32 v15, 0x3d372713, v24
	v_mul_f32_e32 v15, v15, v24
	v_lshlrev_b32_e32 v25, 16, v219
	v_mov_b32_e32 v22, v24
	v_fmac_f32_e32 v22, v15, v22
	v_mul_f32_e32 v15, 0x3f4c422a, v22
	v_add_f32_e32 v15, v15, v15
	v_mul_f32_e32 v15, 0x3fb8aa3b, v15
	v_exp_f32_e32 v15, v15
	v_mov_b32_e32 v23, v25
	v_add_f32_e32 v15, 1.0, v15
	v_rcp_f32_e32 v22, v15
	v_mul_f32_e32 v15, 0x3d372713, v25
	v_mul_f32_e32 v15, v15, v25
	v_fmac_f32_e32 v23, v15, v23
	v_mul_f32_e32 v15, 0x3f4c422a, v23
	v_add_f32_e32 v15, v15, v15
	v_mul_f32_e32 v15, 0x3fb8aa3b, v15
	v_exp_f32_e32 v15, v15
	s_nop 0
	v_add_f32_e32 v15, 1.0, v15
	v_rcp_f32_e32 v23, v15
	s_nop 0
	v_pk_fma_f32 v[26:27], v[22:23], 2.0, 1.0 op_sel_hi:[1,0,0] neg_lo:[1,0,0] neg_hi:[1,0,0]
	s_nop 1
	v_lshlrev_b32_e32 v28, 16, v220
	v_mul_f32_e32 v15, 0x3d372713, v28
	v_mul_f32_e32 v15, v15, v28
	v_lshlrev_b32_e32 v29, 16, v221
	v_mov_b32_e32 v22, v28
	v_fmac_f32_e32 v22, v15, v22
	v_mul_f32_e32 v15, 0x3f4c422a, v22
	v_add_f32_e32 v15, v15, v15
	v_mul_f32_e32 v15, 0x3fb8aa3b, v15
	v_exp_f32_e32 v15, v15
	v_mov_b32_e32 v23, v29
	v_add_f32_e32 v15, 1.0, v15
	v_rcp_f32_e32 v22, v15
	v_mul_f32_e32 v15, 0x3d372713, v29
	v_mul_f32_e32 v15, v15, v29
	v_fmac_f32_e32 v23, v15, v23
	v_mul_f32_e32 v15, 0x3f4c422a, v23
	v_add_f32_e32 v15, v15, v15
	v_mul_f32_e32 v15, 0x3fb8aa3b, v15
	v_exp_f32_e32 v15, v15
	s_nop 0
	v_add_f32_e32 v15, 1.0, v15
	v_rcp_f32_e32 v23, v15
	s_nop 0
	v_pk_fma_f32 v[30:31], v[22:23], 2.0, 1.0 op_sel_hi:[1,0,0] neg_lo:[1,0,0] neg_hi:[1,0,0]
	s_nop 1
	v_lshlrev_b32_e32 v32, 16, v222
	v_mul_f32_e32 v15, 0x3d372713, v32
	v_mul_f32_e32 v15, v15, v32
	v_lshlrev_b32_e32 v33, 16, v223
	v_mov_b32_e32 v22, v32
	v_fmac_f32_e32 v22, v15, v22
	v_mul_f32_e32 v15, 0x3f4c422a, v22
	v_add_f32_e32 v15, v15, v15
	v_mul_f32_e32 v15, 0x3fb8aa3b, v15
	v_exp_f32_e32 v15, v15
	v_mov_b32_e32 v23, v33
	v_add_f32_e32 v15, 1.0, v15
	v_rcp_f32_e32 v22, v15
	v_mul_f32_e32 v15, 0x3d372713, v33
	v_mul_f32_e32 v15, v15, v33
	v_fmac_f32_e32 v23, v15, v23
	v_mul_f32_e32 v15, 0x3f4c422a, v23
	v_add_f32_e32 v15, v15, v15
; #define LAS __attribute__((address_space(3)))
; __device__ __forceinline__ unsigned pk2(float lo, float hi) { return f2bf(lo) | (f2bf(hi) << 16); }
; __device__ __forceinline__ void gmlp_fast(KArgs ap, int l, LAS unsigned char* lds, const Ctx cx) {
;     ...
;             for (int e = 0; e < 4; ++e) { const int chl = lane + 64 * e, ch = 256 * k + chl;
;                 const float gg = lng[ch], bb = lnb[ch];
;                 float vv[16];
; #pragma unroll
;                 for (int i = 0; i < 16; ++i) { const int s = wave * 16 + i; const float x = gelu_tanh(bf2f(z[(t0 + s) * DIN + ZGV + ch])); vv[i] = (x - ST[2 * s]) * ST[2 * s + 1] * gg + bb; }
;                 u32x4 w0, w1;
;                 w0.x = pk2(vv[0], vv[1]); w0.y = pk2(vv[2], vv[3]); w0.z = pk2(vv[4], vv[5]); w0.w = pk2(vv[6], vv[7]);
;                 w1.x = pk2(vv[8], vv[9]); w1.y = pk2(vv[10], vv[11]); w1.z = pk2(vv[12], vv[13]); w1.w = pk2(vv[14], vv[15]);
;                 *(LAS u32x4*)(VT + chl * 272 + wave * 32) = w0; *(LAS u32x4*)(VT + chl * 272 + wave * 32 + 16) = w1; }
	v_mul_f32_e32 v15, 0x3fb8aa3b, v15
	v_exp_f32_e32 v15, v15
	s_nop 0
	v_add_f32_e32 v15, 1.0, v15
	v_rcp_f32_e32 v23, v15
	s_nop 0
	v_pk_fma_f32 v[34:35], v[22:23], 2.0, 1.0 op_sel_hi:[1,0,0] neg_lo:[1,0,0] neg_hi:[1,0,0]
	s_nop 1
	v_lshlrev_b32_e32 v36, 16, v224
	v_mul_f32_e32 v15, 0x3d372713, v36
	v_mul_f32_e32 v15, v15, v36
	v_lshlrev_b32_e32 v37, 16, v225
	v_mov_b32_e32 v22, v36
	v_fmac_f32_e32 v22, v15, v22
	v_mul_f32_e32 v15, 0x3f4c422a, v22
	v_add_f32_e32 v15, v15, v15
	v_mul_f32_e32 v15, 0x3fb8aa3b, v15
	v_exp_f32_e32 v15, v15
	v_mov_b32_e32 v23, v37
	v_add_f32_e32 v15, 1.0, v15
	v_rcp_f32_e32 v22, v15
	v_mul_f32_e32 v15, 0x3d372713, v37
	v_mul_f32_e32 v15, v15, v37
	v_fmac_f32_e32 v23, v15, v23
	v_mul_f32_e32 v15, 0x3f4c422a, v23
	v_add_f32_e32 v15, v15, v15
	v_mul_f32_e32 v15, 0x3fb8aa3b, v15
	v_exp_f32_e32 v15, v15
	s_nop 0
	v_add_f32_e32 v15, 1.0, v15
	v_rcp_f32_e32 v23, v15
	s_nop 0
	v_pk_fma_f32 v[38:39], v[22:23], 2.0, 1.0 op_sel_hi:[1,0,0] neg_lo:[1,0,0] neg_hi:[1,0,0]
	s_nop 1
	v_lshlrev_b32_e32 v40, 16, v226
	v_mul_f32_e32 v15, 0x3d372713, v40
	v_mul_f32_e32 v15, v15, v40
	v_lshlrev_b32_e32 v41, 16, v227
	v_mov_b32_e32 v22, v40
	v_fmac_f32_e32 v22, v15, v22
	v_mul_f32_e32 v15, 0x3f4c422a, v22
	v_add_f32_e32 v15, v15, v15
	v_mul_f32_e32 v15, 0x3fb8aa3b, v15
	v_exp_f32_e32 v15, v15
	v_mov_b32_e32 v23, v41
	v_add_f32_e32 v15, 1.0, v15
	v_rcp_f32_e32 v22, v15
	v_mul_f32_e32 v15, 0x3d372713, v41
	v_mul_f32_e32 v15, v15, v41
	v_fmac_f32_e32 v23, v15, v23
	v_mul_f32_e32 v15, 0x3f4c422a, v23
	v_add_f32_e32 v15, v15, v15
	v_mul_f32_e32 v15, 0x3fb8aa3b, v15
	v_exp_f32_e32 v15, v15
	s_nop 0
	v_add_f32_e32 v15, 1.0, v15
	v_rcp_f32_e32 v23, v15
	s_nop 0
	v_pk_fma_f32 v[42:43], v[22:23], 2.0, 1.0 op_sel_hi:[1,0,0] neg_lo:[1,0,0] neg_hi:[1,0,0]
	s_nop 1
	v_lshlrev_b32_e32 v44, 16, v228
	v_mul_f32_e32 v15, 0x3d372713, v44
	v_mul_f32_e32 v15, v15, v44
	v_lshlrev_b32_e32 v45, 16, v229
	v_mov_b32_e32 v22, v44
	v_fmac_f32_e32 v22, v15, v22
	v_mul_f32_e32 v15, 0x3f4c422a, v22
	v_add_f32_e32 v15, v15, v15
	v_mul_f32_e32 v15, 0x3fb8aa3b, v15
	v_exp_f32_e32 v15, v15
	v_mov_b32_e32 v23, v45
	v_add_f32_e32 v15, 1.0, v15
	v_rcp_f32_e32 v22, v15
	v_mul_f32_e32 v15, 0x3d372713, v45
	v_mul_f32_e32 v15, v15, v45
	v_fmac_f32_e32 v23, v15, v23
	v_mul_f32_e32 v15, 0x3f4c422a, v23
	v_add_f32_e32 v15, v15, v15
	v_mul_f32_e32 v15, 0x3fb8aa3b, v15
	v_exp_f32_e32 v15, v15
	s_nop 0
	v_add_f32_e32 v15, 1.0, v15
	v_rcp_f32_e32 v23, v15
	s_nop 0
	v_pk_fma_f32 v[46:47], v[22:23], 2.0, 1.0 op_sel_hi:[1,0,0] neg_lo:[1,0,0] neg_hi:[1,0,0]
	s_nop 1
	s_nop 1
	v_lshlrev_b32_e32 v48, 16, v230
	v_mul_f32_e32 v15, 0x3d372713, v48
	v_mul_f32_e32 v15, v15, v48
	v_lshlrev_b32_e32 v49, 16, v231
	v_mov_b32_e32 v16, v48
	v_fmac_f32_e32 v16, v15, v16
	v_mul_f32_e32 v15, 0x3f4c422a, v16
	v_add_f32_e32 v15, v15, v15
	v_mul_f32_e32 v15, 0x3fb8aa3b, v15
	v_exp_f32_e32 v15, v15
	v_mov_b32_e32 v17, v49
	v_add_f32_e32 v15, 1.0, v15
	v_rcp_f32_e32 v16, v15
	v_mul_f32_e32 v15, 0x3d372713, v49
	v_mul_f32_e32 v15, v15, v49
	v_fmac_f32_e32 v17, v15, v17
	v_mul_f32_e32 v15, 0x3f4c422a, v17
	v_add_f32_e32 v15, v15, v15
	v_mul_f32_e32 v15, 0x3fb8aa3b, v15
	v_exp_f32_e32 v15, v15
	s_nop 0
	v_add_f32_e32 v15, 1.0, v15
	v_rcp_f32_e32 v17, v15
	s_nop 0
	v_pk_fma_f32 v[50:51], v[16:17], 2.0, 1.0 op_sel_hi:[1,0,0] neg_lo:[1,0,0] neg_hi:[1,0,0]
	ds_read_b128 v[16:19], v11
	ds_read_b128 v[20:23], v11 offset:16
	s_waitcnt lgkmcnt(1)
	v_mov_b32_e32 v56, v16
	s_waitcnt lgkmcnt(0)
	v_mov_b32_e32 v57, v20
	v_pk_fma_f32 v[52:53], v[52:53], v[54:55], v[56:57] neg_lo:[0,0,1] neg_hi:[0,0,1]
	v_mov_b32_e32 v20, v17
	v_pk_mul_f32 v[16:17], v[20:21], v[52:53]
	v_pk_add_f32 v[20:21], v[26:27], 1.0 op_sel_hi:[1,0]
	v_pk_fma_f32 v[52:53], v[8:9], v[16:17], v[10:11] op_sel_hi:[0,1,0]
	v_pk_mul_f32 v[16:17], v[24:25], 0.5 op_sel_hi:[1,0]
	v_mov_b32_e32 v24, v18
	v_mov_b32_e32 v25, v22
	v_pk_fma_f32 v[16:17], v[16:17], v[20:21], v[24:25] neg_lo:[0,0,1] neg_hi:[0,0,1]
	v_mov_b32_e32 v22, v19
	v_pk_mul_f32 v[16:17], v[22:23], v[16:17]
	v_pk_mul_f32 v[26:27], v[28:29], 0.5 op_sel_hi:[1,0]
	v_pk_fma_f32 v[24:25], v[8:9], v[16:17], v[10:11] op_sel_hi:[0,1,0]
	ds_read_b128 v[16:19], v12
	ds_read_b128 v[20:23], v12 offset:16
	v_pk_add_f32 v[28:29], v[30:31], 1.0 op_sel_hi:[1,0]
	v_bfe_u32 v15, v25, 16, 1
	v_add3_u32 v15, v25, v15, s45
	s_waitcnt lgkmcnt(1)
	v_mov_b32_e32 v30, v16
	s_waitcnt lgkmcnt(0)
	v_mov_b32_e32 v31, v20
	v_pk_fma_f32 v[26:27], v[26:27], v[28:29], v[30:31] neg_lo:[0,0,1] neg_hi:[0,0,1]
	v_mov_b32_e32 v20, v17
	v_pk_mul_f32 v[16:17], v[20:21], v[26:27]
	v_pk_mul_f32 v[20:21], v[32:33], 0.5 op_sel_hi:[1,0]
	v_pk_add_f32 v[26:27], v[34:35], 1.0 op_sel_hi:[1,0]
	v_mov_b32_e32 v28, v18
	v_mov_b32_e32 v29, v22
	v_pk_fma_f32 v[20:21], v[20:21], v[26:27], v[28:29] neg_lo:[0,0,1] neg_hi:[0,0,1]
	v_mov_b32_e32 v22, v19
	v_pk_mul_f32 v[18:19], v[22:23], v[20:21]
	v_pk_fma_f32 v[16:17], v[8:9], v[16:17], v[10:11] op_sel_hi:[0,1,0]
	v_pk_fma_f32 v[18:19], v[8:9], v[18:19], v[10:11] op_sel_hi:[0,1,0]
	s_nop 0
	v_bfe_u32 v11, v19, 16, 1
	v_bfe_u32 v12, v18, 16, 1
	v_add3_u32 v12, v18, v12, s45
	v_add3_u32 v11, v19, v11, s45
	v_bfe_u32 v18, v52, 16, 1
	v_bfe_u32 v19, v53, 16, 1
	v_bfe_u32 v21, v16, 16, 1
	v_bfe_u32 v22, v17, 16, 1
	v_bfe_u32 v20, v24, 16, 1
	v_add3_u32 v17, v17, v22, s45
	v_add3_u32 v16, v16, v21, s45
	v_add3_u32 v19, v53, v19, s45
	v_add3_u32 v18, v52, v18, s45
	v_add3_u32 v20, v24, v20, s45
	v_lshrrev_b32_e32 v21, 16, v18
	v_lshrrev_b32_e32 v22, 16, v19
	v_lshrrev_b32_e32 v16, 16, v16
	v_lshrrev_b32_e32 v17, 16, v17
	v_and_or_b32 v19, v11, s43, v17
	v_and_or_b32 v18, v12, s43, v16
	v_and_or_b32 v17, v15, s43, v22
	v_and_or_b32 v16, v20, s43, v21
	ds_read_b128 v[20:23], v13
	ds_read_b128 v[24:27], v13 offset:16
	v_pk_mul_f32 v[28:29], v[36:37], 0.5 op_sel_hi:[1,0]
	v_pk_add_f32 v[30:31], v[38:39], 1.0 op_sel_hi:[1,0]
	s_waitcnt lgkmcnt(1)
; #define LAS __attribute__((address_space(3)))
; __device__ __forceinline__ unsigned pk2(float lo, float hi) { return f2bf(lo) | (f2bf(hi) << 16); }
; __device__ __forceinline__ void gmlp_fast(KArgs ap, int l, LAS unsigned char* lds, const Ctx cx) {
;     ...
;             for (int e = 0; e < 4; ++e) { const int chl = lane + 64 * e, ch = 256 * k + chl;
;                 const float gg = lng[ch], bb = lnb[ch];
;                 float vv[16];
; #pragma unroll
;                 for (int i = 0; i < 16; ++i) { const int s = wave * 16 + i; const float x = gelu_tanh(bf2f(z[(t0 + s) * DIN + ZGV + ch])); vv[i] = (x - ST[2 * s]) * ST[2 * s + 1] * gg + bb; }
;                 u32x4 w0, w1;
;                 w0.x = pk2(vv[0], vv[1]); w0.y = pk2(vv[2], vv[3]); w0.z = pk2(vv[4], vv[5]); w0.w = pk2(vv[6], vv[7]);
;                 w1.x = pk2(vv[8], vv[9]); w1.y = pk2(vv[10], vv[11]); w1.z = pk2(vv[12], vv[13]); w1.w = pk2(vv[14], vv[15]);
;                 *(LAS u32x4*)(VT + chl * 272 + wave * 32) = w0; *(LAS u32x4*)(VT + chl * 272 + wave * 32 + 16) = w1; }
;             __syncthreads();
;             const int gl = wave >> 2, tb = wave & 3, g = 2 * k + gl;
;             f32x16 acc[4];
; #pragma unroll
;             for (int ht = 0; ht < 4; ++ht)
; #pragma unroll
;                 for (int i = 0; i < 16; ++i) acc[ht][i] = 0.f;
;             const int tl = 32 * tb + r;
;             const float* wrow = wsp + ((size_t)g * 128 + tl) * 128 + 8 * hh;
;             f32x4 wn0 = *(const f32x4*)wrow, wn1 = *(const f32x4*)(wrow + 4);
	v_mov_b32_e32 v12, v20
	s_waitcnt lgkmcnt(0)
	v_mov_b32_e32 v13, v24
	v_pk_fma_f32 v[12:13], v[28:29], v[30:31], v[12:13] neg_lo:[0,0,1] neg_hi:[0,0,1]
	v_mov_b32_e32 v24, v21
	v_pk_mul_f32 v[12:13], v[24:25], v[12:13]
	v_pk_add_f32 v[20:21], v[42:43], 1.0 op_sel_hi:[1,0]
	v_pk_fma_f32 v[24:25], v[8:9], v[12:13], v[10:11] op_sel_hi:[0,1,0]
	v_pk_mul_f32 v[12:13], v[40:41], 0.5 op_sel_hi:[1,0]
	v_mov_b32_e32 v28, v22
	v_mov_b32_e32 v29, v26
	v_pk_fma_f32 v[12:13], v[12:13], v[20:21], v[28:29] neg_lo:[0,0,1] neg_hi:[0,0,1]
	v_mov_b32_e32 v26, v23
	v_pk_mul_f32 v[12:13], v[26:27], v[12:13]
	v_pk_mul_f32 v[28:29], v[44:45], 0.5 op_sel_hi:[1,0]
	v_pk_fma_f32 v[26:27], v[8:9], v[12:13], v[10:11] op_sel_hi:[0,1,0]
	ds_read_b128 v[20:23], v14
	ds_read_b128 v[12:15], v14 offset:16
	v_pk_add_f32 v[30:31], v[46:47], 1.0 op_sel_hi:[1,0]
	s_waitcnt lgkmcnt(1)
	v_mov_b32_e32 v32, v20
	s_waitcnt lgkmcnt(0)
	v_mov_b32_e32 v33, v12
	v_pk_fma_f32 v[28:29], v[28:29], v[30:31], v[32:33] neg_lo:[0,0,1] neg_hi:[0,0,1]
	v_mov_b32_e32 v12, v21
	v_pk_mul_f32 v[12:13], v[12:13], v[28:29]
	v_pk_mul_f32 v[20:21], v[48:49], 0.5 op_sel_hi:[1,0]
	v_pk_add_f32 v[28:29], v[50:51], 1.0 op_sel_hi:[1,0]
	v_mov_b32_e32 v30, v22
	v_mov_b32_e32 v31, v14
	v_pk_fma_f32 v[20:21], v[20:21], v[28:29], v[30:31] neg_lo:[0,0,1] neg_hi:[0,0,1]
	v_mov_b32_e32 v14, v23
	v_pk_mul_f32 v[14:15], v[14:15], v[20:21]
	v_pk_fma_f32 v[12:13], v[8:9], v[12:13], v[10:11] op_sel_hi:[0,1,0]
	v_pk_fma_f32 v[10:11], v[8:9], v[14:15], v[10:11] op_sel_hi:[0,1,0]
	s_nop 0
	v_bfe_u32 v8, v11, 16, 1
	v_bfe_u32 v14, v10, 16, 1
	v_add3_u32 v10, v10, v14, s45
	v_add3_u32 v8, v11, v8, s45
	v_bfe_u32 v11, v24, 16, 1
	v_bfe_u32 v14, v25, 16, 1
	v_bfe_u32 v21, v12, 16, 1
	v_bfe_u32 v22, v13, 16, 1
	v_bfe_u32 v15, v27, 16, 1
	v_bfe_u32 v20, v26, 16, 1
	v_add3_u32 v13, v13, v22, s45
	v_add3_u32 v12, v12, v21, s45
	v_add3_u32 v14, v25, v14, s45
	v_add3_u32 v11, v24, v11, s45
	v_add3_u32 v20, v26, v20, s45
	v_add3_u32 v15, v27, v15, s45
	v_lshrrev_b32_e32 v21, 16, v11
	v_lshrrev_b32_e32 v11, 16, v14
	v_lshrrev_b32_e32 v12, 16, v12
	v_lshrrev_b32_e32 v13, 16, v13
	v_and_or_b32 v13, v8, s43, v13
	v_and_or_b32 v12, v10, s43, v12
	v_and_or_b32 v11, v15, s43, v11
	v_and_or_b32 v10, v20, s43, v21
	ds_write_b128 v9, v[16:19] offset:17408
	ds_write_b128 v9, v[10:13] offset:17424
	v_add_u32_e32 v9, 0x8800, v9
	s_cbranch_scc0 .LBB0_162
	s_lshl_b32 s13, s13, 1
	s_add_i32 s20, s13, s28
	s_ashr_i32 s21, s20, 31
	s_lshl_b64 s[22:23], s[20:21], 16
	v_lshl_add_u64 v[0:1], v[82:83], 0, s[22:23]
	s_waitcnt lgkmcnt(0)
	s_barrier
	global_load_dwordx4 v[72:75], v[0:1], off offset:16
	global_load_dwordx4 v[76:79], v[0:1], off
	v_mov_b32_e32 v0, 0
	v_lshl_add_u64 v[98:99], v[90:91], 0, s[22:23]
	s_mov_b32 s13, 0
	v_mov_b32_e32 v93, v107
	s_mov_b32 s21, 0
	v_mov_b32_e32 v1, v0
	v_mov_b32_e32 v2, v0
	v_mov_b32_e32 v3, v0
	v_mov_b32_e32 v4, v0
	v_mov_b32_e32 v5, v0
	v_mov_b32_e32 v6, v0
	v_mov_b32_e32 v7, v0
	v_mov_b32_e32 v8, v0
	v_mov_b32_e32 v9, v0
	v_mov_b32_e32 v10, v0
	v_mov_b32_e32 v11, v0
	v_mov_b32_e32 v12, v0
	v_mov_b32_e32 v13, v0
	v_mov_b32_e32 v14, v0
	v_mov_b32_e32 v15, v0
	v_mov_b32_e32 v16, v0
	v_mov_b32_e32 v17, v0
	v_mov_b32_e32 v18, v0
	v_mov_b32_e32 v19, v0
	v_mov_b32_e32 v20, v0
	v_mov_b32_e32 v21, v0
	v_mov_b32_e32 v22, v0
	v_mov_b32_e32 v23, v0
	v_mov_b32_e32 v24, v0
	v_mov_b32_e32 v25, v0
	v_mov_b32_e32 v26, v0
	v_mov_b32_e32 v27, v0
	v_mov_b32_e32 v28, v0
	v_mov_b32_e32 v29, v0
	v_mov_b32_e32 v30, v0
	v_mov_b32_e32 v31, v0
	v_mov_b32_e32 v32, v0
	v_mov_b32_e32 v33, v0
	v_mov_b32_e32 v34, v0
	v_mov_b32_e32 v35, v0
	v_mov_b32_e32 v36, v0
	v_mov_b32_e32 v37, v0
	v_mov_b32_e32 v38, v0
	v_mov_b32_e32 v39, v0
	v_mov_b32_e32 v40, v0
	v_mov_b32_e32 v41, v0
	v_mov_b32_e32 v42, v0
	v_mov_b32_e32 v43, v0
	v_mov_b32_e32 v44, v0
	v_mov_b32_e32 v45, v0
	v_mov_b32_e32 v46, v0
	v_mov_b32_e32 v47, v0
	v_mov_b32_e32 v48, v0
	v_mov_b32_e32 v49, v0
	v_mov_b32_e32 v50, v0
	v_mov_b32_e32 v51, v0
	v_mov_b32_e32 v52, v0
	v_mov_b32_e32 v53, v0
	v_mov_b32_e32 v54, v0
	v_mov_b32_e32 v55, v0
	v_mov_b32_e32 v56, v0
	v_mov_b32_e32 v57, v0
	v_mov_b32_e32 v58, v0
	v_mov_b32_e32 v59, v0
	v_mov_b32_e32 v60, v0
	v_mov_b32_e32 v61, v0
	v_mov_b32_e32 v62, v0
	v_mov_b32_e32 v63, v0
	s_waitcnt vmcnt(1)
	v_mov_b64_e32 v[68:69], v[72:73]
	s_waitcnt vmcnt(0)
	v_mov_b64_e32 v[64:65], v[76:77]
	v_mov_b64_e32 v[66:67], v[78:79]
	v_mov_b64_e32 v[70:71], v[74:75]
	s_branch .LBB0_165
